# one static s_setprio 1 for waves 4-7 at kernel entry; per-segment s_setprio toggles removed from the GEMM k-loops
# speedup vs baseline: 1.0015x; 1.0015x over previous
_Z4mega4Args:
	s_mov_b32 s86, s2
	v_readfirstlane_b32 s8, v0
	s_bitcmp1_b32 s8, 8
	s_cbranch_scc0 .Lprio_skip
	s_setprio 1
.Lprio_skip:
	s_load_dwordx2 s[2:3], s[0:1], 0x118
	s_load_dwordx4 s[4:7], s[0:1], 0x100
	s_add_u32 s8, s0, 0x118
	v_and_b32_e32 v190, 0x3ff, v0
	s_addc_u32 s9, s1, 0
	s_waitcnt lgkmcnt(0)
	s_mov_b32 s21, s2
	v_writelane_b32 v252, s4, 0
	v_cmp_gt_u32_e32 vcc, 2, v190
	s_nop 0
	v_writelane_b32 v252, s5, 1
	v_writelane_b32 v252, s6, 2
	v_writelane_b32 v252, s7, 3
	s_and_saveexec_b64 s[2:3], vcc
	v_lshl_add_u32 v1, v190, 2, 0
	v_add_u32_e32 v1, 0x23fc0, v1
	v_mov_b32_e32 v2, 0
	ds_write_b32 v1, v2
	s_or_b64 exec, exec, s[2:3]
	s_load_dword s2, s[0:1], 0x114
	s_load_dwordx4 s[12:15], s[0:1], 0x100
	s_waitcnt lgkmcnt(0)
	s_barrier
	s_lshl_b32 s2, s2, 12
	s_ashr_i32 s3, s2, 31
	s_lshl_b64 s[2:3], s[2:3], 2
	s_add_u32 s2, s12, s2
	s_addc_u32 s3, s13, s3
	s_getreg_b32 s4, hwreg(HW_REG_XCC_ID, 0, 4)
	s_add_u32 s70, s2, 0x32f16d00
	s_addc_u32 s71, s3, 0
	s_and_b32 s20, s4, 15
	v_cmp_eq_u32_e64 s[4:5], 0, v190
	s_mov_b64 s[2:3], exec
	s_nop 0
	v_writelane_b32 v252, s4, 4
	s_nop 1
	v_writelane_b32 v252, s5, 5
	s_and_b64 s[4:5], s[2:3], s[4:5]
	s_mov_b64 exec, s[4:5]
	s_cbranch_execz .LBB0_5
	s_mov_b64 s[4:5], exec
	v_mbcnt_lo_u32_b32 v1, s4, 0
	v_mbcnt_hi_u32_b32 v1, s5, v1
	v_cmp_eq_u32_e32 vcc, 0, v1
	s_and_b64 s[6:7], exec, vcc
	s_mov_b64 exec, s[6:7]
	s_cbranch_execz .LBB0_5
	s_lshl_b32 s6, s20, 8
	s_bcnt1_i32_b64 s4, s[4:5]
	v_mov_b32_e32 v1, s6
	v_mov_b32_e32 v2, s4
	global_atomic_add v1, v2, s[70:71] offset:1024

.LBB0_240:
	s_add_u32 s40, s38, 0xfff80080
	s_addc_u32 s41, s39, -1
	s_add_i32 s54, 0, 0x10000
	s_cmp_eq_u32 s53, 28
	s_cselect_b32 s43, s5, s41
	s_cselect_b32 s42, s7, s40
	s_cselect_b32 s41, s29, s52
	s_cselect_b32 s40, s31, s51
	s_add_i32 s56, 0, 0x14000
	v_add_u32_e32 v84, s54, v176
	v_add_u32_e32 v158, s56, v176
	ds_read_b128 v[64:67], v84
	ds_read_b128 v[68:71], v84 offset:1024
	ds_read_b128 v[80:83], v84 offset:2048
	ds_read_b128 v[84:87], v84 offset:3072
	ds_read_b128 v[154:157], v158
	ds_read_b128 v[172:175], v158 offset:1024
	ds_read_b128 v[180:183], v158 offset:2048
	ds_read_b128 v[184:187], v158 offset:3072
	v_lshl_add_u64 v[158:159], s[38:39], 0, v[150:151]
	s_add_i32 m0, s44, 0xc000
	ds_read_b128 v[196:199], v178
	ds_read_b128 v[200:203], v178 offset:1024
	ds_read_b128 v[204:207], v178 offset:2048
	ds_read_b128 v[234:237], v178 offset:3072
	ds_read_b128 v[238:241], v178 offset:4096
	ds_read_b128 v[242:245], v178 offset:5120
	ds_read_b128 v[246:249], v178 offset:6144
	ds_read_b128 v[208:211], v178 offset:7168
	global_load_lds_dwordx4 v[158:159], off
	v_lshl_add_u64 v[158:159], s[38:39], 0, v[152:153]
	s_add_i32 m0, s44, 0xe000
	s_nop 0
	global_load_lds_dwordx4 v[158:159], off
	s_waitcnt vmcnt(8)
	s_waitcnt lgkmcnt(0)
	s_barrier
	s_waitcnt lgkmcnt(0)
	v_mfma_f32_16x16x32_bf16 v[140:143], v[64:67], v[196:199], v[140:143]
	v_mfma_f32_16x16x32_bf16 v[136:139], v[80:83], v[196:199], v[136:139]
	v_mfma_f32_16x16x32_bf16 v[124:127], v[64:67], v[204:207], v[124:127]
	v_mfma_f32_16x16x32_bf16 v[120:123], v[80:83], v[204:207], v[120:123]
	v_mfma_f32_16x16x32_bf16 v[108:111], v[64:67], v[238:241], v[108:111]
	v_mfma_f32_16x16x32_bf16 v[104:107], v[80:83], v[238:241], v[104:107]
	v_mfma_f32_16x16x32_bf16 v[92:95], v[64:67], v[246:249], v[92:95]
	v_mfma_f32_16x16x32_bf16 v[88:91], v[80:83], v[246:249], v[88:91]
	v_mfma_f32_16x16x32_bf16 v[140:143], v[68:71], v[200:203], v[140:143]
	v_mfma_f32_16x16x32_bf16 v[136:139], v[84:87], v[200:203], v[136:139]
	v_mfma_f32_16x16x32_bf16 v[124:127], v[68:71], v[234:237], v[124:127]
	v_mfma_f32_16x16x32_bf16 v[120:123], v[84:87], v[234:237], v[120:123]
	v_mfma_f32_16x16x32_bf16 v[108:111], v[68:71], v[242:245], v[108:111]
	v_mfma_f32_16x16x32_bf16 v[104:107], v[84:87], v[242:245], v[104:107]
	v_mfma_f32_16x16x32_bf16 v[92:95], v[68:71], v[208:211], v[92:95]
	v_mfma_f32_16x16x32_bf16 v[88:91], v[84:87], v[208:211], v[88:91]
	v_mfma_f32_16x16x32_bf16 v[132:135], v[154:157], v[196:199], v[132:135]
	v_mfma_f32_16x16x32_bf16 v[128:131], v[180:183], v[196:199], v[128:131]
	v_mfma_f32_16x16x32_bf16 v[116:119], v[154:157], v[204:207], v[116:119]
	v_mfma_f32_16x16x32_bf16 v[112:115], v[180:183], v[204:207], v[112:115]
	v_mfma_f32_16x16x32_bf16 v[100:103], v[154:157], v[238:241], v[100:103]
	v_mfma_f32_16x16x32_bf16 v[96:99], v[180:183], v[238:241], v[96:99]
	v_mfma_f32_16x16x32_bf16 v[76:79], v[154:157], v[246:249], v[76:79]
	v_mfma_f32_16x16x32_bf16 v[72:75], v[180:183], v[246:249], v[72:75]
	v_mfma_f32_16x16x32_bf16 v[132:135], v[172:175], v[200:203], v[132:135]
	v_mfma_f32_16x16x32_bf16 v[128:131], v[184:187], v[200:203], v[128:131]
	v_mfma_f32_16x16x32_bf16 v[116:119], v[172:175], v[234:237], v[116:119]
	v_mfma_f32_16x16x32_bf16 v[112:115], v[184:187], v[234:237], v[112:115]
	v_mfma_f32_16x16x32_bf16 v[100:103], v[172:175], v[242:245], v[100:103]
	v_mfma_f32_16x16x32_bf16 v[96:99], v[184:187], v[242:245], v[96:99]
	v_mfma_f32_16x16x32_bf16 v[76:79], v[172:175], v[208:211], v[76:79]
	v_mfma_f32_16x16x32_bf16 v[72:75], v[184:187], v[208:211], v[72:75]
	s_barrier
	s_add_i32 s54, s54, s24
	v_lshl_add_u64 v[158:159], s[40:41], 0, v[160:161]
	s_mov_b32 m0, s54
	ds_read_b128 v[196:199], v178 offset:16384
	ds_read_b128 v[200:203], v178 offset:17408
	ds_read_b128 v[204:207], v178 offset:18432
	ds_read_b128 v[208:211], v178 offset:19456
	ds_read_b128 v[234:237], v178 offset:20480
	ds_read_b128 v[238:241], v178 offset:21504
	ds_read_b128 v[242:245], v178 offset:22528
	ds_read_b128 v[246:249], v178 offset:23552
	global_load_lds_dwordx4 v[158:159], off
	s_add_i32 m0, s54, 0x2000
	s_add_u32 s54, s40, 0x80000
	v_lshl_add_u64 v[188:189], s[40:41], 0, v[148:149]
	s_addc_u32 s55, s41, 0
	s_add_i32 s56, s56, s24
	global_load_lds_dwordx4 v[188:189], off
	v_lshl_add_u64 v[212:213], s[54:55], 0, v[160:161]
	s_mov_b32 m0, s56
	v_lshl_add_u64 v[214:215], s[42:43], 0, v[146:147]
	global_load_lds_dwordx4 v[212:213], off
	v_lshl_add_u64 v[212:213], s[54:55], 0, v[148:149]
	s_add_i32 m0, s56, 0x2000
	s_nop 0
	global_load_lds_dwordx4 v[212:213], off
	v_lshl_add_u64 v[212:213], s[42:43], 0, v[144:145]
	s_mov_b32 m0, s44
	s_nop 0
	global_load_lds_dwordx4 v[212:213], off
	s_mov_b32 m0, s45
	s_nop 0
	global_load_lds_dwordx4 v[214:215], off
	s_waitcnt vmcnt(8)
	s_waitcnt lgkmcnt(0)
	s_barrier
	s_waitcnt lgkmcnt(0)
	v_mfma_f32_16x16x32_bf16 v[60:63], v[64:67], v[196:199], v[60:63]
	v_mfma_f32_16x16x32_bf16 v[56:59], v[80:83], v[196:199], v[56:59]
	v_mfma_f32_16x16x32_bf16 v[44:47], v[64:67], v[204:207], v[44:47]
	v_mfma_f32_16x16x32_bf16 v[40:43], v[80:83], v[204:207], v[40:43]
	v_mfma_f32_16x16x32_bf16 v[28:31], v[64:67], v[234:237], v[28:31]
	v_mfma_f32_16x16x32_bf16 v[24:27], v[80:83], v[234:237], v[24:27]
	v_mfma_f32_16x16x32_bf16 v[12:15], v[64:67], v[242:245], v[12:15]
	v_mfma_f32_16x16x32_bf16 v[8:11], v[80:83], v[242:245], v[8:11]
	v_mfma_f32_16x16x32_bf16 v[60:63], v[68:71], v[200:203], v[60:63]
	v_mfma_f32_16x16x32_bf16 v[56:59], v[84:87], v[200:203], v[56:59]
	v_mfma_f32_16x16x32_bf16 v[44:47], v[68:71], v[208:211], v[44:47]
	v_mfma_f32_16x16x32_bf16 v[40:43], v[84:87], v[208:211], v[40:43]
	v_mfma_f32_16x16x32_bf16 v[28:31], v[68:71], v[238:241], v[28:31]
	v_mfma_f32_16x16x32_bf16 v[24:27], v[84:87], v[238:241], v[24:27]
	v_mfma_f32_16x16x32_bf16 v[12:15], v[68:71], v[246:249], v[12:15]
	v_mfma_f32_16x16x32_bf16 v[8:11], v[84:87], v[246:249], v[8:11]
	v_mfma_f32_16x16x32_bf16 v[52:55], v[154:157], v[196:199], v[52:55]
	v_mfma_f32_16x16x32_bf16 v[48:51], v[180:183], v[196:199], v[48:51]
	v_mfma_f32_16x16x32_bf16 v[36:39], v[154:157], v[204:207], v[36:39]
	v_mfma_f32_16x16x32_bf16 v[32:35], v[180:183], v[204:207], v[32:35]
	v_mfma_f32_16x16x32_bf16 v[20:23], v[154:157], v[234:237], v[20:23]
	v_mfma_f32_16x16x32_bf16 v[16:19], v[180:183], v[234:237], v[16:19]
	v_mfma_f32_16x16x32_bf16 v[4:7], v[154:157], v[242:245], v[4:7]
	v_mfma_f32_16x16x32_bf16 v[0:3], v[180:183], v[242:245], v[0:3]
	v_mfma_f32_16x16x32_bf16 v[52:55], v[172:175], v[200:203], v[52:55]
	v_mfma_f32_16x16x32_bf16 v[48:51], v[184:187], v[200:203], v[48:51]
	v_mfma_f32_16x16x32_bf16 v[36:39], v[172:175], v[208:211], v[36:39]
	v_mfma_f32_16x16x32_bf16 v[32:35], v[184:187], v[208:211], v[32:35]
	v_mfma_f32_16x16x32_bf16 v[20:23], v[172:175], v[238:241], v[20:23]
	v_mfma_f32_16x16x32_bf16 v[16:19], v[184:187], v[238:241], v[16:19]
	v_mfma_f32_16x16x32_bf16 v[4:7], v[172:175], v[246:249], v[4:7]
	v_mfma_f32_16x16x32_bf16 v[0:3], v[184:187], v[246:249], v[0:3]
	s_barrier
	s_add_i32 s54, 0, 0x18000
	s_add_i32 s55, 0, 0x1c000
	v_add_u32_e32 v84, s54, v176
	v_add_u32_e32 v179, s55, v176
	ds_read_b128 v[64:67], v84
	ds_read_b128 v[68:71], v84 offset:1024
	ds_read_b128 v[80:83], v84 offset:2048
	ds_read_b128 v[84:87], v84 offset:3072
	ds_read_b128 v[154:157], v179
	ds_read_b128 v[172:175], v179 offset:1024
	ds_read_b128 v[180:183], v179 offset:2048
	ds_read_b128 v[184:187], v179 offset:3072
	s_add_u32 s42, s42, 0x80000
	s_addc_u32 s43, s43, 0
	s_mov_b32 m0, s46
	v_lshl_add_u64 v[250:251], s[42:43], 0, v[144:145]
	ds_read_b128 v[196:199], v178 offset:32768
	ds_read_b128 v[200:203], v178 offset:33792
	ds_read_b128 v[204:207], v178 offset:34816
	ds_read_b128 v[208:211], v178 offset:35840
	ds_read_b128 v[234:237], v178 offset:36864
	ds_read_b128 v[238:241], v178 offset:37888
	ds_read_b128 v[242:245], v178 offset:38912
	ds_read_b128 v[246:249], v178 offset:39936
	global_load_lds_dwordx4 v[250:251], off
	v_lshl_add_u64 v[250:251], s[42:43], 0, v[146:147]
	s_mov_b32 m0, s47
	s_nop 0
	global_load_lds_dwordx4 v[250:251], off
	s_waitcnt vmcnt(8)
	s_waitcnt lgkmcnt(0)
	s_barrier
	s_waitcnt lgkmcnt(0)
	v_mfma_f32_16x16x32_bf16 v[140:143], v[64:67], v[196:199], v[140:143]
	v_mfma_f32_16x16x32_bf16 v[136:139], v[80:83], v[196:199], v[136:139]
	v_mfma_f32_16x16x32_bf16 v[124:127], v[64:67], v[204:207], v[124:127]
	v_mfma_f32_16x16x32_bf16 v[120:123], v[80:83], v[204:207], v[120:123]
	v_mfma_f32_16x16x32_bf16 v[108:111], v[64:67], v[234:237], v[108:111]
	v_mfma_f32_16x16x32_bf16 v[104:107], v[80:83], v[234:237], v[104:107]
	v_mfma_f32_16x16x32_bf16 v[92:95], v[64:67], v[242:245], v[92:95]
	v_mfma_f32_16x16x32_bf16 v[88:91], v[80:83], v[242:245], v[88:91]
	v_mfma_f32_16x16x32_bf16 v[140:143], v[68:71], v[200:203], v[140:143]
	v_mfma_f32_16x16x32_bf16 v[136:139], v[84:87], v[200:203], v[136:139]
	v_mfma_f32_16x16x32_bf16 v[124:127], v[68:71], v[208:211], v[124:127]
	v_mfma_f32_16x16x32_bf16 v[120:123], v[84:87], v[208:211], v[120:123]
	v_mfma_f32_16x16x32_bf16 v[108:111], v[68:71], v[238:241], v[108:111]
	v_mfma_f32_16x16x32_bf16 v[104:107], v[84:87], v[238:241], v[104:107]
	v_mfma_f32_16x16x32_bf16 v[92:95], v[68:71], v[246:249], v[92:95]
	v_mfma_f32_16x16x32_bf16 v[88:91], v[84:87], v[246:249], v[88:91]
	v_mfma_f32_16x16x32_bf16 v[132:135], v[154:157], v[196:199], v[132:135]
	v_mfma_f32_16x16x32_bf16 v[128:131], v[180:183], v[196:199], v[128:131]
	v_mfma_f32_16x16x32_bf16 v[116:119], v[154:157], v[204:207], v[116:119]
	v_mfma_f32_16x16x32_bf16 v[112:115], v[180:183], v[204:207], v[112:115]
	v_mfma_f32_16x16x32_bf16 v[100:103], v[154:157], v[234:237], v[100:103]
	v_mfma_f32_16x16x32_bf16 v[96:99], v[180:183], v[234:237], v[96:99]
	v_mfma_f32_16x16x32_bf16 v[76:79], v[154:157], v[242:245], v[76:79]
	v_mfma_f32_16x16x32_bf16 v[72:75], v[180:183], v[242:245], v[72:75]
	v_mfma_f32_16x16x32_bf16 v[132:135], v[172:175], v[200:203], v[132:135]
	v_mfma_f32_16x16x32_bf16 v[128:131], v[184:187], v[200:203], v[128:131]
	v_mfma_f32_16x16x32_bf16 v[116:119], v[172:175], v[208:211], v[116:119]
	v_mfma_f32_16x16x32_bf16 v[112:115], v[184:187], v[208:211], v[112:115]
	v_mfma_f32_16x16x32_bf16 v[100:103], v[172:175], v[238:241], v[100:103]
	v_mfma_f32_16x16x32_bf16 v[96:99], v[184:187], v[238:241], v[96:99]
	v_mfma_f32_16x16x32_bf16 v[76:79], v[172:175], v[246:249], v[76:79]
	v_mfma_f32_16x16x32_bf16 v[72:75], v[184:187], v[246:249], v[72:75]
	s_barrier
	s_add_i32 s42, s54, s24
	v_lshl_add_u64 v[158:159], v[158:159], 0, s[20:21]
	s_mov_b32 m0, s42
	ds_read_b128 v[196:199], v178 offset:49152
	ds_read_b128 v[200:203], v178 offset:50176
	ds_read_b128 v[204:207], v178 offset:51200
	ds_read_b128 v[208:211], v178 offset:52224
	ds_read_b128 v[234:237], v178 offset:53248
	ds_read_b128 v[238:241], v178 offset:54272
	ds_read_b128 v[242:245], v178 offset:55296
	ds_read_b128 v[246:249], v178 offset:56320
	global_load_lds_dwordx4 v[158:159], off
	s_add_i32 m0, s42, 0x2000
	s_add_u32 s40, s40, 0x80080
	v_lshl_add_u64 v[158:159], v[188:189], 0, s[20:21]
	s_addc_u32 s41, s41, 0
	s_add_i32 s42, s55, s24
	global_load_lds_dwordx4 v[158:159], off
	v_lshl_add_u64 v[158:159], s[40:41], 0, v[160:161]
	s_mov_b32 m0, s42
	s_nop 0
	global_load_lds_dwordx4 v[158:159], off
	v_lshl_add_u64 v[158:159], s[40:41], 0, v[148:149]
	s_add_i32 m0, s42, 0x2000
	s_nop 0
	global_load_lds_dwordx4 v[158:159], off
	v_lshl_add_u64 v[158:159], v[212:213], 0, s[20:21]
	s_mov_b32 m0, s48
	s_nop 0
	global_load_lds_dwordx4 v[158:159], off
	v_lshl_add_u64 v[158:159], v[214:215], 0, s[20:21]
	s_mov_b32 m0, s49
	s_nop 0
	global_load_lds_dwordx4 v[158:159], off
	s_waitcnt vmcnt(8)
	s_waitcnt lgkmcnt(0)
	s_barrier
	s_waitcnt lgkmcnt(0)
	v_mfma_f32_16x16x32_bf16 v[60:63], v[64:67], v[196:199], v[60:63]
	v_mfma_f32_16x16x32_bf16 v[56:59], v[80:83], v[196:199], v[56:59]
	v_mfma_f32_16x16x32_bf16 v[44:47], v[64:67], v[204:207], v[44:47]
	v_mfma_f32_16x16x32_bf16 v[40:43], v[80:83], v[204:207], v[40:43]
	v_mfma_f32_16x16x32_bf16 v[28:31], v[64:67], v[234:237], v[28:31]
	v_mfma_f32_16x16x32_bf16 v[24:27], v[80:83], v[234:237], v[24:27]
	v_mfma_f32_16x16x32_bf16 v[12:15], v[64:67], v[242:245], v[12:15]
	v_mfma_f32_16x16x32_bf16 v[8:11], v[80:83], v[242:245], v[8:11]
	v_mfma_f32_16x16x32_bf16 v[60:63], v[68:71], v[200:203], v[60:63]
	v_mfma_f32_16x16x32_bf16 v[56:59], v[84:87], v[200:203], v[56:59]
	v_mfma_f32_16x16x32_bf16 v[44:47], v[68:71], v[208:211], v[44:47]
	v_mfma_f32_16x16x32_bf16 v[40:43], v[84:87], v[208:211], v[40:43]
	v_mfma_f32_16x16x32_bf16 v[28:31], v[68:71], v[238:241], v[28:31]
	v_mfma_f32_16x16x32_bf16 v[24:27], v[84:87], v[238:241], v[24:27]
	v_mfma_f32_16x16x32_bf16 v[12:15], v[68:71], v[246:249], v[12:15]
	v_mfma_f32_16x16x32_bf16 v[8:11], v[84:87], v[246:249], v[8:11]
	v_mfma_f32_16x16x32_bf16 v[52:55], v[154:157], v[196:199], v[52:55]
	v_mfma_f32_16x16x32_bf16 v[48:51], v[180:183], v[196:199], v[48:51]
	v_mfma_f32_16x16x32_bf16 v[36:39], v[154:157], v[204:207], v[36:39]
	v_mfma_f32_16x16x32_bf16 v[32:35], v[180:183], v[204:207], v[32:35]
	v_mfma_f32_16x16x32_bf16 v[20:23], v[154:157], v[234:237], v[20:23]
	v_mfma_f32_16x16x32_bf16 v[16:19], v[180:183], v[234:237], v[16:19]
	v_mfma_f32_16x16x32_bf16 v[4:7], v[154:157], v[242:245], v[4:7]
	v_mfma_f32_16x16x32_bf16 v[0:3], v[180:183], v[242:245], v[0:3]
	v_mfma_f32_16x16x32_bf16 v[52:55], v[172:175], v[200:203], v[52:55]
	v_mfma_f32_16x16x32_bf16 v[48:51], v[184:187], v[200:203], v[48:51]
	v_mfma_f32_16x16x32_bf16 v[36:39], v[172:175], v[208:211], v[36:39]
	v_mfma_f32_16x16x32_bf16 v[32:35], v[184:187], v[208:211], v[32:35]
	v_mfma_f32_16x16x32_bf16 v[20:23], v[172:175], v[238:241], v[20:23]
	v_mfma_f32_16x16x32_bf16 v[16:19], v[184:187], v[238:241], v[16:19]
	v_mfma_f32_16x16x32_bf16 v[4:7], v[172:175], v[246:249], v[4:7]
	v_mfma_f32_16x16x32_bf16 v[0:3], v[184:187], v[246:249], v[0:3]
	s_barrier
	s_add_i32 s53, s53, 2
	s_add_u32 s38, s38, 0x100
	s_addc_u32 s39, s39, 0
	s_add_u32 s51, s51, 0x100
	s_addc_u32 s52, s52, 0
	s_cmp_gt_u32 s53, 29
	s_cbranch_scc0 .LBB0_240
	s_and_b64 vcc, exec, s[18:19]
	s_cbranch_vccz .LBB0_243
	s_barrier

.LBB0_352:
	s_add_u32 s30, s28, 0xfff80080
	s_addc_u32 s31, s29, -1
	s_add_i32 s52, 0, 0x10000
	s_cmp_eq_u32 s51, 28
	s_cselect_b32 s35, s15, s31
	s_cselect_b32 s34, s47, s30
	s_cselect_b32 s31, s13, s50
	s_cselect_b32 s30, s48, s49
	s_add_i32 s54, 0, 0x14000
	v_add_u32_e32 v154, s52, v143
	v_add_u32_e32 v158, s54, v143
	ds_read_b128 v[138:141], v154
	ds_read_b128 v[146:149], v154 offset:1024
	ds_read_b128 v[150:153], v154 offset:2048
	ds_read_b128 v[154:157], v154 offset:3072
	ds_read_b128 v[172:175], v158
	ds_read_b128 v[176:179], v158 offset:1024
	ds_read_b128 v[180:183], v158 offset:2048
	ds_read_b128 v[184:187], v158 offset:3072
	v_lshl_add_u64 v[158:159], s[28:29], 0, v[134:135]
	s_add_i32 m0, s38, 0xc000
	ds_read_b128 v[196:199], v145
	ds_read_b128 v[200:203], v145 offset:1024
	ds_read_b128 v[204:207], v145 offset:2048
	ds_read_b128 v[208:211], v145 offset:3072
	ds_read_b128 v[234:237], v145 offset:4096
	ds_read_b128 v[238:241], v145 offset:5120
	ds_read_b128 v[242:245], v145 offset:6144
	ds_read_b128 v[246:249], v145 offset:7168
	global_load_lds_dwordx4 v[158:159], off
	v_lshl_add_u64 v[158:159], s[28:29], 0, v[136:137]
	s_add_i32 m0, s38, 0xe000
	s_nop 0
	global_load_lds_dwordx4 v[158:159], off
	s_waitcnt vmcnt(8)
	s_waitcnt lgkmcnt(0)
	s_barrier
	s_waitcnt lgkmcnt(0)
	v_mfma_f32_16x16x32_bf16 v[124:127], v[138:141], v[196:199], v[124:127]
	v_mfma_f32_16x16x32_bf16 v[120:123], v[150:153], v[196:199], v[120:123]
	v_mfma_f32_16x16x32_bf16 v[112:115], v[138:141], v[204:207], v[112:115]
	v_mfma_f32_16x16x32_bf16 v[104:107], v[150:153], v[204:207], v[104:107]
	v_mfma_f32_16x16x32_bf16 v[92:95], v[138:141], v[234:237], v[92:95]
	v_mfma_f32_16x16x32_bf16 v[88:91], v[150:153], v[234:237], v[88:91]
	v_mfma_f32_16x16x32_bf16 v[80:83], v[138:141], v[242:245], v[80:83]
	v_mfma_f32_16x16x32_bf16 v[72:75], v[150:153], v[242:245], v[72:75]
	v_mfma_f32_16x16x32_bf16 v[124:127], v[146:149], v[200:203], v[124:127]
	v_mfma_f32_16x16x32_bf16 v[120:123], v[154:157], v[200:203], v[120:123]
	v_mfma_f32_16x16x32_bf16 v[112:115], v[146:149], v[208:211], v[112:115]
	v_mfma_f32_16x16x32_bf16 v[104:107], v[154:157], v[208:211], v[104:107]
	v_mfma_f32_16x16x32_bf16 v[92:95], v[146:149], v[238:241], v[92:95]
	v_mfma_f32_16x16x32_bf16 v[88:91], v[154:157], v[238:241], v[88:91]
	v_mfma_f32_16x16x32_bf16 v[80:83], v[146:149], v[246:249], v[80:83]
	v_mfma_f32_16x16x32_bf16 v[72:75], v[154:157], v[246:249], v[72:75]
	v_mfma_f32_16x16x32_bf16 v[116:119], v[172:175], v[196:199], v[116:119]
	v_mfma_f32_16x16x32_bf16 v[108:111], v[180:183], v[196:199], v[108:111]
	v_mfma_f32_16x16x32_bf16 v[100:103], v[172:175], v[204:207], v[100:103]
	v_mfma_f32_16x16x32_bf16 v[96:99], v[180:183], v[204:207], v[96:99]
	v_mfma_f32_16x16x32_bf16 v[84:87], v[172:175], v[234:237], v[84:87]
	v_mfma_f32_16x16x32_bf16 v[76:79], v[180:183], v[234:237], v[76:79]
	v_mfma_f32_16x16x32_bf16 v[68:71], v[172:175], v[242:245], v[68:71]
	v_mfma_f32_16x16x32_bf16 v[64:67], v[180:183], v[242:245], v[64:67]
	v_mfma_f32_16x16x32_bf16 v[116:119], v[176:179], v[200:203], v[116:119]
	v_mfma_f32_16x16x32_bf16 v[108:111], v[184:187], v[200:203], v[108:111]
	v_mfma_f32_16x16x32_bf16 v[100:103], v[176:179], v[208:211], v[100:103]
	v_mfma_f32_16x16x32_bf16 v[96:99], v[184:187], v[208:211], v[96:99]
	v_mfma_f32_16x16x32_bf16 v[84:87], v[176:179], v[238:241], v[84:87]
	v_mfma_f32_16x16x32_bf16 v[76:79], v[184:187], v[238:241], v[76:79]
	v_mfma_f32_16x16x32_bf16 v[68:71], v[176:179], v[246:249], v[68:71]
	v_mfma_f32_16x16x32_bf16 v[64:67], v[184:187], v[246:249], v[64:67]
	s_barrier
	s_add_i32 s52, s52, s37
	v_lshl_add_u64 v[158:159], s[30:31], 0, v[160:161]
	s_mov_b32 m0, s52
	ds_read_b128 v[196:199], v145 offset:16384
	ds_read_b128 v[200:203], v145 offset:17408
	ds_read_b128 v[204:207], v145 offset:18432
	ds_read_b128 v[208:211], v145 offset:19456
	ds_read_b128 v[234:237], v145 offset:20480
	ds_read_b128 v[238:241], v145 offset:21504
	ds_read_b128 v[242:245], v145 offset:22528
	ds_read_b128 v[246:249], v145 offset:23552
	global_load_lds_dwordx4 v[158:159], off
	s_add_i32 m0, s52, 0x2000
	s_add_u32 s52, s30, 0x80000
	v_lshl_add_u64 v[188:189], s[30:31], 0, v[128:129]
	s_addc_u32 s53, s31, 0
	s_add_i32 s54, s54, s37
	global_load_lds_dwordx4 v[188:189], off
	v_lshl_add_u64 v[212:213], s[52:53], 0, v[160:161]
	s_mov_b32 m0, s54
	v_lshl_add_u64 v[214:215], s[34:35], 0, v[130:131]
	global_load_lds_dwordx4 v[212:213], off
	v_lshl_add_u64 v[212:213], s[52:53], 0, v[128:129]
	s_add_i32 m0, s54, 0x2000
	s_nop 0
	global_load_lds_dwordx4 v[212:213], off
	v_lshl_add_u64 v[212:213], s[34:35], 0, v[132:133]
	s_mov_b32 m0, s38
	s_nop 0
	global_load_lds_dwordx4 v[212:213], off
	s_mov_b32 m0, s39
	s_nop 0
	global_load_lds_dwordx4 v[214:215], off
	s_waitcnt vmcnt(8)
	s_waitcnt lgkmcnt(0)
	s_barrier
	s_waitcnt lgkmcnt(0)
	v_mfma_f32_16x16x32_bf16 v[60:63], v[138:141], v[196:199], v[60:63]
	v_mfma_f32_16x16x32_bf16 v[56:59], v[150:153], v[196:199], v[56:59]
	v_mfma_f32_16x16x32_bf16 v[48:51], v[138:141], v[204:207], v[48:51]
	v_mfma_f32_16x16x32_bf16 v[40:43], v[150:153], v[204:207], v[40:43]
	v_mfma_f32_16x16x32_bf16 v[28:31], v[138:141], v[234:237], v[28:31]
	v_mfma_f32_16x16x32_bf16 v[24:27], v[150:153], v[234:237], v[24:27]
	v_mfma_f32_16x16x32_bf16 v[16:19], v[138:141], v[242:245], v[16:19]
	v_mfma_f32_16x16x32_bf16 v[8:11], v[150:153], v[242:245], v[8:11]
	v_mfma_f32_16x16x32_bf16 v[60:63], v[146:149], v[200:203], v[60:63]
	v_mfma_f32_16x16x32_bf16 v[56:59], v[154:157], v[200:203], v[56:59]
	v_mfma_f32_16x16x32_bf16 v[48:51], v[146:149], v[208:211], v[48:51]
	v_mfma_f32_16x16x32_bf16 v[40:43], v[154:157], v[208:211], v[40:43]
	v_mfma_f32_16x16x32_bf16 v[28:31], v[146:149], v[238:241], v[28:31]
	v_mfma_f32_16x16x32_bf16 v[24:27], v[154:157], v[238:241], v[24:27]
	v_mfma_f32_16x16x32_bf16 v[16:19], v[146:149], v[246:249], v[16:19]
	v_mfma_f32_16x16x32_bf16 v[8:11], v[154:157], v[246:249], v[8:11]
	v_mfma_f32_16x16x32_bf16 v[52:55], v[172:175], v[196:199], v[52:55]
	v_mfma_f32_16x16x32_bf16 v[44:47], v[180:183], v[196:199], v[44:47]
	v_mfma_f32_16x16x32_bf16 v[36:39], v[172:175], v[204:207], v[36:39]
	v_mfma_f32_16x16x32_bf16 v[32:35], v[180:183], v[204:207], v[32:35]
	v_mfma_f32_16x16x32_bf16 v[20:23], v[172:175], v[234:237], v[20:23]
	v_mfma_f32_16x16x32_bf16 v[12:15], v[180:183], v[234:237], v[12:15]
	v_mfma_f32_16x16x32_bf16 v[4:7], v[172:175], v[242:245], v[4:7]
	v_mfma_f32_16x16x32_bf16 v[0:3], v[180:183], v[242:245], v[0:3]
	v_mfma_f32_16x16x32_bf16 v[52:55], v[176:179], v[200:203], v[52:55]
	v_mfma_f32_16x16x32_bf16 v[44:47], v[184:187], v[200:203], v[44:47]
	v_mfma_f32_16x16x32_bf16 v[36:39], v[176:179], v[208:211], v[36:39]
	v_mfma_f32_16x16x32_bf16 v[32:35], v[184:187], v[208:211], v[32:35]
	v_mfma_f32_16x16x32_bf16 v[20:23], v[176:179], v[238:241], v[20:23]
	v_mfma_f32_16x16x32_bf16 v[12:15], v[184:187], v[238:241], v[12:15]
	v_mfma_f32_16x16x32_bf16 v[4:7], v[176:179], v[246:249], v[4:7]
	v_mfma_f32_16x16x32_bf16 v[0:3], v[184:187], v[246:249], v[0:3]
	s_barrier
	s_add_i32 s52, 0, 0x18000
	s_add_i32 s53, 0, 0x1c000
	v_add_u32_e32 v154, s52, v143
	v_add_u32_e32 v162, s53, v143
	ds_read_b128 v[138:141], v154
	ds_read_b128 v[146:149], v154 offset:1024
	ds_read_b128 v[150:153], v154 offset:2048
	ds_read_b128 v[154:157], v154 offset:3072
	ds_read_b128 v[172:175], v162
	ds_read_b128 v[176:179], v162 offset:1024
	ds_read_b128 v[180:183], v162 offset:2048
	ds_read_b128 v[184:187], v162 offset:3072
	s_add_u32 s34, s34, 0x80000
	s_addc_u32 s35, s35, 0
	s_mov_b32 m0, s40
	v_lshl_add_u64 v[250:251], s[34:35], 0, v[132:133]
	ds_read_b128 v[196:199], v145 offset:32768
	ds_read_b128 v[200:203], v145 offset:33792
	ds_read_b128 v[204:207], v145 offset:34816
	ds_read_b128 v[208:211], v145 offset:35840
	ds_read_b128 v[234:237], v145 offset:36864
	ds_read_b128 v[238:241], v145 offset:37888
	ds_read_b128 v[242:245], v145 offset:38912
	ds_read_b128 v[246:249], v145 offset:39936
	global_load_lds_dwordx4 v[250:251], off
	v_lshl_add_u64 v[250:251], s[34:35], 0, v[130:131]
	s_mov_b32 m0, s41
	s_nop 0
	global_load_lds_dwordx4 v[250:251], off
	s_waitcnt vmcnt(8)
	s_waitcnt lgkmcnt(0)
	s_barrier
	s_waitcnt lgkmcnt(0)
	v_mfma_f32_16x16x32_bf16 v[124:127], v[138:141], v[196:199], v[124:127]
	v_mfma_f32_16x16x32_bf16 v[120:123], v[150:153], v[196:199], v[120:123]
	v_mfma_f32_16x16x32_bf16 v[112:115], v[138:141], v[204:207], v[112:115]
	v_mfma_f32_16x16x32_bf16 v[104:107], v[150:153], v[204:207], v[104:107]
	v_mfma_f32_16x16x32_bf16 v[92:95], v[138:141], v[234:237], v[92:95]
	v_mfma_f32_16x16x32_bf16 v[88:91], v[150:153], v[234:237], v[88:91]
	v_mfma_f32_16x16x32_bf16 v[80:83], v[138:141], v[242:245], v[80:83]
	v_mfma_f32_16x16x32_bf16 v[72:75], v[150:153], v[242:245], v[72:75]
	v_mfma_f32_16x16x32_bf16 v[124:127], v[146:149], v[200:203], v[124:127]
	v_mfma_f32_16x16x32_bf16 v[120:123], v[154:157], v[200:203], v[120:123]
	v_mfma_f32_16x16x32_bf16 v[112:115], v[146:149], v[208:211], v[112:115]
	v_mfma_f32_16x16x32_bf16 v[104:107], v[154:157], v[208:211], v[104:107]
	v_mfma_f32_16x16x32_bf16 v[92:95], v[146:149], v[238:241], v[92:95]
	v_mfma_f32_16x16x32_bf16 v[88:91], v[154:157], v[238:241], v[88:91]
	v_mfma_f32_16x16x32_bf16 v[80:83], v[146:149], v[246:249], v[80:83]
	v_mfma_f32_16x16x32_bf16 v[72:75], v[154:157], v[246:249], v[72:75]
	v_mfma_f32_16x16x32_bf16 v[116:119], v[172:175], v[196:199], v[116:119]
	v_mfma_f32_16x16x32_bf16 v[108:111], v[180:183], v[196:199], v[108:111]
	v_mfma_f32_16x16x32_bf16 v[100:103], v[172:175], v[204:207], v[100:103]
	v_mfma_f32_16x16x32_bf16 v[96:99], v[180:183], v[204:207], v[96:99]
	v_mfma_f32_16x16x32_bf16 v[84:87], v[172:175], v[234:237], v[84:87]
	v_mfma_f32_16x16x32_bf16 v[76:79], v[180:183], v[234:237], v[76:79]
	v_mfma_f32_16x16x32_bf16 v[68:71], v[172:175], v[242:245], v[68:71]
	v_mfma_f32_16x16x32_bf16 v[64:67], v[180:183], v[242:245], v[64:67]
	v_mfma_f32_16x16x32_bf16 v[116:119], v[176:179], v[200:203], v[116:119]
	v_mfma_f32_16x16x32_bf16 v[108:111], v[184:187], v[200:203], v[108:111]
	v_mfma_f32_16x16x32_bf16 v[100:103], v[176:179], v[208:211], v[100:103]
	v_mfma_f32_16x16x32_bf16 v[96:99], v[184:187], v[208:211], v[96:99]
	v_mfma_f32_16x16x32_bf16 v[84:87], v[176:179], v[238:241], v[84:87]
	v_mfma_f32_16x16x32_bf16 v[76:79], v[184:187], v[238:241], v[76:79]
	v_mfma_f32_16x16x32_bf16 v[68:71], v[176:179], v[246:249], v[68:71]
	v_mfma_f32_16x16x32_bf16 v[64:67], v[184:187], v[246:249], v[64:67]
	s_barrier
	s_add_i32 s34, s52, s37
	v_lshl_add_u64 v[158:159], v[158:159], 0, s[20:21]
	s_mov_b32 m0, s34
	ds_read_b128 v[196:199], v145 offset:49152
	ds_read_b128 v[200:203], v145 offset:50176
	ds_read_b128 v[204:207], v145 offset:51200
	ds_read_b128 v[208:211], v145 offset:52224
	ds_read_b128 v[234:237], v145 offset:53248
	ds_read_b128 v[238:241], v145 offset:54272
	ds_read_b128 v[242:245], v145 offset:55296
	ds_read_b128 v[246:249], v145 offset:56320
	global_load_lds_dwordx4 v[158:159], off
	s_add_i32 m0, s34, 0x2000
	s_add_u32 s30, s30, 0x80080
	v_lshl_add_u64 v[158:159], v[188:189], 0, s[20:21]
	s_addc_u32 s31, s31, 0
	s_add_i32 s34, s53, s37
	global_load_lds_dwordx4 v[158:159], off
	v_lshl_add_u64 v[158:159], s[30:31], 0, v[160:161]
	s_mov_b32 m0, s34
	s_nop 0
	global_load_lds_dwordx4 v[158:159], off
	v_lshl_add_u64 v[158:159], s[30:31], 0, v[128:129]
	s_add_i32 m0, s34, 0x2000
	s_nop 0
	global_load_lds_dwordx4 v[158:159], off
	v_lshl_add_u64 v[158:159], v[212:213], 0, s[20:21]
	s_mov_b32 m0, s42
	s_nop 0
	global_load_lds_dwordx4 v[158:159], off
	v_lshl_add_u64 v[158:159], v[214:215], 0, s[20:21]
	s_mov_b32 m0, s43
	s_nop 0
	global_load_lds_dwordx4 v[158:159], off
	s_waitcnt vmcnt(8)
	s_waitcnt lgkmcnt(0)
	s_barrier
	s_waitcnt lgkmcnt(0)
	v_mfma_f32_16x16x32_bf16 v[60:63], v[138:141], v[196:199], v[60:63]
	v_mfma_f32_16x16x32_bf16 v[56:59], v[150:153], v[196:199], v[56:59]
	v_mfma_f32_16x16x32_bf16 v[48:51], v[138:141], v[204:207], v[48:51]
	v_mfma_f32_16x16x32_bf16 v[40:43], v[150:153], v[204:207], v[40:43]
	v_mfma_f32_16x16x32_bf16 v[28:31], v[138:141], v[234:237], v[28:31]
	v_mfma_f32_16x16x32_bf16 v[24:27], v[150:153], v[234:237], v[24:27]
	v_mfma_f32_16x16x32_bf16 v[16:19], v[138:141], v[242:245], v[16:19]
	v_mfma_f32_16x16x32_bf16 v[8:11], v[150:153], v[242:245], v[8:11]
	v_mfma_f32_16x16x32_bf16 v[60:63], v[146:149], v[200:203], v[60:63]
	v_mfma_f32_16x16x32_bf16 v[56:59], v[154:157], v[200:203], v[56:59]
	v_mfma_f32_16x16x32_bf16 v[48:51], v[146:149], v[208:211], v[48:51]
	v_mfma_f32_16x16x32_bf16 v[40:43], v[154:157], v[208:211], v[40:43]
	v_mfma_f32_16x16x32_bf16 v[28:31], v[146:149], v[238:241], v[28:31]
	v_mfma_f32_16x16x32_bf16 v[24:27], v[154:157], v[238:241], v[24:27]
	v_mfma_f32_16x16x32_bf16 v[16:19], v[146:149], v[246:249], v[16:19]
	v_mfma_f32_16x16x32_bf16 v[8:11], v[154:157], v[246:249], v[8:11]
	v_mfma_f32_16x16x32_bf16 v[52:55], v[172:175], v[196:199], v[52:55]
	v_mfma_f32_16x16x32_bf16 v[44:47], v[180:183], v[196:199], v[44:47]
	v_mfma_f32_16x16x32_bf16 v[36:39], v[172:175], v[204:207], v[36:39]
	v_mfma_f32_16x16x32_bf16 v[32:35], v[180:183], v[204:207], v[32:35]
	v_mfma_f32_16x16x32_bf16 v[20:23], v[172:175], v[234:237], v[20:23]
	v_mfma_f32_16x16x32_bf16 v[12:15], v[180:183], v[234:237], v[12:15]
	v_mfma_f32_16x16x32_bf16 v[4:7], v[172:175], v[242:245], v[4:7]
	v_mfma_f32_16x16x32_bf16 v[0:3], v[180:183], v[242:245], v[0:3]
	v_mfma_f32_16x16x32_bf16 v[52:55], v[176:179], v[200:203], v[52:55]
	v_mfma_f32_16x16x32_bf16 v[44:47], v[184:187], v[200:203], v[44:47]
	v_mfma_f32_16x16x32_bf16 v[36:39], v[176:179], v[208:211], v[36:39]
	v_mfma_f32_16x16x32_bf16 v[32:35], v[184:187], v[208:211], v[32:35]
	v_mfma_f32_16x16x32_bf16 v[20:23], v[176:179], v[238:241], v[20:23]
	v_mfma_f32_16x16x32_bf16 v[12:15], v[184:187], v[238:241], v[12:15]
	v_mfma_f32_16x16x32_bf16 v[4:7], v[176:179], v[246:249], v[4:7]
	v_mfma_f32_16x16x32_bf16 v[0:3], v[184:187], v[246:249], v[0:3]
	s_barrier
	s_add_i32 s51, s51, 2
	s_add_u32 s28, s28, 0x100
	s_addc_u32 s29, s29, 0
	s_add_u32 s49, s49, 0x100
	s_addc_u32 s50, s50, 0
	s_cmp_gt_u32 s51, 29
	s_cbranch_scc0 .LBB0_352
	s_and_b64 vcc, exec, s[10:11]
	s_cbranch_vccz .LBB0_355
	s_barrier

.LBB0_526:
	s_add_u32 s28, s18, 0xfff00080
	s_addc_u32 s29, s19, -1
	s_add_i32 s54, 0, 0x10000
	s_cmp_eq_u32 s53, 4
	s_cselect_b32 s31, s13, s29
	s_cselect_b32 s30, s49, s28
	s_cselect_b32 s29, s11, s52
	s_cselect_b32 s28, s50, s51
	s_add_i32 s56, 0, 0x14000
	v_add_u32_e32 v154, s54, v143
	v_add_u32_e32 v158, s56, v143
	ds_read_b128 v[138:141], v154
	ds_read_b128 v[146:149], v154 offset:1024
	ds_read_b128 v[150:153], v154 offset:2048
	ds_read_b128 v[154:157], v154 offset:3072
	ds_read_b128 v[172:175], v158
	ds_read_b128 v[176:179], v158 offset:1024
	ds_read_b128 v[180:183], v158 offset:2048
	ds_read_b128 v[184:187], v158 offset:3072
	v_lshl_add_u64 v[158:159], s[18:19], 0, v[134:135]
	s_add_i32 m0, s40, 0xc000
	ds_read_b128 v[196:199], v145
	ds_read_b128 v[200:203], v145 offset:1024
	ds_read_b128 v[204:207], v145 offset:2048
	ds_read_b128 v[208:211], v145 offset:3072
	ds_read_b128 v[234:237], v145 offset:4096
	ds_read_b128 v[238:241], v145 offset:5120
	ds_read_b128 v[242:245], v145 offset:6144
	ds_read_b128 v[246:249], v145 offset:7168
	global_load_lds_dwordx4 v[158:159], off
	v_lshl_add_u64 v[158:159], s[18:19], 0, v[136:137]
	s_add_i32 m0, s40, 0xe000
	s_nop 0
	global_load_lds_dwordx4 v[158:159], off
	s_waitcnt vmcnt(8)
	s_waitcnt lgkmcnt(0)
	s_barrier
	s_waitcnt lgkmcnt(0)
	v_mfma_f32_16x16x32_bf16 v[124:127], v[138:141], v[196:199], v[124:127]
	v_mfma_f32_16x16x32_bf16 v[120:123], v[150:153], v[196:199], v[120:123]
	v_mfma_f32_16x16x32_bf16 v[116:119], v[138:141], v[204:207], v[116:119]
	v_mfma_f32_16x16x32_bf16 v[108:111], v[150:153], v[204:207], v[108:111]
	v_mfma_f32_16x16x32_bf16 v[100:103], v[138:141], v[234:237], v[100:103]
	v_mfma_f32_16x16x32_bf16 v[92:95], v[150:153], v[234:237], v[92:95]
	v_mfma_f32_16x16x32_bf16 v[84:87], v[138:141], v[242:245], v[84:87]
	v_mfma_f32_16x16x32_bf16 v[76:79], v[150:153], v[242:245], v[76:79]
	v_mfma_f32_16x16x32_bf16 v[124:127], v[146:149], v[200:203], v[124:127]
	v_mfma_f32_16x16x32_bf16 v[120:123], v[154:157], v[200:203], v[120:123]
	v_mfma_f32_16x16x32_bf16 v[116:119], v[146:149], v[208:211], v[116:119]
	v_mfma_f32_16x16x32_bf16 v[108:111], v[154:157], v[208:211], v[108:111]
	v_mfma_f32_16x16x32_bf16 v[100:103], v[146:149], v[238:241], v[100:103]
	v_mfma_f32_16x16x32_bf16 v[92:95], v[154:157], v[238:241], v[92:95]
	v_mfma_f32_16x16x32_bf16 v[84:87], v[146:149], v[246:249], v[84:87]
	v_mfma_f32_16x16x32_bf16 v[76:79], v[154:157], v[246:249], v[76:79]
	v_mfma_f32_16x16x32_bf16 v[112:115], v[172:175], v[196:199], v[112:115]
	v_mfma_f32_16x16x32_bf16 v[104:107], v[180:183], v[196:199], v[104:107]
	v_mfma_f32_16x16x32_bf16 v[96:99], v[172:175], v[204:207], v[96:99]
	v_mfma_f32_16x16x32_bf16 v[88:91], v[180:183], v[204:207], v[88:91]
	v_mfma_f32_16x16x32_bf16 v[80:83], v[172:175], v[234:237], v[80:83]
	v_mfma_f32_16x16x32_bf16 v[72:75], v[180:183], v[234:237], v[72:75]
	v_mfma_f32_16x16x32_bf16 v[68:71], v[172:175], v[242:245], v[68:71]
	v_mfma_f32_16x16x32_bf16 v[64:67], v[180:183], v[242:245], v[64:67]
	v_mfma_f32_16x16x32_bf16 v[112:115], v[176:179], v[200:203], v[112:115]
	v_mfma_f32_16x16x32_bf16 v[104:107], v[184:187], v[200:203], v[104:107]
	v_mfma_f32_16x16x32_bf16 v[96:99], v[176:179], v[208:211], v[96:99]
	v_mfma_f32_16x16x32_bf16 v[88:91], v[184:187], v[208:211], v[88:91]
	v_mfma_f32_16x16x32_bf16 v[80:83], v[176:179], v[238:241], v[80:83]
	v_mfma_f32_16x16x32_bf16 v[72:75], v[184:187], v[238:241], v[72:75]
	v_mfma_f32_16x16x32_bf16 v[68:71], v[176:179], v[246:249], v[68:71]
	v_mfma_f32_16x16x32_bf16 v[64:67], v[184:187], v[246:249], v[64:67]
	s_barrier
	s_add_i32 s54, s54, s37
	v_lshl_add_u64 v[158:159], s[28:29], 0, v[160:161]
	s_mov_b32 m0, s54
	ds_read_b128 v[196:199], v145 offset:16384
	ds_read_b128 v[200:203], v145 offset:17408
	ds_read_b128 v[204:207], v145 offset:18432
	ds_read_b128 v[208:211], v145 offset:19456
	ds_read_b128 v[234:237], v145 offset:20480
	ds_read_b128 v[238:241], v145 offset:21504
	ds_read_b128 v[242:245], v145 offset:22528
	ds_read_b128 v[246:249], v145 offset:23552
	global_load_lds_dwordx4 v[158:159], off
	s_add_i32 m0, s54, 0x2000
	s_add_u32 s54, s28, 0x20000
	v_lshl_add_u64 v[188:189], s[28:29], 0, v[128:129]
	s_addc_u32 s55, s29, 0
	s_add_i32 s56, s56, s37
	global_load_lds_dwordx4 v[188:189], off
	v_lshl_add_u64 v[212:213], s[54:55], 0, v[160:161]
	s_mov_b32 m0, s56
	v_lshl_add_u64 v[214:215], s[30:31], 0, v[130:131]
	global_load_lds_dwordx4 v[212:213], off
	v_lshl_add_u64 v[212:213], s[54:55], 0, v[128:129]
	s_add_i32 m0, s56, 0x2000
	s_nop 0
	global_load_lds_dwordx4 v[212:213], off
	v_lshl_add_u64 v[212:213], s[30:31], 0, v[132:133]
	s_mov_b32 m0, s40
	s_nop 0
	global_load_lds_dwordx4 v[212:213], off
	s_mov_b32 m0, s41
	s_nop 0
	global_load_lds_dwordx4 v[214:215], off
	s_waitcnt vmcnt(8)
	s_waitcnt lgkmcnt(0)
	s_barrier
	s_waitcnt lgkmcnt(0)
	v_mfma_f32_16x16x32_bf16 v[60:63], v[138:141], v[196:199], v[60:63]
	v_mfma_f32_16x16x32_bf16 v[56:59], v[150:153], v[196:199], v[56:59]
	v_mfma_f32_16x16x32_bf16 v[52:55], v[138:141], v[204:207], v[52:55]
	v_mfma_f32_16x16x32_bf16 v[44:47], v[150:153], v[204:207], v[44:47]
	v_mfma_f32_16x16x32_bf16 v[36:39], v[138:141], v[234:237], v[36:39]
	v_mfma_f32_16x16x32_bf16 v[28:31], v[150:153], v[234:237], v[28:31]
	v_mfma_f32_16x16x32_bf16 v[20:23], v[138:141], v[242:245], v[20:23]
	v_mfma_f32_16x16x32_bf16 v[12:15], v[150:153], v[242:245], v[12:15]
	v_mfma_f32_16x16x32_bf16 v[60:63], v[146:149], v[200:203], v[60:63]
	v_mfma_f32_16x16x32_bf16 v[56:59], v[154:157], v[200:203], v[56:59]
	v_mfma_f32_16x16x32_bf16 v[52:55], v[146:149], v[208:211], v[52:55]
	v_mfma_f32_16x16x32_bf16 v[44:47], v[154:157], v[208:211], v[44:47]
	v_mfma_f32_16x16x32_bf16 v[36:39], v[146:149], v[238:241], v[36:39]
	v_mfma_f32_16x16x32_bf16 v[28:31], v[154:157], v[238:241], v[28:31]
	v_mfma_f32_16x16x32_bf16 v[20:23], v[146:149], v[246:249], v[20:23]
	v_mfma_f32_16x16x32_bf16 v[12:15], v[154:157], v[246:249], v[12:15]
	v_mfma_f32_16x16x32_bf16 v[48:51], v[172:175], v[196:199], v[48:51]
	v_mfma_f32_16x16x32_bf16 v[40:43], v[180:183], v[196:199], v[40:43]
	v_mfma_f32_16x16x32_bf16 v[32:35], v[172:175], v[204:207], v[32:35]
	v_mfma_f32_16x16x32_bf16 v[24:27], v[180:183], v[204:207], v[24:27]
	v_mfma_f32_16x16x32_bf16 v[16:19], v[172:175], v[234:237], v[16:19]
	v_mfma_f32_16x16x32_bf16 v[8:11], v[180:183], v[234:237], v[8:11]
	v_mfma_f32_16x16x32_bf16 v[4:7], v[172:175], v[242:245], v[4:7]
	v_mfma_f32_16x16x32_bf16 v[0:3], v[180:183], v[242:245], v[0:3]
	v_mfma_f32_16x16x32_bf16 v[48:51], v[176:179], v[200:203], v[48:51]
	v_mfma_f32_16x16x32_bf16 v[40:43], v[184:187], v[200:203], v[40:43]
	v_mfma_f32_16x16x32_bf16 v[32:35], v[176:179], v[208:211], v[32:35]
	v_mfma_f32_16x16x32_bf16 v[24:27], v[184:187], v[208:211], v[24:27]
	v_mfma_f32_16x16x32_bf16 v[16:19], v[176:179], v[238:241], v[16:19]
	v_mfma_f32_16x16x32_bf16 v[8:11], v[184:187], v[238:241], v[8:11]
	v_mfma_f32_16x16x32_bf16 v[4:7], v[176:179], v[246:249], v[4:7]
	v_mfma_f32_16x16x32_bf16 v[0:3], v[184:187], v[246:249], v[0:3]
	s_barrier
	s_add_i32 s54, 0, 0x18000
	s_add_i32 s55, 0, 0x1c000
	v_add_u32_e32 v154, s54, v143
	v_add_u32_e32 v162, s55, v143
	ds_read_b128 v[138:141], v154
	ds_read_b128 v[146:149], v154 offset:1024
	ds_read_b128 v[150:153], v154 offset:2048
	ds_read_b128 v[154:157], v154 offset:3072
	ds_read_b128 v[172:175], v162
	ds_read_b128 v[176:179], v162 offset:1024
	ds_read_b128 v[180:183], v162 offset:2048
	ds_read_b128 v[184:187], v162 offset:3072
	s_add_u32 s30, s30, 0x100000
	s_addc_u32 s31, s31, 0
	s_mov_b32 m0, s42
	v_lshl_add_u64 v[250:251], s[30:31], 0, v[132:133]
	ds_read_b128 v[196:199], v145 offset:32768
	ds_read_b128 v[200:203], v145 offset:33792
	ds_read_b128 v[204:207], v145 offset:34816
	ds_read_b128 v[208:211], v145 offset:35840
	ds_read_b128 v[234:237], v145 offset:36864
	ds_read_b128 v[238:241], v145 offset:37888
	ds_read_b128 v[242:245], v145 offset:38912
	ds_read_b128 v[246:249], v145 offset:39936
	global_load_lds_dwordx4 v[250:251], off
	v_lshl_add_u64 v[250:251], s[30:31], 0, v[130:131]
	s_mov_b32 m0, s43
	s_nop 0
	global_load_lds_dwordx4 v[250:251], off
	s_waitcnt vmcnt(8)
	s_waitcnt lgkmcnt(0)
	s_barrier
	s_waitcnt lgkmcnt(0)
	v_mfma_f32_16x16x32_bf16 v[124:127], v[138:141], v[196:199], v[124:127]
	v_mfma_f32_16x16x32_bf16 v[120:123], v[150:153], v[196:199], v[120:123]
	v_mfma_f32_16x16x32_bf16 v[116:119], v[138:141], v[204:207], v[116:119]
	v_mfma_f32_16x16x32_bf16 v[108:111], v[150:153], v[204:207], v[108:111]
	v_mfma_f32_16x16x32_bf16 v[100:103], v[138:141], v[234:237], v[100:103]
	v_mfma_f32_16x16x32_bf16 v[92:95], v[150:153], v[234:237], v[92:95]
	v_mfma_f32_16x16x32_bf16 v[84:87], v[138:141], v[242:245], v[84:87]
	v_mfma_f32_16x16x32_bf16 v[76:79], v[150:153], v[242:245], v[76:79]
	v_mfma_f32_16x16x32_bf16 v[124:127], v[146:149], v[200:203], v[124:127]
	v_mfma_f32_16x16x32_bf16 v[120:123], v[154:157], v[200:203], v[120:123]
	v_mfma_f32_16x16x32_bf16 v[116:119], v[146:149], v[208:211], v[116:119]
	v_mfma_f32_16x16x32_bf16 v[108:111], v[154:157], v[208:211], v[108:111]
	v_mfma_f32_16x16x32_bf16 v[100:103], v[146:149], v[238:241], v[100:103]
	v_mfma_f32_16x16x32_bf16 v[92:95], v[154:157], v[238:241], v[92:95]
	v_mfma_f32_16x16x32_bf16 v[84:87], v[146:149], v[246:249], v[84:87]
	v_mfma_f32_16x16x32_bf16 v[76:79], v[154:157], v[246:249], v[76:79]
	v_mfma_f32_16x16x32_bf16 v[112:115], v[172:175], v[196:199], v[112:115]
	v_mfma_f32_16x16x32_bf16 v[104:107], v[180:183], v[196:199], v[104:107]
	v_mfma_f32_16x16x32_bf16 v[96:99], v[172:175], v[204:207], v[96:99]
	v_mfma_f32_16x16x32_bf16 v[88:91], v[180:183], v[204:207], v[88:91]
	v_mfma_f32_16x16x32_bf16 v[80:83], v[172:175], v[234:237], v[80:83]
	v_mfma_f32_16x16x32_bf16 v[72:75], v[180:183], v[234:237], v[72:75]
	v_mfma_f32_16x16x32_bf16 v[68:71], v[172:175], v[242:245], v[68:71]
	v_mfma_f32_16x16x32_bf16 v[64:67], v[180:183], v[242:245], v[64:67]
	v_mfma_f32_16x16x32_bf16 v[112:115], v[176:179], v[200:203], v[112:115]
	v_mfma_f32_16x16x32_bf16 v[104:107], v[184:187], v[200:203], v[104:107]
	v_mfma_f32_16x16x32_bf16 v[96:99], v[176:179], v[208:211], v[96:99]
	v_mfma_f32_16x16x32_bf16 v[88:91], v[184:187], v[208:211], v[88:91]
	v_mfma_f32_16x16x32_bf16 v[80:83], v[176:179], v[238:241], v[80:83]
	v_mfma_f32_16x16x32_bf16 v[72:75], v[184:187], v[238:241], v[72:75]
	v_mfma_f32_16x16x32_bf16 v[68:71], v[176:179], v[246:249], v[68:71]
	v_mfma_f32_16x16x32_bf16 v[64:67], v[184:187], v[246:249], v[64:67]
	s_barrier
	s_add_i32 s30, s54, s37
	v_lshl_add_u64 v[158:159], v[158:159], 0, s[20:21]
	s_mov_b32 m0, s30
	ds_read_b128 v[196:199], v145 offset:49152
	ds_read_b128 v[200:203], v145 offset:50176
	ds_read_b128 v[204:207], v145 offset:51200
	ds_read_b128 v[208:211], v145 offset:52224
	ds_read_b128 v[234:237], v145 offset:53248
	ds_read_b128 v[238:241], v145 offset:54272
	ds_read_b128 v[242:245], v145 offset:55296
	ds_read_b128 v[246:249], v145 offset:56320
	global_load_lds_dwordx4 v[158:159], off
	s_add_i32 m0, s30, 0x2000
	s_add_u32 s28, s28, 0x20080
	v_lshl_add_u64 v[158:159], v[188:189], 0, s[20:21]
	s_addc_u32 s29, s29, 0
	s_add_i32 s30, s55, s37
	global_load_lds_dwordx4 v[158:159], off
	v_lshl_add_u64 v[158:159], s[28:29], 0, v[160:161]
	s_mov_b32 m0, s30
	s_nop 0
	global_load_lds_dwordx4 v[158:159], off
	v_lshl_add_u64 v[158:159], s[28:29], 0, v[128:129]
	s_add_i32 m0, s30, 0x2000
	s_nop 0
	global_load_lds_dwordx4 v[158:159], off
	v_lshl_add_u64 v[158:159], v[212:213], 0, s[20:21]
	s_mov_b32 m0, s44
	s_nop 0
	global_load_lds_dwordx4 v[158:159], off
	v_lshl_add_u64 v[158:159], v[214:215], 0, s[20:21]
	s_mov_b32 m0, s45
	s_nop 0
	global_load_lds_dwordx4 v[158:159], off
	s_waitcnt vmcnt(8)
	s_waitcnt lgkmcnt(0)
	s_barrier
	s_waitcnt lgkmcnt(0)
	v_mfma_f32_16x16x32_bf16 v[60:63], v[138:141], v[196:199], v[60:63]
	v_mfma_f32_16x16x32_bf16 v[56:59], v[150:153], v[196:199], v[56:59]
	v_mfma_f32_16x16x32_bf16 v[52:55], v[138:141], v[204:207], v[52:55]
	v_mfma_f32_16x16x32_bf16 v[44:47], v[150:153], v[204:207], v[44:47]
	v_mfma_f32_16x16x32_bf16 v[36:39], v[138:141], v[234:237], v[36:39]
	v_mfma_f32_16x16x32_bf16 v[28:31], v[150:153], v[234:237], v[28:31]
	v_mfma_f32_16x16x32_bf16 v[20:23], v[138:141], v[242:245], v[20:23]
	v_mfma_f32_16x16x32_bf16 v[12:15], v[150:153], v[242:245], v[12:15]
	v_mfma_f32_16x16x32_bf16 v[60:63], v[146:149], v[200:203], v[60:63]
	v_mfma_f32_16x16x32_bf16 v[56:59], v[154:157], v[200:203], v[56:59]
	v_mfma_f32_16x16x32_bf16 v[52:55], v[146:149], v[208:211], v[52:55]
	v_mfma_f32_16x16x32_bf16 v[44:47], v[154:157], v[208:211], v[44:47]
	v_mfma_f32_16x16x32_bf16 v[36:39], v[146:149], v[238:241], v[36:39]
	v_mfma_f32_16x16x32_bf16 v[28:31], v[154:157], v[238:241], v[28:31]
	v_mfma_f32_16x16x32_bf16 v[20:23], v[146:149], v[246:249], v[20:23]
	v_mfma_f32_16x16x32_bf16 v[12:15], v[154:157], v[246:249], v[12:15]
	v_mfma_f32_16x16x32_bf16 v[48:51], v[172:175], v[196:199], v[48:51]
	v_mfma_f32_16x16x32_bf16 v[40:43], v[180:183], v[196:199], v[40:43]
	v_mfma_f32_16x16x32_bf16 v[32:35], v[172:175], v[204:207], v[32:35]
	v_mfma_f32_16x16x32_bf16 v[24:27], v[180:183], v[204:207], v[24:27]
	v_mfma_f32_16x16x32_bf16 v[16:19], v[172:175], v[234:237], v[16:19]
	v_mfma_f32_16x16x32_bf16 v[8:11], v[180:183], v[234:237], v[8:11]
	v_mfma_f32_16x16x32_bf16 v[4:7], v[172:175], v[242:245], v[4:7]
	v_mfma_f32_16x16x32_bf16 v[0:3], v[180:183], v[242:245], v[0:3]
	v_mfma_f32_16x16x32_bf16 v[48:51], v[176:179], v[200:203], v[48:51]
	v_mfma_f32_16x16x32_bf16 v[40:43], v[184:187], v[200:203], v[40:43]
	v_mfma_f32_16x16x32_bf16 v[32:35], v[176:179], v[208:211], v[32:35]
	v_mfma_f32_16x16x32_bf16 v[24:27], v[184:187], v[208:211], v[24:27]
	v_mfma_f32_16x16x32_bf16 v[16:19], v[176:179], v[238:241], v[16:19]
	v_mfma_f32_16x16x32_bf16 v[8:11], v[184:187], v[238:241], v[8:11]
	v_mfma_f32_16x16x32_bf16 v[4:7], v[176:179], v[246:249], v[4:7]
	v_mfma_f32_16x16x32_bf16 v[0:3], v[184:187], v[246:249], v[0:3]
	s_barrier
	s_add_i32 s53, s53, 2
	s_add_u32 s18, s18, 0x100
	s_addc_u32 s19, s19, 0
	s_add_u32 s51, s51, 0x100
	s_addc_u32 s52, s52, 0
	s_cmp_gt_u32 s53, 5
	s_cbranch_scc0 .LBB0_526
	s_and_b64 vcc, exec, s[8:9]
	s_cbranch_vccz .LBB0_529
	s_barrier

.LBB0_542:
	s_add_u32 s28, s26, 0xfff00080
	s_addc_u32 s29, s27, -1
	s_add_i32 s54, 0, 0x10000
	s_cmp_eq_u32 s53, 4
	s_cselect_b32 s31, s15, s29
	s_cselect_b32 s30, s49, s28
	v_add_u32_e32 v140, s54, v143
	s_cselect_b32 s29, s13, s52
	s_cselect_b32 s28, s50, s51
	s_add_i32 s56, 0, 0x14000
	ds_read_b128 v[146:149], v140
	ds_read_b128 v[150:153], v140 offset:1024
	ds_read_b128 v[154:157], v140 offset:2048
	ds_read_b128 v[172:175], v140 offset:3072
	v_add_u32_e32 v140, s56, v143
	ds_read_b128 v[176:179], v140
	ds_read_b128 v[180:183], v140 offset:1024
	ds_read_b128 v[184:187], v140 offset:2048
	ds_read_b128 v[196:199], v140 offset:3072
	v_lshl_add_u64 v[140:141], s[26:27], 0, v[136:137]
	s_add_i32 m0, s40, 0xc000
	ds_read_b128 v[200:203], v144
	ds_read_b128 v[204:207], v144 offset:1024
	ds_read_b128 v[208:211], v144 offset:2048
	ds_read_b128 v[234:237], v144 offset:3072
	ds_read_b128 v[238:241], v144 offset:4096
	ds_read_b128 v[242:245], v144 offset:5120
	ds_read_b128 v[246:249], v144 offset:6144
	ds_read_b128 v[212:215], v144 offset:7168
	global_load_lds_dwordx4 v[140:141], off
	v_lshl_add_u64 v[140:141], s[26:27], 0, v[138:139]
	s_add_i32 m0, s40, 0xe000
	s_nop 0
	global_load_lds_dwordx4 v[140:141], off
	s_waitcnt vmcnt(8)
	s_waitcnt lgkmcnt(0)
	s_barrier
	s_waitcnt lgkmcnt(0)
	v_mfma_f32_16x16x32_bf16 v[124:127], v[146:149], v[200:203], v[124:127]
	v_mfma_f32_16x16x32_bf16 v[120:123], v[154:157], v[200:203], v[120:123]
	v_mfma_f32_16x16x32_bf16 v[116:119], v[146:149], v[208:211], v[116:119]
	v_mfma_f32_16x16x32_bf16 v[108:111], v[154:157], v[208:211], v[108:111]
	v_mfma_f32_16x16x32_bf16 v[100:103], v[146:149], v[238:241], v[100:103]
	v_mfma_f32_16x16x32_bf16 v[92:95], v[154:157], v[238:241], v[92:95]
	v_mfma_f32_16x16x32_bf16 v[84:87], v[146:149], v[246:249], v[84:87]
	v_mfma_f32_16x16x32_bf16 v[76:79], v[154:157], v[246:249], v[76:79]
	v_mfma_f32_16x16x32_bf16 v[124:127], v[150:153], v[204:207], v[124:127]
	v_mfma_f32_16x16x32_bf16 v[120:123], v[172:175], v[204:207], v[120:123]
	v_mfma_f32_16x16x32_bf16 v[116:119], v[150:153], v[234:237], v[116:119]
	v_mfma_f32_16x16x32_bf16 v[108:111], v[172:175], v[234:237], v[108:111]
	v_mfma_f32_16x16x32_bf16 v[100:103], v[150:153], v[242:245], v[100:103]
	v_mfma_f32_16x16x32_bf16 v[92:95], v[172:175], v[242:245], v[92:95]
	v_mfma_f32_16x16x32_bf16 v[84:87], v[150:153], v[212:215], v[84:87]
	v_mfma_f32_16x16x32_bf16 v[76:79], v[172:175], v[212:215], v[76:79]
	v_mfma_f32_16x16x32_bf16 v[112:115], v[176:179], v[200:203], v[112:115]
	v_mfma_f32_16x16x32_bf16 v[104:107], v[184:187], v[200:203], v[104:107]
	v_mfma_f32_16x16x32_bf16 v[96:99], v[176:179], v[208:211], v[96:99]
	v_mfma_f32_16x16x32_bf16 v[88:91], v[184:187], v[208:211], v[88:91]
	v_mfma_f32_16x16x32_bf16 v[80:83], v[176:179], v[238:241], v[80:83]
	v_mfma_f32_16x16x32_bf16 v[72:75], v[184:187], v[238:241], v[72:75]
	v_mfma_f32_16x16x32_bf16 v[68:71], v[176:179], v[246:249], v[68:71]
	v_mfma_f32_16x16x32_bf16 v[64:67], v[184:187], v[246:249], v[64:67]
	v_mfma_f32_16x16x32_bf16 v[112:115], v[180:183], v[204:207], v[112:115]
	v_mfma_f32_16x16x32_bf16 v[104:107], v[196:199], v[204:207], v[104:107]
	v_mfma_f32_16x16x32_bf16 v[96:99], v[180:183], v[234:237], v[96:99]
	v_mfma_f32_16x16x32_bf16 v[88:91], v[196:199], v[234:237], v[88:91]
	v_mfma_f32_16x16x32_bf16 v[80:83], v[180:183], v[242:245], v[80:83]
	v_mfma_f32_16x16x32_bf16 v[72:75], v[196:199], v[242:245], v[72:75]
	v_mfma_f32_16x16x32_bf16 v[68:71], v[180:183], v[212:215], v[68:71]
	v_mfma_f32_16x16x32_bf16 v[64:67], v[196:199], v[212:215], v[64:67]
	s_barrier
	s_add_i32 s54, s54, s37
	v_lshl_add_u64 v[140:141], s[28:29], 0, v[132:133]
	s_mov_b32 m0, s54
	ds_read_b128 v[200:203], v144 offset:16384
	ds_read_b128 v[204:207], v144 offset:17408
	ds_read_b128 v[208:211], v144 offset:18432
	ds_read_b128 v[212:215], v144 offset:19456
	ds_read_b128 v[234:237], v144 offset:20480
	ds_read_b128 v[238:241], v144 offset:21504
	ds_read_b128 v[242:245], v144 offset:22528
	ds_read_b128 v[246:249], v144 offset:23552
	global_load_lds_dwordx4 v[140:141], off
	s_add_i32 m0, s54, 0x2000
	s_add_u32 s54, s28, 0x20000
	v_lshl_add_u64 v[158:159], s[28:29], 0, v[128:129]
	s_addc_u32 s55, s29, 0
	s_add_i32 s56, s56, s37
	global_load_lds_dwordx4 v[158:159], off
	v_lshl_add_u64 v[188:189], s[54:55], 0, v[132:133]
	s_mov_b32 m0, s56
	v_lshl_add_u64 v[250:251], s[30:31], 0, v[130:131]
	global_load_lds_dwordx4 v[188:189], off
	v_lshl_add_u64 v[188:189], s[54:55], 0, v[128:129]
	s_add_i32 m0, s56, 0x2000
	s_nop 0
	global_load_lds_dwordx4 v[188:189], off
	v_lshl_add_u64 v[188:189], s[30:31], 0, v[134:135]
	s_mov_b32 m0, s40
	s_nop 0
	global_load_lds_dwordx4 v[188:189], off
	s_mov_b32 m0, s41
	s_nop 0
	global_load_lds_dwordx4 v[250:251], off
	s_waitcnt vmcnt(8)
	s_waitcnt lgkmcnt(0)
	s_barrier
	s_waitcnt lgkmcnt(0)
	v_mfma_f32_16x16x32_bf16 v[60:63], v[146:149], v[200:203], v[60:63]
	v_mfma_f32_16x16x32_bf16 v[56:59], v[154:157], v[200:203], v[56:59]
	v_mfma_f32_16x16x32_bf16 v[52:55], v[146:149], v[208:211], v[52:55]
	v_mfma_f32_16x16x32_bf16 v[44:47], v[154:157], v[208:211], v[44:47]
	v_mfma_f32_16x16x32_bf16 v[36:39], v[146:149], v[234:237], v[36:39]
	v_mfma_f32_16x16x32_bf16 v[28:31], v[154:157], v[234:237], v[28:31]
	v_mfma_f32_16x16x32_bf16 v[20:23], v[146:149], v[242:245], v[20:23]
	v_mfma_f32_16x16x32_bf16 v[12:15], v[154:157], v[242:245], v[12:15]
	v_mfma_f32_16x16x32_bf16 v[60:63], v[150:153], v[204:207], v[60:63]
	v_mfma_f32_16x16x32_bf16 v[56:59], v[172:175], v[204:207], v[56:59]
	v_mfma_f32_16x16x32_bf16 v[52:55], v[150:153], v[212:215], v[52:55]
	v_mfma_f32_16x16x32_bf16 v[44:47], v[172:175], v[212:215], v[44:47]
	v_mfma_f32_16x16x32_bf16 v[36:39], v[150:153], v[238:241], v[36:39]
	v_mfma_f32_16x16x32_bf16 v[28:31], v[172:175], v[238:241], v[28:31]
	v_mfma_f32_16x16x32_bf16 v[20:23], v[150:153], v[246:249], v[20:23]
	v_mfma_f32_16x16x32_bf16 v[12:15], v[172:175], v[246:249], v[12:15]
	v_mfma_f32_16x16x32_bf16 v[48:51], v[176:179], v[200:203], v[48:51]
	v_mfma_f32_16x16x32_bf16 v[40:43], v[184:187], v[200:203], v[40:43]
	v_mfma_f32_16x16x32_bf16 v[32:35], v[176:179], v[208:211], v[32:35]
	v_mfma_f32_16x16x32_bf16 v[24:27], v[184:187], v[208:211], v[24:27]
	v_mfma_f32_16x16x32_bf16 v[16:19], v[176:179], v[234:237], v[16:19]
	v_mfma_f32_16x16x32_bf16 v[8:11], v[184:187], v[234:237], v[8:11]
	v_mfma_f32_16x16x32_bf16 v[4:7], v[176:179], v[242:245], v[4:7]
	v_mfma_f32_16x16x32_bf16 v[0:3], v[184:187], v[242:245], v[0:3]
	v_mfma_f32_16x16x32_bf16 v[48:51], v[180:183], v[204:207], v[48:51]
	v_mfma_f32_16x16x32_bf16 v[40:43], v[196:199], v[204:207], v[40:43]
	v_mfma_f32_16x16x32_bf16 v[32:35], v[180:183], v[212:215], v[32:35]
	v_mfma_f32_16x16x32_bf16 v[24:27], v[196:199], v[212:215], v[24:27]
	v_mfma_f32_16x16x32_bf16 v[16:19], v[180:183], v[238:241], v[16:19]
	v_mfma_f32_16x16x32_bf16 v[8:11], v[196:199], v[238:241], v[8:11]
	v_mfma_f32_16x16x32_bf16 v[4:7], v[180:183], v[246:249], v[4:7]
	v_mfma_f32_16x16x32_bf16 v[0:3], v[196:199], v[246:249], v[0:3]
	s_barrier
	s_add_i32 s54, 0, 0x18000
	v_add_u32_e32 v145, s54, v143
	s_add_i32 s55, 0, 0x1c000
	ds_read_b128 v[146:149], v145
	ds_read_b128 v[150:153], v145 offset:1024
	ds_read_b128 v[154:157], v145 offset:2048
	ds_read_b128 v[172:175], v145 offset:3072
	v_add_u32_e32 v145, s55, v143
	ds_read_b128 v[176:179], v145
	ds_read_b128 v[180:183], v145 offset:1024
	ds_read_b128 v[184:187], v145 offset:2048
	ds_read_b128 v[196:199], v145 offset:3072
	s_add_u32 s30, s30, 0x100000
	s_addc_u32 s31, s31, 0
	s_mov_b32 m0, s42
	v_lshl_add_u64 v[216:217], s[30:31], 0, v[134:135]
	ds_read_b128 v[200:203], v144 offset:32768
	ds_read_b128 v[204:207], v144 offset:33792
	ds_read_b128 v[208:211], v144 offset:34816
	ds_read_b128 v[212:215], v144 offset:35840
	ds_read_b128 v[234:237], v144 offset:36864
	ds_read_b128 v[238:241], v144 offset:37888
	ds_read_b128 v[242:245], v144 offset:38912
	ds_read_b128 v[246:249], v144 offset:39936
	global_load_lds_dwordx4 v[216:217], off
	v_lshl_add_u64 v[216:217], s[30:31], 0, v[130:131]
	s_mov_b32 m0, s43
	s_nop 0
	global_load_lds_dwordx4 v[216:217], off
	s_waitcnt vmcnt(8)
	s_waitcnt lgkmcnt(0)
	s_barrier
	s_waitcnt lgkmcnt(0)
	v_mfma_f32_16x16x32_bf16 v[124:127], v[146:149], v[200:203], v[124:127]
	v_mfma_f32_16x16x32_bf16 v[120:123], v[154:157], v[200:203], v[120:123]
	v_mfma_f32_16x16x32_bf16 v[116:119], v[146:149], v[208:211], v[116:119]
	v_mfma_f32_16x16x32_bf16 v[108:111], v[154:157], v[208:211], v[108:111]
	v_mfma_f32_16x16x32_bf16 v[100:103], v[146:149], v[234:237], v[100:103]
	v_mfma_f32_16x16x32_bf16 v[92:95], v[154:157], v[234:237], v[92:95]
	v_mfma_f32_16x16x32_bf16 v[84:87], v[146:149], v[242:245], v[84:87]
	v_mfma_f32_16x16x32_bf16 v[76:79], v[154:157], v[242:245], v[76:79]
	v_mfma_f32_16x16x32_bf16 v[124:127], v[150:153], v[204:207], v[124:127]
	v_mfma_f32_16x16x32_bf16 v[120:123], v[172:175], v[204:207], v[120:123]
	v_mfma_f32_16x16x32_bf16 v[116:119], v[150:153], v[212:215], v[116:119]
	v_mfma_f32_16x16x32_bf16 v[108:111], v[172:175], v[212:215], v[108:111]
	v_mfma_f32_16x16x32_bf16 v[100:103], v[150:153], v[238:241], v[100:103]
	v_mfma_f32_16x16x32_bf16 v[92:95], v[172:175], v[238:241], v[92:95]
	v_mfma_f32_16x16x32_bf16 v[84:87], v[150:153], v[246:249], v[84:87]
	v_mfma_f32_16x16x32_bf16 v[76:79], v[172:175], v[246:249], v[76:79]
	v_mfma_f32_16x16x32_bf16 v[112:115], v[176:179], v[200:203], v[112:115]
	v_mfma_f32_16x16x32_bf16 v[104:107], v[184:187], v[200:203], v[104:107]
	v_mfma_f32_16x16x32_bf16 v[96:99], v[176:179], v[208:211], v[96:99]
	v_mfma_f32_16x16x32_bf16 v[88:91], v[184:187], v[208:211], v[88:91]
	v_mfma_f32_16x16x32_bf16 v[80:83], v[176:179], v[234:237], v[80:83]
	v_mfma_f32_16x16x32_bf16 v[72:75], v[184:187], v[234:237], v[72:75]
	v_mfma_f32_16x16x32_bf16 v[68:71], v[176:179], v[242:245], v[68:71]
	v_mfma_f32_16x16x32_bf16 v[64:67], v[184:187], v[242:245], v[64:67]
	v_mfma_f32_16x16x32_bf16 v[112:115], v[180:183], v[204:207], v[112:115]
	v_mfma_f32_16x16x32_bf16 v[104:107], v[196:199], v[204:207], v[104:107]
	v_mfma_f32_16x16x32_bf16 v[96:99], v[180:183], v[212:215], v[96:99]
	v_mfma_f32_16x16x32_bf16 v[88:91], v[196:199], v[212:215], v[88:91]
	v_mfma_f32_16x16x32_bf16 v[80:83], v[180:183], v[238:241], v[80:83]
	v_mfma_f32_16x16x32_bf16 v[72:75], v[196:199], v[238:241], v[72:75]
	v_mfma_f32_16x16x32_bf16 v[68:71], v[180:183], v[246:249], v[68:71]
	v_mfma_f32_16x16x32_bf16 v[64:67], v[196:199], v[246:249], v[64:67]
	s_barrier
	s_add_i32 s30, s54, s37
	v_lshl_add_u64 v[140:141], v[140:141], 0, s[20:21]
	s_mov_b32 m0, s30
	ds_read_b128 v[200:203], v144 offset:49152
	ds_read_b128 v[204:207], v144 offset:50176
	ds_read_b128 v[208:211], v144 offset:51200
	ds_read_b128 v[212:215], v144 offset:52224
	ds_read_b128 v[234:237], v144 offset:53248
	ds_read_b128 v[238:241], v144 offset:54272
	ds_read_b128 v[242:245], v144 offset:55296
	ds_read_b128 v[246:249], v144 offset:56320
	global_load_lds_dwordx4 v[140:141], off
	s_add_i32 m0, s30, 0x2000
	s_add_u32 s28, s28, 0x20080
	v_lshl_add_u64 v[140:141], v[158:159], 0, s[20:21]
	s_addc_u32 s29, s29, 0
	s_add_i32 s30, s55, s37
	global_load_lds_dwordx4 v[140:141], off
	v_lshl_add_u64 v[140:141], s[28:29], 0, v[132:133]
	s_mov_b32 m0, s30
	s_nop 0
	global_load_lds_dwordx4 v[140:141], off
	v_lshl_add_u64 v[140:141], s[28:29], 0, v[128:129]
	s_add_i32 m0, s30, 0x2000
	s_nop 0
	global_load_lds_dwordx4 v[140:141], off
	v_lshl_add_u64 v[140:141], v[188:189], 0, s[20:21]
	s_mov_b32 m0, s44
	s_nop 0
	global_load_lds_dwordx4 v[140:141], off
	v_lshl_add_u64 v[140:141], v[250:251], 0, s[20:21]
	s_mov_b32 m0, s45
	s_nop 0
	global_load_lds_dwordx4 v[140:141], off
	s_waitcnt vmcnt(8)
	s_waitcnt lgkmcnt(0)
	s_barrier
	s_waitcnt lgkmcnt(0)
	v_mfma_f32_16x16x32_bf16 v[60:63], v[146:149], v[200:203], v[60:63]
	v_mfma_f32_16x16x32_bf16 v[56:59], v[154:157], v[200:203], v[56:59]
	v_mfma_f32_16x16x32_bf16 v[52:55], v[146:149], v[208:211], v[52:55]
	v_mfma_f32_16x16x32_bf16 v[44:47], v[154:157], v[208:211], v[44:47]
	v_mfma_f32_16x16x32_bf16 v[36:39], v[146:149], v[234:237], v[36:39]
	v_mfma_f32_16x16x32_bf16 v[28:31], v[154:157], v[234:237], v[28:31]
	v_mfma_f32_16x16x32_bf16 v[20:23], v[146:149], v[242:245], v[20:23]
	v_mfma_f32_16x16x32_bf16 v[12:15], v[154:157], v[242:245], v[12:15]
	v_mfma_f32_16x16x32_bf16 v[60:63], v[150:153], v[204:207], v[60:63]
	v_mfma_f32_16x16x32_bf16 v[56:59], v[172:175], v[204:207], v[56:59]
	v_mfma_f32_16x16x32_bf16 v[52:55], v[150:153], v[212:215], v[52:55]
	v_mfma_f32_16x16x32_bf16 v[44:47], v[172:175], v[212:215], v[44:47]
	v_mfma_f32_16x16x32_bf16 v[36:39], v[150:153], v[238:241], v[36:39]
	v_mfma_f32_16x16x32_bf16 v[28:31], v[172:175], v[238:241], v[28:31]
	v_mfma_f32_16x16x32_bf16 v[20:23], v[150:153], v[246:249], v[20:23]
	v_mfma_f32_16x16x32_bf16 v[12:15], v[172:175], v[246:249], v[12:15]
	v_mfma_f32_16x16x32_bf16 v[48:51], v[176:179], v[200:203], v[48:51]
	v_mfma_f32_16x16x32_bf16 v[40:43], v[184:187], v[200:203], v[40:43]
	v_mfma_f32_16x16x32_bf16 v[32:35], v[176:179], v[208:211], v[32:35]
	v_mfma_f32_16x16x32_bf16 v[24:27], v[184:187], v[208:211], v[24:27]
	v_mfma_f32_16x16x32_bf16 v[16:19], v[176:179], v[234:237], v[16:19]
	v_mfma_f32_16x16x32_bf16 v[8:11], v[184:187], v[234:237], v[8:11]
	v_mfma_f32_16x16x32_bf16 v[4:7], v[176:179], v[242:245], v[4:7]
	v_mfma_f32_16x16x32_bf16 v[0:3], v[184:187], v[242:245], v[0:3]
	v_mfma_f32_16x16x32_bf16 v[48:51], v[180:183], v[204:207], v[48:51]
	v_mfma_f32_16x16x32_bf16 v[40:43], v[196:199], v[204:207], v[40:43]
	v_mfma_f32_16x16x32_bf16 v[32:35], v[180:183], v[212:215], v[32:35]
	v_mfma_f32_16x16x32_bf16 v[24:27], v[196:199], v[212:215], v[24:27]
	v_mfma_f32_16x16x32_bf16 v[16:19], v[180:183], v[238:241], v[16:19]
	v_mfma_f32_16x16x32_bf16 v[8:11], v[196:199], v[238:241], v[8:11]
	v_mfma_f32_16x16x32_bf16 v[4:7], v[180:183], v[246:249], v[4:7]
	v_mfma_f32_16x16x32_bf16 v[0:3], v[196:199], v[246:249], v[0:3]
	s_barrier
	s_add_i32 s53, s53, 2
	s_add_u32 s26, s26, 0x100
	s_addc_u32 s27, s27, 0
	s_add_u32 s51, s51, 0x100
	s_addc_u32 s52, s52, 0
	s_cmp_gt_u32 s53, 5
	s_cbranch_scc0 .LBB0_542
	s_and_b64 vcc, exec, s[10:11]
	s_cbranch_vccz .LBB0_545
	s_barrier

.LBB0_558:
	s_add_u32 s26, s18, 0xfffe0080
	s_addc_u32 s27, s19, -1
	s_add_i32 s52, 0, 0x10000
	s_cmp_eq_u32 s51, 4
	s_cselect_b32 s29, s13, s27
	s_cselect_b32 s28, s47, s26
	s_cselect_b32 s27, s11, s50
	s_cselect_b32 s26, s48, s49
	s_add_i32 s54, 0, 0x14000
	v_add_u32_e32 v154, s52, v139
	v_add_u32_e32 v158, s54, v139
	ds_read_b128 v[142:145], v154
	ds_read_b128 v[146:149], v154 offset:1024
	ds_read_b128 v[150:153], v154 offset:2048
	ds_read_b128 v[154:157], v154 offset:3072
	ds_read_b128 v[172:175], v158
	ds_read_b128 v[176:179], v158 offset:1024
	ds_read_b128 v[180:183], v158 offset:2048
	ds_read_b128 v[184:187], v158 offset:3072
	v_lshl_add_u64 v[158:159], s[18:19], 0, v[134:135]
	s_add_i32 m0, s36, 0xc000
	ds_read_b128 v[196:199], v141
	ds_read_b128 v[200:203], v141 offset:1024
	ds_read_b128 v[204:207], v141 offset:2048
	ds_read_b128 v[208:211], v141 offset:3072
	ds_read_b128 v[212:215], v141 offset:4096
	ds_read_b128 v[234:237], v141 offset:5120
	ds_read_b128 v[238:241], v141 offset:6144
	ds_read_b128 v[242:245], v141 offset:7168
	global_load_lds_dwordx4 v[158:159], off
	v_lshl_add_u64 v[158:159], s[18:19], 0, v[136:137]
	s_add_i32 m0, s36, 0xe000
	s_nop 0
	global_load_lds_dwordx4 v[158:159], off
	s_waitcnt vmcnt(8)
	s_waitcnt lgkmcnt(0)
	s_barrier
	s_waitcnt lgkmcnt(0)
	v_mfma_f32_16x16x32_bf16 v[124:127], v[142:145], v[196:199], v[124:127]
	v_mfma_f32_16x16x32_bf16 v[120:123], v[150:153], v[196:199], v[120:123]
	v_mfma_f32_16x16x32_bf16 v[112:115], v[142:145], v[204:207], v[112:115]
	v_mfma_f32_16x16x32_bf16 v[104:107], v[150:153], v[204:207], v[104:107]
	v_mfma_f32_16x16x32_bf16 v[96:99], v[142:145], v[212:215], v[96:99]
	v_mfma_f32_16x16x32_bf16 v[88:91], v[150:153], v[212:215], v[88:91]
	v_mfma_f32_16x16x32_bf16 v[80:83], v[142:145], v[238:241], v[80:83]
	v_mfma_f32_16x16x32_bf16 v[72:75], v[150:153], v[238:241], v[72:75]
	v_mfma_f32_16x16x32_bf16 v[124:127], v[146:149], v[200:203], v[124:127]
	v_mfma_f32_16x16x32_bf16 v[120:123], v[154:157], v[200:203], v[120:123]
	v_mfma_f32_16x16x32_bf16 v[112:115], v[146:149], v[208:211], v[112:115]
	v_mfma_f32_16x16x32_bf16 v[104:107], v[154:157], v[208:211], v[104:107]
	v_mfma_f32_16x16x32_bf16 v[96:99], v[146:149], v[234:237], v[96:99]
	v_mfma_f32_16x16x32_bf16 v[88:91], v[154:157], v[234:237], v[88:91]
	v_mfma_f32_16x16x32_bf16 v[80:83], v[146:149], v[242:245], v[80:83]
	v_mfma_f32_16x16x32_bf16 v[72:75], v[154:157], v[242:245], v[72:75]
	v_mfma_f32_16x16x32_bf16 v[116:119], v[172:175], v[196:199], v[116:119]
	v_mfma_f32_16x16x32_bf16 v[108:111], v[180:183], v[196:199], v[108:111]
	v_mfma_f32_16x16x32_bf16 v[100:103], v[172:175], v[204:207], v[100:103]
	v_mfma_f32_16x16x32_bf16 v[92:95], v[180:183], v[204:207], v[92:95]
	v_mfma_f32_16x16x32_bf16 v[84:87], v[172:175], v[212:215], v[84:87]
	v_mfma_f32_16x16x32_bf16 v[76:79], v[180:183], v[212:215], v[76:79]
	v_mfma_f32_16x16x32_bf16 v[68:71], v[172:175], v[238:241], v[68:71]
	v_mfma_f32_16x16x32_bf16 v[64:67], v[180:183], v[238:241], v[64:67]
	v_mfma_f32_16x16x32_bf16 v[116:119], v[176:179], v[200:203], v[116:119]
	v_mfma_f32_16x16x32_bf16 v[108:111], v[184:187], v[200:203], v[108:111]
	v_mfma_f32_16x16x32_bf16 v[100:103], v[176:179], v[208:211], v[100:103]
	v_mfma_f32_16x16x32_bf16 v[92:95], v[184:187], v[208:211], v[92:95]
	v_mfma_f32_16x16x32_bf16 v[84:87], v[176:179], v[234:237], v[84:87]
	v_mfma_f32_16x16x32_bf16 v[76:79], v[184:187], v[234:237], v[76:79]
	v_mfma_f32_16x16x32_bf16 v[68:71], v[176:179], v[242:245], v[68:71]
	v_mfma_f32_16x16x32_bf16 v[64:67], v[184:187], v[242:245], v[64:67]
	s_barrier
	s_add_i32 s52, s52, s35
	v_lshl_add_u64 v[158:159], s[26:27], 0, v[160:161]
	s_mov_b32 m0, s52
	ds_read_b128 v[196:199], v141 offset:16384
	ds_read_b128 v[200:203], v141 offset:17408
	ds_read_b128 v[204:207], v141 offset:18432
	ds_read_b128 v[208:211], v141 offset:19456
	ds_read_b128 v[212:215], v141 offset:20480
	ds_read_b128 v[234:237], v141 offset:21504
	ds_read_b128 v[238:241], v141 offset:22528
	ds_read_b128 v[242:245], v141 offset:23552
	global_load_lds_dwordx4 v[158:159], off
	s_add_i32 m0, s52, 0x2000
	s_add_u32 s52, s26, 0x100000
	v_lshl_add_u64 v[188:189], s[26:27], 0, v[128:129]
	s_addc_u32 s53, s27, 0
	s_add_i32 s54, s54, s35
	global_load_lds_dwordx4 v[188:189], off
	v_lshl_add_u64 v[216:217], s[52:53], 0, v[160:161]
	s_mov_b32 m0, s54
	v_lshl_add_u64 v[246:247], s[28:29], 0, v[130:131]
	global_load_lds_dwordx4 v[216:217], off
	v_lshl_add_u64 v[216:217], s[52:53], 0, v[128:129]
	s_add_i32 m0, s54, 0x2000
	s_nop 0
	global_load_lds_dwordx4 v[216:217], off
	v_lshl_add_u64 v[216:217], s[28:29], 0, v[132:133]
	s_mov_b32 m0, s36
	s_nop 0
	global_load_lds_dwordx4 v[216:217], off
	s_mov_b32 m0, s37
	s_nop 0
	global_load_lds_dwordx4 v[246:247], off
	s_waitcnt vmcnt(8)
	s_waitcnt lgkmcnt(0)
	s_barrier
	s_waitcnt lgkmcnt(0)
	v_mfma_f32_16x16x32_bf16 v[60:63], v[142:145], v[196:199], v[60:63]
	v_mfma_f32_16x16x32_bf16 v[56:59], v[150:153], v[196:199], v[56:59]
	v_mfma_f32_16x16x32_bf16 v[48:51], v[142:145], v[204:207], v[48:51]
	v_mfma_f32_16x16x32_bf16 v[40:43], v[150:153], v[204:207], v[40:43]
	v_mfma_f32_16x16x32_bf16 v[32:35], v[142:145], v[212:215], v[32:35]
	v_mfma_f32_16x16x32_bf16 v[24:27], v[150:153], v[212:215], v[24:27]
	v_mfma_f32_16x16x32_bf16 v[16:19], v[142:145], v[238:241], v[16:19]
	v_mfma_f32_16x16x32_bf16 v[8:11], v[150:153], v[238:241], v[8:11]
	v_mfma_f32_16x16x32_bf16 v[60:63], v[146:149], v[200:203], v[60:63]
	v_mfma_f32_16x16x32_bf16 v[56:59], v[154:157], v[200:203], v[56:59]
	v_mfma_f32_16x16x32_bf16 v[48:51], v[146:149], v[208:211], v[48:51]
	v_mfma_f32_16x16x32_bf16 v[40:43], v[154:157], v[208:211], v[40:43]
	v_mfma_f32_16x16x32_bf16 v[32:35], v[146:149], v[234:237], v[32:35]
	v_mfma_f32_16x16x32_bf16 v[24:27], v[154:157], v[234:237], v[24:27]
	v_mfma_f32_16x16x32_bf16 v[16:19], v[146:149], v[242:245], v[16:19]
	v_mfma_f32_16x16x32_bf16 v[8:11], v[154:157], v[242:245], v[8:11]
	v_mfma_f32_16x16x32_bf16 v[52:55], v[172:175], v[196:199], v[52:55]
	v_mfma_f32_16x16x32_bf16 v[44:47], v[180:183], v[196:199], v[44:47]
	v_mfma_f32_16x16x32_bf16 v[36:39], v[172:175], v[204:207], v[36:39]
	v_mfma_f32_16x16x32_bf16 v[28:31], v[180:183], v[204:207], v[28:31]
	v_mfma_f32_16x16x32_bf16 v[20:23], v[172:175], v[212:215], v[20:23]
	v_mfma_f32_16x16x32_bf16 v[12:15], v[180:183], v[212:215], v[12:15]
	v_mfma_f32_16x16x32_bf16 v[4:7], v[172:175], v[238:241], v[4:7]
	v_mfma_f32_16x16x32_bf16 v[0:3], v[180:183], v[238:241], v[0:3]
	v_mfma_f32_16x16x32_bf16 v[52:55], v[176:179], v[200:203], v[52:55]
	v_mfma_f32_16x16x32_bf16 v[44:47], v[184:187], v[200:203], v[44:47]
	v_mfma_f32_16x16x32_bf16 v[36:39], v[176:179], v[208:211], v[36:39]
	v_mfma_f32_16x16x32_bf16 v[28:31], v[184:187], v[208:211], v[28:31]
	v_mfma_f32_16x16x32_bf16 v[20:23], v[176:179], v[234:237], v[20:23]
	v_mfma_f32_16x16x32_bf16 v[12:15], v[184:187], v[234:237], v[12:15]
	v_mfma_f32_16x16x32_bf16 v[4:7], v[176:179], v[242:245], v[4:7]
	v_mfma_f32_16x16x32_bf16 v[0:3], v[184:187], v[242:245], v[0:3]
	s_barrier
	s_add_i32 s52, 0, 0x18000
	s_add_i32 s53, 0, 0x1c000
	v_add_u32_e32 v154, s52, v139
	v_add_u32_e32 v162, s53, v139
	ds_read_b128 v[142:145], v154
	ds_read_b128 v[146:149], v154 offset:1024
	ds_read_b128 v[150:153], v154 offset:2048
	ds_read_b128 v[154:157], v154 offset:3072
	ds_read_b128 v[172:175], v162
	ds_read_b128 v[176:179], v162 offset:1024
	ds_read_b128 v[180:183], v162 offset:2048
	ds_read_b128 v[184:187], v162 offset:3072
	s_add_u32 s28, s28, 0x20000
	s_addc_u32 s29, s29, 0
	s_mov_b32 m0, s40
	v_lshl_add_u64 v[248:249], s[28:29], 0, v[132:133]
	ds_read_b128 v[196:199], v141 offset:32768
	ds_read_b128 v[200:203], v141 offset:33792
	ds_read_b128 v[204:207], v141 offset:34816
	ds_read_b128 v[208:211], v141 offset:35840
	ds_read_b128 v[212:215], v141 offset:36864
	ds_read_b128 v[234:237], v141 offset:37888
	ds_read_b128 v[238:241], v141 offset:38912
	ds_read_b128 v[242:245], v141 offset:39936
	global_load_lds_dwordx4 v[248:249], off
	v_lshl_add_u64 v[248:249], s[28:29], 0, v[130:131]
	s_mov_b32 m0, s41
	s_nop 0
	global_load_lds_dwordx4 v[248:249], off
	s_waitcnt vmcnt(8)
	s_waitcnt lgkmcnt(0)
	s_barrier
	s_waitcnt lgkmcnt(0)
	v_mfma_f32_16x16x32_bf16 v[124:127], v[142:145], v[196:199], v[124:127]
	v_mfma_f32_16x16x32_bf16 v[120:123], v[150:153], v[196:199], v[120:123]
	v_mfma_f32_16x16x32_bf16 v[112:115], v[142:145], v[204:207], v[112:115]
	v_mfma_f32_16x16x32_bf16 v[104:107], v[150:153], v[204:207], v[104:107]
	v_mfma_f32_16x16x32_bf16 v[96:99], v[142:145], v[212:215], v[96:99]
	v_mfma_f32_16x16x32_bf16 v[88:91], v[150:153], v[212:215], v[88:91]
	v_mfma_f32_16x16x32_bf16 v[80:83], v[142:145], v[238:241], v[80:83]
	v_mfma_f32_16x16x32_bf16 v[72:75], v[150:153], v[238:241], v[72:75]
	v_mfma_f32_16x16x32_bf16 v[124:127], v[146:149], v[200:203], v[124:127]
	v_mfma_f32_16x16x32_bf16 v[120:123], v[154:157], v[200:203], v[120:123]
	v_mfma_f32_16x16x32_bf16 v[112:115], v[146:149], v[208:211], v[112:115]
	v_mfma_f32_16x16x32_bf16 v[104:107], v[154:157], v[208:211], v[104:107]
	v_mfma_f32_16x16x32_bf16 v[96:99], v[146:149], v[234:237], v[96:99]
	v_mfma_f32_16x16x32_bf16 v[88:91], v[154:157], v[234:237], v[88:91]
	v_mfma_f32_16x16x32_bf16 v[80:83], v[146:149], v[242:245], v[80:83]
	v_mfma_f32_16x16x32_bf16 v[72:75], v[154:157], v[242:245], v[72:75]
	v_mfma_f32_16x16x32_bf16 v[116:119], v[172:175], v[196:199], v[116:119]
	v_mfma_f32_16x16x32_bf16 v[108:111], v[180:183], v[196:199], v[108:111]
	v_mfma_f32_16x16x32_bf16 v[100:103], v[172:175], v[204:207], v[100:103]
	v_mfma_f32_16x16x32_bf16 v[92:95], v[180:183], v[204:207], v[92:95]
	v_mfma_f32_16x16x32_bf16 v[84:87], v[172:175], v[212:215], v[84:87]
	v_mfma_f32_16x16x32_bf16 v[76:79], v[180:183], v[212:215], v[76:79]
	v_mfma_f32_16x16x32_bf16 v[68:71], v[172:175], v[238:241], v[68:71]
	v_mfma_f32_16x16x32_bf16 v[64:67], v[180:183], v[238:241], v[64:67]
	v_mfma_f32_16x16x32_bf16 v[116:119], v[176:179], v[200:203], v[116:119]
	v_mfma_f32_16x16x32_bf16 v[108:111], v[184:187], v[200:203], v[108:111]
	v_mfma_f32_16x16x32_bf16 v[100:103], v[176:179], v[208:211], v[100:103]
	v_mfma_f32_16x16x32_bf16 v[92:95], v[184:187], v[208:211], v[92:95]
	v_mfma_f32_16x16x32_bf16 v[84:87], v[176:179], v[234:237], v[84:87]
	v_mfma_f32_16x16x32_bf16 v[76:79], v[184:187], v[234:237], v[76:79]
	v_mfma_f32_16x16x32_bf16 v[68:71], v[176:179], v[242:245], v[68:71]
	v_mfma_f32_16x16x32_bf16 v[64:67], v[184:187], v[242:245], v[64:67]
	s_barrier
	s_add_i32 s28, s52, s35
	v_lshl_add_u64 v[158:159], v[158:159], 0, s[20:21]
	s_mov_b32 m0, s28
	ds_read_b128 v[196:199], v141 offset:49152
	ds_read_b128 v[200:203], v141 offset:50176
	ds_read_b128 v[204:207], v141 offset:51200
	ds_read_b128 v[208:211], v141 offset:52224
	ds_read_b128 v[212:215], v141 offset:53248
	ds_read_b128 v[234:237], v141 offset:54272
	ds_read_b128 v[238:241], v141 offset:55296
	ds_read_b128 v[242:245], v141 offset:56320
	global_load_lds_dwordx4 v[158:159], off
	s_add_i32 m0, s28, 0x2000
	s_add_u32 s26, s26, 0x100080
	v_lshl_add_u64 v[158:159], v[188:189], 0, s[20:21]
	s_addc_u32 s27, s27, 0
	s_add_i32 s28, s53, s35
	global_load_lds_dwordx4 v[158:159], off
	v_lshl_add_u64 v[158:159], s[26:27], 0, v[160:161]
	s_mov_b32 m0, s28
	s_nop 0
	global_load_lds_dwordx4 v[158:159], off
	v_lshl_add_u64 v[158:159], s[26:27], 0, v[128:129]
	s_add_i32 m0, s28, 0x2000
	s_nop 0
	global_load_lds_dwordx4 v[158:159], off
	v_lshl_add_u64 v[158:159], v[216:217], 0, s[20:21]
	s_mov_b32 m0, s42
	s_nop 0
	global_load_lds_dwordx4 v[158:159], off
	v_lshl_add_u64 v[158:159], v[246:247], 0, s[20:21]
	s_mov_b32 m0, s43
	s_nop 0
	global_load_lds_dwordx4 v[158:159], off
	s_waitcnt vmcnt(8)
	s_waitcnt lgkmcnt(0)
	s_barrier
	s_waitcnt lgkmcnt(0)
	v_mfma_f32_16x16x32_bf16 v[60:63], v[142:145], v[196:199], v[60:63]
	v_mfma_f32_16x16x32_bf16 v[56:59], v[150:153], v[196:199], v[56:59]
	v_mfma_f32_16x16x32_bf16 v[48:51], v[142:145], v[204:207], v[48:51]
	v_mfma_f32_16x16x32_bf16 v[40:43], v[150:153], v[204:207], v[40:43]
	v_mfma_f32_16x16x32_bf16 v[32:35], v[142:145], v[212:215], v[32:35]
	v_mfma_f32_16x16x32_bf16 v[24:27], v[150:153], v[212:215], v[24:27]
	v_mfma_f32_16x16x32_bf16 v[16:19], v[142:145], v[238:241], v[16:19]
	v_mfma_f32_16x16x32_bf16 v[8:11], v[150:153], v[238:241], v[8:11]
	v_mfma_f32_16x16x32_bf16 v[60:63], v[146:149], v[200:203], v[60:63]
	v_mfma_f32_16x16x32_bf16 v[56:59], v[154:157], v[200:203], v[56:59]
	v_mfma_f32_16x16x32_bf16 v[48:51], v[146:149], v[208:211], v[48:51]
	v_mfma_f32_16x16x32_bf16 v[40:43], v[154:157], v[208:211], v[40:43]
	v_mfma_f32_16x16x32_bf16 v[32:35], v[146:149], v[234:237], v[32:35]
	v_mfma_f32_16x16x32_bf16 v[24:27], v[154:157], v[234:237], v[24:27]
	v_mfma_f32_16x16x32_bf16 v[16:19], v[146:149], v[242:245], v[16:19]
	v_mfma_f32_16x16x32_bf16 v[8:11], v[154:157], v[242:245], v[8:11]
	v_mfma_f32_16x16x32_bf16 v[52:55], v[172:175], v[196:199], v[52:55]
	v_mfma_f32_16x16x32_bf16 v[44:47], v[180:183], v[196:199], v[44:47]
	v_mfma_f32_16x16x32_bf16 v[36:39], v[172:175], v[204:207], v[36:39]
	v_mfma_f32_16x16x32_bf16 v[28:31], v[180:183], v[204:207], v[28:31]
	v_mfma_f32_16x16x32_bf16 v[20:23], v[172:175], v[212:215], v[20:23]
	v_mfma_f32_16x16x32_bf16 v[12:15], v[180:183], v[212:215], v[12:15]
	v_mfma_f32_16x16x32_bf16 v[4:7], v[172:175], v[238:241], v[4:7]
	v_mfma_f32_16x16x32_bf16 v[0:3], v[180:183], v[238:241], v[0:3]
	v_mfma_f32_16x16x32_bf16 v[52:55], v[176:179], v[200:203], v[52:55]
	v_mfma_f32_16x16x32_bf16 v[44:47], v[184:187], v[200:203], v[44:47]
	v_mfma_f32_16x16x32_bf16 v[36:39], v[176:179], v[208:211], v[36:39]
	v_mfma_f32_16x16x32_bf16 v[28:31], v[184:187], v[208:211], v[28:31]
	v_mfma_f32_16x16x32_bf16 v[20:23], v[176:179], v[234:237], v[20:23]
	v_mfma_f32_16x16x32_bf16 v[12:15], v[184:187], v[234:237], v[12:15]
	v_mfma_f32_16x16x32_bf16 v[4:7], v[176:179], v[242:245], v[4:7]
	v_mfma_f32_16x16x32_bf16 v[0:3], v[184:187], v[242:245], v[0:3]
	s_barrier
	s_add_i32 s51, s51, 2
	s_add_u32 s18, s18, 0x100
	s_addc_u32 s19, s19, 0
	s_add_u32 s49, s49, 0x100
	s_addc_u32 s50, s50, 0
	s_cmp_gt_u32 s51, 5
	s_cbranch_scc0 .LBB0_558
	s_and_b64 vcc, exec, s[8:9]
	s_cbranch_vccz .LBB0_561
	s_barrier

.LBB0_1024:
	s_add_u32 s30, s28, 0xfffc0080
	s_addc_u32 s31, s29, -1
	s_add_i32 s59, 0, 0x10000
	s_cmp_eq_u32 s58, 12
	s_cselect_b32 s35, s15, s31
	s_cselect_b32 s34, s54, s30
	s_cselect_b32 s31, s13, s57
	s_cselect_b32 s30, s55, s56
	s_add_i32 s62, 0, 0x14000
	v_add_u32_e32 v36, s59, v186
	v_add_u32_e32 v178, s62, v186
	ds_read_b128 v[16:19], v36
	ds_read_b128 v[20:23], v36 offset:1024
	ds_read_b128 v[32:35], v36 offset:2048
	ds_read_b128 v[36:39], v36 offset:3072
	ds_read_b128 v[128:131], v178
	ds_read_b128 v[140:143], v178 offset:1024
	ds_read_b128 v[152:155], v178 offset:2048
	ds_read_b128 v[178:181], v178 offset:3072
	v_lshl_add_u64 v[216:217], s[28:29], 0, v[174:175]
	s_add_i32 m0, s47, 0xc000
	ds_read_b128 v[182:185], v188
	ds_read_b128 v[196:199], v188 offset:1024
	ds_read_b128 v[200:203], v188 offset:2048
	ds_read_b128 v[204:207], v188 offset:3072
	ds_read_b128 v[208:211], v188 offset:4096
	ds_read_b128 v[212:215], v188 offset:5120
	ds_read_b128 v[234:237], v188 offset:6144
	ds_read_b128 v[238:241], v188 offset:7168
	global_load_lds_dwordx4 v[216:217], off
	v_lshl_add_u64 v[216:217], s[28:29], 0, v[176:177]
	s_add_i32 m0, s47, 0xe000
	s_nop 0
	global_load_lds_dwordx4 v[216:217], off
	s_waitcnt vmcnt(8)
	s_waitcnt lgkmcnt(0)
	s_barrier
	s_waitcnt lgkmcnt(0)
	v_mfma_f32_16x16x32_bf16 v[148:151], v[16:19], v[182:185], v[148:151]
	v_mfma_f32_16x16x32_bf16 v[144:147], v[32:35], v[182:185], v[144:147]
	v_mfma_f32_16x16x32_bf16 v[124:127], v[16:19], v[200:203], v[124:127]
	v_mfma_f32_16x16x32_bf16 v[120:123], v[32:35], v[200:203], v[120:123]
	v_mfma_f32_16x16x32_bf16 v[108:111], v[16:19], v[208:211], v[108:111]
	v_mfma_f32_16x16x32_bf16 v[104:107], v[32:35], v[208:211], v[104:107]
	v_mfma_f32_16x16x32_bf16 v[92:95], v[16:19], v[234:237], v[92:95]
	v_mfma_f32_16x16x32_bf16 v[88:91], v[32:35], v[234:237], v[88:91]
	v_mfma_f32_16x16x32_bf16 v[148:151], v[20:23], v[196:199], v[148:151]
	v_mfma_f32_16x16x32_bf16 v[144:147], v[36:39], v[196:199], v[144:147]
	v_mfma_f32_16x16x32_bf16 v[124:127], v[20:23], v[204:207], v[124:127]
	v_mfma_f32_16x16x32_bf16 v[120:123], v[36:39], v[204:207], v[120:123]
	v_mfma_f32_16x16x32_bf16 v[108:111], v[20:23], v[212:215], v[108:111]
	v_mfma_f32_16x16x32_bf16 v[104:107], v[36:39], v[212:215], v[104:107]
	v_mfma_f32_16x16x32_bf16 v[92:95], v[20:23], v[238:241], v[92:95]
	v_mfma_f32_16x16x32_bf16 v[88:91], v[36:39], v[238:241], v[88:91]
	v_mfma_f32_16x16x32_bf16 v[136:139], v[128:131], v[182:185], v[136:139]
	v_mfma_f32_16x16x32_bf16 v[132:135], v[152:155], v[182:185], v[132:135]
	v_mfma_f32_16x16x32_bf16 v[116:119], v[128:131], v[200:203], v[116:119]
	v_mfma_f32_16x16x32_bf16 v[112:115], v[152:155], v[200:203], v[112:115]
	v_mfma_f32_16x16x32_bf16 v[100:103], v[128:131], v[208:211], v[100:103]
	v_mfma_f32_16x16x32_bf16 v[96:99], v[152:155], v[208:211], v[96:99]
	v_mfma_f32_16x16x32_bf16 v[84:87], v[128:131], v[234:237], v[84:87]
	v_mfma_f32_16x16x32_bf16 v[80:83], v[152:155], v[234:237], v[80:83]
	v_mfma_f32_16x16x32_bf16 v[136:139], v[140:143], v[196:199], v[136:139]
	v_mfma_f32_16x16x32_bf16 v[132:135], v[178:181], v[196:199], v[132:135]
	v_mfma_f32_16x16x32_bf16 v[116:119], v[140:143], v[204:207], v[116:119]
	v_mfma_f32_16x16x32_bf16 v[112:115], v[178:181], v[204:207], v[112:115]
	v_mfma_f32_16x16x32_bf16 v[100:103], v[140:143], v[212:215], v[100:103]
	v_mfma_f32_16x16x32_bf16 v[96:99], v[178:181], v[212:215], v[96:99]
	v_mfma_f32_16x16x32_bf16 v[84:87], v[140:143], v[238:241], v[84:87]
	v_mfma_f32_16x16x32_bf16 v[80:83], v[178:181], v[238:241], v[80:83]
	s_barrier
	s_add_i32 s59, s59, s44
	v_lshl_add_u64 v[216:217], s[30:31], 0, v[160:161]
	s_mov_b32 m0, s59
	ds_read_b128 v[182:185], v188 offset:16384
	ds_read_b128 v[196:199], v188 offset:17408
	ds_read_b128 v[200:203], v188 offset:18432
	ds_read_b128 v[204:207], v188 offset:19456
	ds_read_b128 v[208:211], v188 offset:20480
	ds_read_b128 v[212:215], v188 offset:21504
	ds_read_b128 v[234:237], v188 offset:22528
	ds_read_b128 v[238:241], v188 offset:23552
	global_load_lds_dwordx4 v[216:217], off
	s_add_i32 m0, s59, 0x2000
	s_add_u32 s60, s30, 0x40000
	v_lshl_add_u64 v[242:243], s[30:31], 0, v[156:157]
	s_addc_u32 s61, s31, 0
	s_add_i32 s59, s62, s44
	global_load_lds_dwordx4 v[242:243], off
	v_lshl_add_u64 v[244:245], s[60:61], 0, v[160:161]
	s_mov_b32 m0, s59
	v_lshl_add_u64 v[246:247], s[34:35], 0, v[158:159]
	global_load_lds_dwordx4 v[244:245], off
	v_lshl_add_u64 v[244:245], s[60:61], 0, v[156:157]
	s_add_i32 m0, s59, 0x2000
	s_nop 0
	global_load_lds_dwordx4 v[244:245], off
	v_lshl_add_u64 v[244:245], s[34:35], 0, v[172:173]
	s_mov_b32 m0, s47
	s_nop 0
	global_load_lds_dwordx4 v[244:245], off
	s_mov_b32 m0, s48
	s_nop 0
	global_load_lds_dwordx4 v[246:247], off
	s_waitcnt vmcnt(8)
	s_waitcnt lgkmcnt(0)
	s_barrier
	s_waitcnt lgkmcnt(0)
	v_mfma_f32_16x16x32_bf16 v[76:79], v[16:19], v[182:185], v[76:79]
	v_mfma_f32_16x16x32_bf16 v[72:75], v[32:35], v[182:185], v[72:75]
	v_mfma_f32_16x16x32_bf16 v[60:63], v[16:19], v[200:203], v[60:63]
	v_mfma_f32_16x16x32_bf16 v[56:59], v[32:35], v[200:203], v[56:59]
	v_mfma_f32_16x16x32_bf16 v[44:47], v[16:19], v[208:211], v[44:47]
	v_mfma_f32_16x16x32_bf16 v[40:43], v[32:35], v[208:211], v[40:43]
	v_mfma_f32_16x16x32_bf16 v[12:15], v[16:19], v[234:237], v[12:15]
	v_mfma_f32_16x16x32_bf16 v[8:11], v[32:35], v[234:237], v[8:11]
	v_mfma_f32_16x16x32_bf16 v[76:79], v[20:23], v[196:199], v[76:79]
	v_mfma_f32_16x16x32_bf16 v[72:75], v[36:39], v[196:199], v[72:75]
	v_mfma_f32_16x16x32_bf16 v[60:63], v[20:23], v[204:207], v[60:63]
	v_mfma_f32_16x16x32_bf16 v[56:59], v[36:39], v[204:207], v[56:59]
	v_mfma_f32_16x16x32_bf16 v[44:47], v[20:23], v[212:215], v[44:47]
	v_mfma_f32_16x16x32_bf16 v[40:43], v[36:39], v[212:215], v[40:43]
	v_mfma_f32_16x16x32_bf16 v[12:15], v[20:23], v[238:241], v[12:15]
	v_mfma_f32_16x16x32_bf16 v[8:11], v[36:39], v[238:241], v[8:11]
	v_mfma_f32_16x16x32_bf16 v[28:31], v[128:131], v[208:211], v[28:31]
	v_mfma_f32_16x16x32_bf16 v[24:27], v[152:155], v[208:211], v[24:27]
	v_mfma_f32_16x16x32_bf16 v[4:7], v[128:131], v[234:237], v[4:7]
	v_mfma_f32_16x16x32_bf16 v[0:3], v[152:155], v[234:237], v[0:3]
	v_mfma_f32_16x16x32_bf16 v[16:19], v[128:131], v[182:185], v[68:71]
	v_mfma_f32_16x16x32_bf16 v[20:23], v[152:155], v[182:185], v[64:67]
	v_mfma_f32_16x16x32_bf16 v[32:35], v[128:131], v[200:203], v[52:55]
	v_mfma_f32_16x16x32_bf16 v[36:39], v[152:155], v[200:203], v[48:51]
	v_mfma_f32_16x16x32_bf16 v[28:31], v[140:143], v[212:215], v[28:31]
	v_mfma_f32_16x16x32_bf16 v[24:27], v[178:181], v[212:215], v[24:27]
	v_mfma_f32_16x16x32_bf16 v[4:7], v[140:143], v[238:241], v[4:7]
	v_mfma_f32_16x16x32_bf16 v[0:3], v[178:181], v[238:241], v[0:3]
	v_mfma_f32_16x16x32_bf16 v[16:19], v[140:143], v[196:199], v[16:19]
	v_mfma_f32_16x16x32_bf16 v[20:23], v[178:181], v[196:199], v[20:23]
	v_mfma_f32_16x16x32_bf16 v[32:35], v[140:143], v[204:207], v[32:35]
	v_mfma_f32_16x16x32_bf16 v[36:39], v[178:181], v[204:207], v[36:39]
	s_barrier
	s_add_i32 s59, 0, 0x18000
	s_add_i32 s60, 0, 0x1c000
	v_add_u32_e32 v68, s59, v186
	v_add_u32_e32 v178, s60, v186
	ds_read_b128 v[48:51], v68
	ds_read_b128 v[52:55], v68 offset:1024
	ds_read_b128 v[64:67], v68 offset:2048
	ds_read_b128 v[68:71], v68 offset:3072
	ds_read_b128 v[128:131], v178
	ds_read_b128 v[140:143], v178 offset:1024
	ds_read_b128 v[152:155], v178 offset:2048
	ds_read_b128 v[178:181], v178 offset:3072
	s_add_u32 s34, s34, 0x40000
	s_addc_u32 s35, s35, 0
	s_mov_b32 m0, s49
	v_lshl_add_u64 v[248:249], s[34:35], 0, v[172:173]
	ds_read_b128 v[182:185], v188 offset:32768
	ds_read_b128 v[196:199], v188 offset:33792
	ds_read_b128 v[200:203], v188 offset:34816
	ds_read_b128 v[204:207], v188 offset:35840
	ds_read_b128 v[208:211], v188 offset:36864
	ds_read_b128 v[212:215], v188 offset:37888
	ds_read_b128 v[234:237], v188 offset:38912
	ds_read_b128 v[238:241], v188 offset:39936
	global_load_lds_dwordx4 v[248:249], off
	v_lshl_add_u64 v[248:249], s[34:35], 0, v[158:159]
	s_mov_b32 m0, s50
	s_nop 0
	global_load_lds_dwordx4 v[248:249], off
	s_waitcnt vmcnt(8)
	s_waitcnt lgkmcnt(0)
	s_barrier
	s_waitcnt lgkmcnt(0)
	v_mfma_f32_16x16x32_bf16 v[148:151], v[48:51], v[182:185], v[148:151]
	v_mfma_f32_16x16x32_bf16 v[144:147], v[64:67], v[182:185], v[144:147]
	v_mfma_f32_16x16x32_bf16 v[124:127], v[48:51], v[200:203], v[124:127]
	v_mfma_f32_16x16x32_bf16 v[120:123], v[64:67], v[200:203], v[120:123]
	v_mfma_f32_16x16x32_bf16 v[108:111], v[48:51], v[208:211], v[108:111]
	v_mfma_f32_16x16x32_bf16 v[104:107], v[64:67], v[208:211], v[104:107]
	v_mfma_f32_16x16x32_bf16 v[92:95], v[48:51], v[234:237], v[92:95]
	v_mfma_f32_16x16x32_bf16 v[88:91], v[64:67], v[234:237], v[88:91]
	v_mfma_f32_16x16x32_bf16 v[148:151], v[52:55], v[196:199], v[148:151]
	v_mfma_f32_16x16x32_bf16 v[144:147], v[68:71], v[196:199], v[144:147]
	v_mfma_f32_16x16x32_bf16 v[124:127], v[52:55], v[204:207], v[124:127]
	v_mfma_f32_16x16x32_bf16 v[120:123], v[68:71], v[204:207], v[120:123]
	v_mfma_f32_16x16x32_bf16 v[108:111], v[52:55], v[212:215], v[108:111]
	v_mfma_f32_16x16x32_bf16 v[104:107], v[68:71], v[212:215], v[104:107]
	v_mfma_f32_16x16x32_bf16 v[92:95], v[52:55], v[238:241], v[92:95]
	v_mfma_f32_16x16x32_bf16 v[88:91], v[68:71], v[238:241], v[88:91]
	v_mfma_f32_16x16x32_bf16 v[136:139], v[128:131], v[182:185], v[136:139]
	v_mfma_f32_16x16x32_bf16 v[132:135], v[152:155], v[182:185], v[132:135]
	v_mfma_f32_16x16x32_bf16 v[116:119], v[128:131], v[200:203], v[116:119]
	v_mfma_f32_16x16x32_bf16 v[112:115], v[152:155], v[200:203], v[112:115]
	v_mfma_f32_16x16x32_bf16 v[100:103], v[128:131], v[208:211], v[100:103]
	v_mfma_f32_16x16x32_bf16 v[96:99], v[152:155], v[208:211], v[96:99]
	v_mfma_f32_16x16x32_bf16 v[84:87], v[128:131], v[234:237], v[84:87]
	v_mfma_f32_16x16x32_bf16 v[80:83], v[152:155], v[234:237], v[80:83]
	v_mfma_f32_16x16x32_bf16 v[136:139], v[140:143], v[196:199], v[136:139]
	v_mfma_f32_16x16x32_bf16 v[132:135], v[178:181], v[196:199], v[132:135]
	v_mfma_f32_16x16x32_bf16 v[116:119], v[140:143], v[204:207], v[116:119]
	v_mfma_f32_16x16x32_bf16 v[112:115], v[178:181], v[204:207], v[112:115]
	v_mfma_f32_16x16x32_bf16 v[100:103], v[140:143], v[212:215], v[100:103]
	v_mfma_f32_16x16x32_bf16 v[96:99], v[178:181], v[212:215], v[96:99]
	v_mfma_f32_16x16x32_bf16 v[84:87], v[140:143], v[238:241], v[84:87]
	v_mfma_f32_16x16x32_bf16 v[80:83], v[178:181], v[238:241], v[80:83]
	s_barrier
	s_add_i32 s34, s59, s44
	v_lshl_add_u64 v[216:217], v[216:217], 0, s[20:21]
	s_mov_b32 m0, s34
	ds_read_b128 v[182:185], v188 offset:49152
	ds_read_b128 v[196:199], v188 offset:50176
	ds_read_b128 v[200:203], v188 offset:51200
	ds_read_b128 v[204:207], v188 offset:52224
	ds_read_b128 v[208:211], v188 offset:53248
	ds_read_b128 v[212:215], v188 offset:54272
	ds_read_b128 v[234:237], v188 offset:55296
	ds_read_b128 v[238:241], v188 offset:56320
	global_load_lds_dwordx4 v[216:217], off
	s_add_i32 m0, s34, 0x2000
	s_add_u32 s30, s30, 0x40080
	v_lshl_add_u64 v[216:217], v[242:243], 0, s[20:21]
	s_addc_u32 s31, s31, 0
	s_add_i32 s34, s60, s44
	global_load_lds_dwordx4 v[216:217], off
	v_lshl_add_u64 v[216:217], s[30:31], 0, v[160:161]
	s_mov_b32 m0, s34
	s_nop 0
	global_load_lds_dwordx4 v[216:217], off
	v_lshl_add_u64 v[216:217], s[30:31], 0, v[156:157]
	s_add_i32 m0, s34, 0x2000
	s_nop 0
	global_load_lds_dwordx4 v[216:217], off
	v_lshl_add_u64 v[216:217], v[244:245], 0, s[20:21]
	s_mov_b32 m0, s51
	s_nop 0
	global_load_lds_dwordx4 v[216:217], off
	v_lshl_add_u64 v[216:217], v[246:247], 0, s[20:21]
	s_mov_b32 m0, s52
	s_nop 0
	global_load_lds_dwordx4 v[216:217], off
	s_waitcnt vmcnt(8)
	s_waitcnt lgkmcnt(0)
	s_barrier
	s_waitcnt lgkmcnt(0)
	v_mfma_f32_16x16x32_bf16 v[76:79], v[48:51], v[182:185], v[76:79]
	v_mfma_f32_16x16x32_bf16 v[72:75], v[64:67], v[182:185], v[72:75]
	v_mfma_f32_16x16x32_bf16 v[60:63], v[48:51], v[200:203], v[60:63]
	v_mfma_f32_16x16x32_bf16 v[56:59], v[64:67], v[200:203], v[56:59]
	v_mfma_f32_16x16x32_bf16 v[44:47], v[48:51], v[208:211], v[44:47]
	v_mfma_f32_16x16x32_bf16 v[40:43], v[64:67], v[208:211], v[40:43]
	v_mfma_f32_16x16x32_bf16 v[12:15], v[48:51], v[234:237], v[12:15]
	v_mfma_f32_16x16x32_bf16 v[8:11], v[64:67], v[234:237], v[8:11]
	v_mfma_f32_16x16x32_bf16 v[76:79], v[52:55], v[196:199], v[76:79]
	v_mfma_f32_16x16x32_bf16 v[72:75], v[68:71], v[196:199], v[72:75]
	v_mfma_f32_16x16x32_bf16 v[60:63], v[52:55], v[204:207], v[60:63]
	v_mfma_f32_16x16x32_bf16 v[56:59], v[68:71], v[204:207], v[56:59]
	v_mfma_f32_16x16x32_bf16 v[44:47], v[52:55], v[212:215], v[44:47]
	v_mfma_f32_16x16x32_bf16 v[40:43], v[68:71], v[212:215], v[40:43]
	v_mfma_f32_16x16x32_bf16 v[12:15], v[52:55], v[238:241], v[12:15]
	v_mfma_f32_16x16x32_bf16 v[8:11], v[68:71], v[238:241], v[8:11]
	v_mfma_f32_16x16x32_bf16 v[16:19], v[128:131], v[182:185], v[16:19]
	v_mfma_f32_16x16x32_bf16 v[68:71], v[140:143], v[196:199], v[16:19]
	v_mfma_f32_16x16x32_bf16 v[16:19], v[152:155], v[182:185], v[20:23]
	v_mfma_f32_16x16x32_bf16 v[64:67], v[178:181], v[196:199], v[16:19]
	v_mfma_f32_16x16x32_bf16 v[16:19], v[128:131], v[200:203], v[32:35]
	v_mfma_f32_16x16x32_bf16 v[52:55], v[140:143], v[204:207], v[16:19]
	v_mfma_f32_16x16x32_bf16 v[16:19], v[152:155], v[200:203], v[36:39]
	v_mfma_f32_16x16x32_bf16 v[48:51], v[178:181], v[204:207], v[16:19]
	v_mfma_f32_16x16x32_bf16 v[16:19], v[128:131], v[208:211], v[28:31]
	v_mfma_f32_16x16x32_bf16 v[28:31], v[140:143], v[212:215], v[16:19]
	v_mfma_f32_16x16x32_bf16 v[16:19], v[152:155], v[208:211], v[24:27]
	v_mfma_f32_16x16x32_bf16 v[4:7], v[128:131], v[234:237], v[4:7]
	v_mfma_f32_16x16x32_bf16 v[0:3], v[152:155], v[234:237], v[0:3]
	v_mfma_f32_16x16x32_bf16 v[24:27], v[178:181], v[212:215], v[16:19]
	v_mfma_f32_16x16x32_bf16 v[4:7], v[140:143], v[238:241], v[4:7]
	v_mfma_f32_16x16x32_bf16 v[0:3], v[178:181], v[238:241], v[0:3]
	s_barrier
	s_add_i32 s58, s58, 2
	s_add_u32 s28, s28, 0x100
	s_addc_u32 s29, s29, 0
	s_add_u32 s56, s56, 0x100
	s_addc_u32 s57, s57, 0
	s_cmp_gt_u32 s58, 13
	s_cbranch_scc0 .LBB0_1024
	s_and_b64 vcc, exec, s[10:11]
	s_cbranch_vccz .LBB0_1027
	s_barrier

.LBB0_1097:
	s_add_u32 s28, s26, 0xfff80080
	s_addc_u32 s29, s27, -1
	s_add_i32 s55, 0, 0x10000
	s_cmp_eq_u32 s54, 28
	s_cselect_b32 s31, s13, s29
	s_cselect_b32 s30, s50, s28
	s_cselect_b32 s29, s11, s53
	s_cselect_b32 s28, s51, s52
	s_add_i32 s58, 0, 0x14000
	v_add_u32_e32 v36, s55, v157
	v_add_u32_e32 v154, s58, v157
	ds_read_b128 v[16:19], v36
	ds_read_b128 v[20:23], v36 offset:1024
	ds_read_b128 v[32:35], v36 offset:2048
	ds_read_b128 v[36:39], v36 offset:3072
	ds_read_b128 v[172:175], v154
	ds_read_b128 v[176:179], v154 offset:1024
	ds_read_b128 v[180:183], v154 offset:2048
	ds_read_b128 v[184:187], v154 offset:3072
	v_lshl_add_u64 v[154:155], s[26:27], 0, v[150:151]
	s_add_i32 m0, s43, 0xc000
	ds_read_b128 v[196:199], v159
	ds_read_b128 v[200:203], v159 offset:1024
	ds_read_b128 v[204:207], v159 offset:2048
	ds_read_b128 v[208:211], v159 offset:3072
	ds_read_b128 v[212:215], v159 offset:4096
	ds_read_b128 v[234:237], v159 offset:5120
	ds_read_b128 v[238:241], v159 offset:6144
	ds_read_b128 v[242:245], v159 offset:7168
	global_load_lds_dwordx4 v[154:155], off
	v_lshl_add_u64 v[154:155], s[26:27], 0, v[152:153]
	s_add_i32 m0, s43, 0xe000
	s_nop 0
	global_load_lds_dwordx4 v[154:155], off
	s_waitcnt vmcnt(8)
	s_waitcnt lgkmcnt(0)
	s_barrier
	s_waitcnt lgkmcnt(0)
	v_mfma_f32_16x16x32_bf16 v[140:143], v[16:19], v[196:199], v[140:143]
	v_mfma_f32_16x16x32_bf16 v[136:139], v[32:35], v[196:199], v[136:139]
	v_mfma_f32_16x16x32_bf16 v[124:127], v[16:19], v[204:207], v[124:127]
	v_mfma_f32_16x16x32_bf16 v[120:123], v[32:35], v[204:207], v[120:123]
	v_mfma_f32_16x16x32_bf16 v[108:111], v[16:19], v[212:215], v[108:111]
	v_mfma_f32_16x16x32_bf16 v[104:107], v[32:35], v[212:215], v[104:107]
	v_mfma_f32_16x16x32_bf16 v[92:95], v[16:19], v[238:241], v[92:95]
	v_mfma_f32_16x16x32_bf16 v[88:91], v[32:35], v[238:241], v[88:91]
	v_mfma_f32_16x16x32_bf16 v[140:143], v[20:23], v[200:203], v[140:143]
	v_mfma_f32_16x16x32_bf16 v[136:139], v[36:39], v[200:203], v[136:139]
	v_mfma_f32_16x16x32_bf16 v[124:127], v[20:23], v[208:211], v[124:127]
	v_mfma_f32_16x16x32_bf16 v[120:123], v[36:39], v[208:211], v[120:123]
	v_mfma_f32_16x16x32_bf16 v[108:111], v[20:23], v[234:237], v[108:111]
	v_mfma_f32_16x16x32_bf16 v[104:107], v[36:39], v[234:237], v[104:107]
	v_mfma_f32_16x16x32_bf16 v[92:95], v[20:23], v[242:245], v[92:95]
	v_mfma_f32_16x16x32_bf16 v[88:91], v[36:39], v[242:245], v[88:91]
	v_mfma_f32_16x16x32_bf16 v[132:135], v[172:175], v[196:199], v[132:135]
	v_mfma_f32_16x16x32_bf16 v[128:131], v[180:183], v[196:199], v[128:131]
	v_mfma_f32_16x16x32_bf16 v[116:119], v[172:175], v[204:207], v[116:119]
	v_mfma_f32_16x16x32_bf16 v[112:115], v[180:183], v[204:207], v[112:115]
	v_mfma_f32_16x16x32_bf16 v[100:103], v[172:175], v[212:215], v[100:103]
	v_mfma_f32_16x16x32_bf16 v[96:99], v[180:183], v[212:215], v[96:99]
	v_mfma_f32_16x16x32_bf16 v[84:87], v[172:175], v[238:241], v[84:87]
	v_mfma_f32_16x16x32_bf16 v[80:83], v[180:183], v[238:241], v[80:83]
	v_mfma_f32_16x16x32_bf16 v[132:135], v[176:179], v[200:203], v[132:135]
	v_mfma_f32_16x16x32_bf16 v[128:131], v[184:187], v[200:203], v[128:131]
	v_mfma_f32_16x16x32_bf16 v[116:119], v[176:179], v[208:211], v[116:119]
	v_mfma_f32_16x16x32_bf16 v[112:115], v[184:187], v[208:211], v[112:115]
	v_mfma_f32_16x16x32_bf16 v[100:103], v[176:179], v[234:237], v[100:103]
	v_mfma_f32_16x16x32_bf16 v[96:99], v[184:187], v[234:237], v[96:99]
	v_mfma_f32_16x16x32_bf16 v[84:87], v[176:179], v[242:245], v[84:87]
	v_mfma_f32_16x16x32_bf16 v[80:83], v[184:187], v[242:245], v[80:83]
	s_barrier
	s_add_i32 s55, s55, s37
	v_lshl_add_u64 v[154:155], s[28:29], 0, v[160:161]
	s_mov_b32 m0, s55
	ds_read_b128 v[196:199], v159 offset:16384
	ds_read_b128 v[200:203], v159 offset:17408
	ds_read_b128 v[204:207], v159 offset:18432
	ds_read_b128 v[208:211], v159 offset:19456
	ds_read_b128 v[212:215], v159 offset:20480
	ds_read_b128 v[234:237], v159 offset:21504
	ds_read_b128 v[238:241], v159 offset:22528
	ds_read_b128 v[242:245], v159 offset:23552
	global_load_lds_dwordx4 v[154:155], off
	s_add_i32 m0, s55, 0x2000
	s_add_u32 s56, s28, 0x80000
	v_lshl_add_u64 v[188:189], s[28:29], 0, v[144:145]
	s_addc_u32 s57, s29, 0
	s_add_i32 s55, s58, s37
	global_load_lds_dwordx4 v[188:189], off
	v_lshl_add_u64 v[216:217], s[56:57], 0, v[160:161]
	s_mov_b32 m0, s55
	v_lshl_add_u64 v[246:247], s[30:31], 0, v[146:147]
	global_load_lds_dwordx4 v[216:217], off
	v_lshl_add_u64 v[216:217], s[56:57], 0, v[144:145]
	s_add_i32 m0, s55, 0x2000
	s_nop 0
	global_load_lds_dwordx4 v[216:217], off
	v_lshl_add_u64 v[216:217], s[30:31], 0, v[148:149]
	s_mov_b32 m0, s43
	s_nop 0
	global_load_lds_dwordx4 v[216:217], off
	s_mov_b32 m0, s44
	s_nop 0
	global_load_lds_dwordx4 v[246:247], off
	s_waitcnt vmcnt(8)
	s_waitcnt lgkmcnt(0)
	s_barrier
	s_waitcnt lgkmcnt(0)
	v_mfma_f32_16x16x32_bf16 v[76:79], v[16:19], v[196:199], v[76:79]
	v_mfma_f32_16x16x32_bf16 v[72:75], v[32:35], v[196:199], v[72:75]
	v_mfma_f32_16x16x32_bf16 v[60:63], v[16:19], v[204:207], v[60:63]
	v_mfma_f32_16x16x32_bf16 v[56:59], v[32:35], v[204:207], v[56:59]
	v_mfma_f32_16x16x32_bf16 v[44:47], v[16:19], v[212:215], v[44:47]
	v_mfma_f32_16x16x32_bf16 v[40:43], v[32:35], v[212:215], v[40:43]
	v_mfma_f32_16x16x32_bf16 v[12:15], v[16:19], v[238:241], v[12:15]
	v_mfma_f32_16x16x32_bf16 v[8:11], v[32:35], v[238:241], v[8:11]
	v_mfma_f32_16x16x32_bf16 v[76:79], v[20:23], v[200:203], v[76:79]
	v_mfma_f32_16x16x32_bf16 v[72:75], v[36:39], v[200:203], v[72:75]
	v_mfma_f32_16x16x32_bf16 v[60:63], v[20:23], v[208:211], v[60:63]
	v_mfma_f32_16x16x32_bf16 v[56:59], v[36:39], v[208:211], v[56:59]
	v_mfma_f32_16x16x32_bf16 v[44:47], v[20:23], v[234:237], v[44:47]
	v_mfma_f32_16x16x32_bf16 v[40:43], v[36:39], v[234:237], v[40:43]
	v_mfma_f32_16x16x32_bf16 v[12:15], v[20:23], v[242:245], v[12:15]
	v_mfma_f32_16x16x32_bf16 v[8:11], v[36:39], v[242:245], v[8:11]
	v_mfma_f32_16x16x32_bf16 v[28:31], v[172:175], v[212:215], v[28:31]
	v_mfma_f32_16x16x32_bf16 v[24:27], v[180:183], v[212:215], v[24:27]
	v_mfma_f32_16x16x32_bf16 v[4:7], v[172:175], v[238:241], v[4:7]
	v_mfma_f32_16x16x32_bf16 v[0:3], v[180:183], v[238:241], v[0:3]
	v_mfma_f32_16x16x32_bf16 v[16:19], v[172:175], v[196:199], v[68:71]
	v_mfma_f32_16x16x32_bf16 v[20:23], v[180:183], v[196:199], v[64:67]
	v_mfma_f32_16x16x32_bf16 v[32:35], v[172:175], v[204:207], v[52:55]
	v_mfma_f32_16x16x32_bf16 v[36:39], v[180:183], v[204:207], v[48:51]
	v_mfma_f32_16x16x32_bf16 v[28:31], v[176:179], v[234:237], v[28:31]
	v_mfma_f32_16x16x32_bf16 v[24:27], v[184:187], v[234:237], v[24:27]
	v_mfma_f32_16x16x32_bf16 v[4:7], v[176:179], v[242:245], v[4:7]
	v_mfma_f32_16x16x32_bf16 v[0:3], v[184:187], v[242:245], v[0:3]
	v_mfma_f32_16x16x32_bf16 v[16:19], v[176:179], v[200:203], v[16:19]
	v_mfma_f32_16x16x32_bf16 v[20:23], v[184:187], v[200:203], v[20:23]
	v_mfma_f32_16x16x32_bf16 v[32:35], v[176:179], v[208:211], v[32:35]
	v_mfma_f32_16x16x32_bf16 v[36:39], v[184:187], v[208:211], v[36:39]
	s_barrier
	s_add_i32 s55, 0, 0x18000
	s_add_i32 s56, 0, 0x1c000
	v_add_u32_e32 v68, s55, v157
	v_add_u32_e32 v162, s56, v157
	ds_read_b128 v[48:51], v68
	ds_read_b128 v[52:55], v68 offset:1024
	ds_read_b128 v[64:67], v68 offset:2048
	ds_read_b128 v[68:71], v68 offset:3072
	ds_read_b128 v[172:175], v162
	ds_read_b128 v[176:179], v162 offset:1024
	ds_read_b128 v[180:183], v162 offset:2048
	ds_read_b128 v[184:187], v162 offset:3072
	s_add_u32 s30, s30, 0x80000
	s_addc_u32 s31, s31, 0
	s_mov_b32 m0, s45
	v_lshl_add_u64 v[248:249], s[30:31], 0, v[148:149]
	ds_read_b128 v[196:199], v159 offset:32768
	ds_read_b128 v[200:203], v159 offset:33792
	ds_read_b128 v[204:207], v159 offset:34816
	ds_read_b128 v[208:211], v159 offset:35840
	ds_read_b128 v[212:215], v159 offset:36864
	ds_read_b128 v[234:237], v159 offset:37888
	ds_read_b128 v[238:241], v159 offset:38912
	ds_read_b128 v[242:245], v159 offset:39936
	global_load_lds_dwordx4 v[248:249], off
	v_lshl_add_u64 v[248:249], s[30:31], 0, v[146:147]
	s_mov_b32 m0, s46
	s_nop 0
	global_load_lds_dwordx4 v[248:249], off
	s_waitcnt vmcnt(8)
	s_waitcnt lgkmcnt(0)
	s_barrier
	s_waitcnt lgkmcnt(0)
	v_mfma_f32_16x16x32_bf16 v[140:143], v[48:51], v[196:199], v[140:143]
	v_mfma_f32_16x16x32_bf16 v[136:139], v[64:67], v[196:199], v[136:139]
	v_mfma_f32_16x16x32_bf16 v[124:127], v[48:51], v[204:207], v[124:127]
	v_mfma_f32_16x16x32_bf16 v[120:123], v[64:67], v[204:207], v[120:123]
	v_mfma_f32_16x16x32_bf16 v[108:111], v[48:51], v[212:215], v[108:111]
	v_mfma_f32_16x16x32_bf16 v[104:107], v[64:67], v[212:215], v[104:107]
	v_mfma_f32_16x16x32_bf16 v[92:95], v[48:51], v[238:241], v[92:95]
	v_mfma_f32_16x16x32_bf16 v[88:91], v[64:67], v[238:241], v[88:91]
	v_mfma_f32_16x16x32_bf16 v[140:143], v[52:55], v[200:203], v[140:143]
	v_mfma_f32_16x16x32_bf16 v[136:139], v[68:71], v[200:203], v[136:139]
	v_mfma_f32_16x16x32_bf16 v[124:127], v[52:55], v[208:211], v[124:127]
	v_mfma_f32_16x16x32_bf16 v[120:123], v[68:71], v[208:211], v[120:123]
	v_mfma_f32_16x16x32_bf16 v[108:111], v[52:55], v[234:237], v[108:111]
	v_mfma_f32_16x16x32_bf16 v[104:107], v[68:71], v[234:237], v[104:107]
	v_mfma_f32_16x16x32_bf16 v[92:95], v[52:55], v[242:245], v[92:95]
	v_mfma_f32_16x16x32_bf16 v[88:91], v[68:71], v[242:245], v[88:91]
	v_mfma_f32_16x16x32_bf16 v[132:135], v[172:175], v[196:199], v[132:135]
	v_mfma_f32_16x16x32_bf16 v[128:131], v[180:183], v[196:199], v[128:131]
	v_mfma_f32_16x16x32_bf16 v[116:119], v[172:175], v[204:207], v[116:119]
	v_mfma_f32_16x16x32_bf16 v[112:115], v[180:183], v[204:207], v[112:115]
	v_mfma_f32_16x16x32_bf16 v[100:103], v[172:175], v[212:215], v[100:103]
	v_mfma_f32_16x16x32_bf16 v[96:99], v[180:183], v[212:215], v[96:99]
	v_mfma_f32_16x16x32_bf16 v[84:87], v[172:175], v[238:241], v[84:87]
	v_mfma_f32_16x16x32_bf16 v[80:83], v[180:183], v[238:241], v[80:83]
	v_mfma_f32_16x16x32_bf16 v[132:135], v[176:179], v[200:203], v[132:135]
	v_mfma_f32_16x16x32_bf16 v[128:131], v[184:187], v[200:203], v[128:131]
	v_mfma_f32_16x16x32_bf16 v[116:119], v[176:179], v[208:211], v[116:119]
	v_mfma_f32_16x16x32_bf16 v[112:115], v[184:187], v[208:211], v[112:115]
	v_mfma_f32_16x16x32_bf16 v[100:103], v[176:179], v[234:237], v[100:103]
	v_mfma_f32_16x16x32_bf16 v[96:99], v[184:187], v[234:237], v[96:99]
	v_mfma_f32_16x16x32_bf16 v[84:87], v[176:179], v[242:245], v[84:87]
	v_mfma_f32_16x16x32_bf16 v[80:83], v[184:187], v[242:245], v[80:83]
	s_barrier
	s_add_i32 s30, s55, s37
	v_lshl_add_u64 v[154:155], v[154:155], 0, s[20:21]
	s_mov_b32 m0, s30
	ds_read_b128 v[196:199], v159 offset:49152
	ds_read_b128 v[200:203], v159 offset:50176
	ds_read_b128 v[204:207], v159 offset:51200
	ds_read_b128 v[208:211], v159 offset:52224
	ds_read_b128 v[212:215], v159 offset:53248
	ds_read_b128 v[234:237], v159 offset:54272
	ds_read_b128 v[238:241], v159 offset:55296
	ds_read_b128 v[242:245], v159 offset:56320
	global_load_lds_dwordx4 v[154:155], off
	s_add_i32 m0, s30, 0x2000
	s_add_u32 s28, s28, 0x80080
	v_lshl_add_u64 v[154:155], v[188:189], 0, s[20:21]
	s_addc_u32 s29, s29, 0
	s_add_i32 s30, s56, s37
	global_load_lds_dwordx4 v[154:155], off
	v_lshl_add_u64 v[154:155], s[28:29], 0, v[160:161]
	s_mov_b32 m0, s30
	s_nop 0
	global_load_lds_dwordx4 v[154:155], off
	v_lshl_add_u64 v[154:155], s[28:29], 0, v[144:145]
	s_add_i32 m0, s30, 0x2000
	s_nop 0
	global_load_lds_dwordx4 v[154:155], off
	v_lshl_add_u64 v[154:155], v[216:217], 0, s[20:21]
	s_mov_b32 m0, s47
	s_nop 0
	global_load_lds_dwordx4 v[154:155], off
	v_lshl_add_u64 v[154:155], v[246:247], 0, s[20:21]
	s_mov_b32 m0, s48
	s_nop 0
	global_load_lds_dwordx4 v[154:155], off
	s_waitcnt vmcnt(8)
	s_waitcnt lgkmcnt(0)
	s_barrier
	s_waitcnt lgkmcnt(0)
	v_mfma_f32_16x16x32_bf16 v[76:79], v[48:51], v[196:199], v[76:79]
	v_mfma_f32_16x16x32_bf16 v[72:75], v[64:67], v[196:199], v[72:75]
	v_mfma_f32_16x16x32_bf16 v[60:63], v[48:51], v[204:207], v[60:63]
	v_mfma_f32_16x16x32_bf16 v[56:59], v[64:67], v[204:207], v[56:59]
	v_mfma_f32_16x16x32_bf16 v[44:47], v[48:51], v[212:215], v[44:47]
	v_mfma_f32_16x16x32_bf16 v[40:43], v[64:67], v[212:215], v[40:43]
	v_mfma_f32_16x16x32_bf16 v[12:15], v[48:51], v[238:241], v[12:15]
	v_mfma_f32_16x16x32_bf16 v[8:11], v[64:67], v[238:241], v[8:11]
	v_mfma_f32_16x16x32_bf16 v[76:79], v[52:55], v[200:203], v[76:79]
	v_mfma_f32_16x16x32_bf16 v[72:75], v[68:71], v[200:203], v[72:75]
	v_mfma_f32_16x16x32_bf16 v[60:63], v[52:55], v[208:211], v[60:63]
	v_mfma_f32_16x16x32_bf16 v[56:59], v[68:71], v[208:211], v[56:59]
	v_mfma_f32_16x16x32_bf16 v[44:47], v[52:55], v[234:237], v[44:47]
	v_mfma_f32_16x16x32_bf16 v[40:43], v[68:71], v[234:237], v[40:43]
	v_mfma_f32_16x16x32_bf16 v[12:15], v[52:55], v[242:245], v[12:15]
	v_mfma_f32_16x16x32_bf16 v[8:11], v[68:71], v[242:245], v[8:11]
	v_mfma_f32_16x16x32_bf16 v[16:19], v[172:175], v[196:199], v[16:19]
	v_mfma_f32_16x16x32_bf16 v[68:71], v[176:179], v[200:203], v[16:19]
	v_mfma_f32_16x16x32_bf16 v[16:19], v[180:183], v[196:199], v[20:23]
	v_mfma_f32_16x16x32_bf16 v[64:67], v[184:187], v[200:203], v[16:19]
	v_mfma_f32_16x16x32_bf16 v[16:19], v[172:175], v[204:207], v[32:35]
	v_mfma_f32_16x16x32_bf16 v[52:55], v[176:179], v[208:211], v[16:19]
	v_mfma_f32_16x16x32_bf16 v[16:19], v[180:183], v[204:207], v[36:39]
	v_mfma_f32_16x16x32_bf16 v[48:51], v[184:187], v[208:211], v[16:19]
	v_mfma_f32_16x16x32_bf16 v[16:19], v[172:175], v[212:215], v[28:31]
	v_mfma_f32_16x16x32_bf16 v[28:31], v[176:179], v[234:237], v[16:19]
	v_mfma_f32_16x16x32_bf16 v[16:19], v[180:183], v[212:215], v[24:27]
	v_mfma_f32_16x16x32_bf16 v[4:7], v[172:175], v[238:241], v[4:7]
	v_mfma_f32_16x16x32_bf16 v[0:3], v[180:183], v[238:241], v[0:3]
	v_mfma_f32_16x16x32_bf16 v[24:27], v[184:187], v[234:237], v[16:19]
	v_mfma_f32_16x16x32_bf16 v[4:7], v[176:179], v[242:245], v[4:7]
	v_mfma_f32_16x16x32_bf16 v[0:3], v[184:187], v[242:245], v[0:3]
	s_barrier
	s_add_i32 s54, s54, 2
	s_add_u32 s26, s26, 0x100
	s_addc_u32 s27, s27, 0
	s_add_u32 s52, s52, 0x100
	s_addc_u32 s53, s53, 0
	s_cmp_gt_u32 s54, 29
	s_cbranch_scc0 .LBB0_1097
	s_and_b64 vcc, exec, s[8:9]
	s_cbranch_vccz .LBB0_1100
	s_barrier

.LBB0_1176:
	s_add_u32 s34, s4, 0xfffc0080
	s_addc_u32 s35, s5, -1
	s_add_i32 s55, 0, 0x10000
	s_cmp_eq_u32 s31, 12
	s_cselect_b32 s37, s19, s35
	s_cselect_b32 s36, s18, s34
	s_cselect_b32 s35, s13, s29
	s_cselect_b32 s34, s15, s17
	s_add_i32 s58, 0, 0x14000
	v_add_u32_e32 v88, s55, v192
	v_add_u32_e32 v156, s58, v192
	ds_read_b128 v[64:67], v88
	ds_read_b128 v[68:71], v88 offset:1024
	ds_read_b128 v[80:83], v88 offset:2048
	ds_read_b128 v[88:91], v88 offset:3072
	ds_read_b128 v[144:147], v156
	ds_read_b128 v[148:151], v156 offset:1024
	ds_read_b128 v[152:155], v156 offset:2048
	ds_read_b128 v[156:159], v156 offset:3072
	v_lshl_add_u64 v[214:215], s[4:5], 0, v[178:179]
	s_add_i32 m0, s45, 0xc000
	ds_read_b128 v[182:185], v197
	ds_read_b128 v[186:189], v197 offset:1024
	ds_read_b128 v[198:201], v197 offset:2048
	ds_read_b128 v[202:205], v197 offset:3072
	ds_read_b128 v[206:209], v197 offset:4096
	ds_read_b128 v[210:213], v197 offset:5120
	ds_read_b128 v[234:237], v197 offset:6144
	ds_read_b128 v[238:241], v197 offset:7168
	global_load_lds_dwordx4 v[214:215], off
	v_lshl_add_u64 v[214:215], s[4:5], 0, v[180:181]
	s_add_i32 m0, s45, 0xe000
	s_nop 0
	global_load_lds_dwordx4 v[214:215], off
	s_waitcnt vmcnt(8)
	s_waitcnt lgkmcnt(0)
	s_barrier
	s_waitcnt lgkmcnt(0)
	v_mfma_f32_16x16x32_bf16 v[140:143], v[64:67], v[182:185], v[140:143]
	v_mfma_f32_16x16x32_bf16 v[136:139], v[80:83], v[182:185], v[136:139]
	v_mfma_f32_16x16x32_bf16 v[124:127], v[64:67], v[198:201], v[124:127]
	v_mfma_f32_16x16x32_bf16 v[120:123], v[80:83], v[198:201], v[120:123]
	v_mfma_f32_16x16x32_bf16 v[108:111], v[64:67], v[206:209], v[108:111]
	v_mfma_f32_16x16x32_bf16 v[104:107], v[80:83], v[206:209], v[104:107]
	v_mfma_f32_16x16x32_bf16 v[92:95], v[64:67], v[234:237], v[92:95]
	v_mfma_f32_16x16x32_bf16 v[84:87], v[80:83], v[234:237], v[84:87]
	v_mfma_f32_16x16x32_bf16 v[140:143], v[68:71], v[186:189], v[140:143]
	v_mfma_f32_16x16x32_bf16 v[136:139], v[88:91], v[186:189], v[136:139]
	v_mfma_f32_16x16x32_bf16 v[124:127], v[68:71], v[202:205], v[124:127]
	v_mfma_f32_16x16x32_bf16 v[120:123], v[88:91], v[202:205], v[120:123]
	v_mfma_f32_16x16x32_bf16 v[108:111], v[68:71], v[210:213], v[108:111]
	v_mfma_f32_16x16x32_bf16 v[104:107], v[88:91], v[210:213], v[104:107]
	v_mfma_f32_16x16x32_bf16 v[92:95], v[68:71], v[238:241], v[92:95]
	v_mfma_f32_16x16x32_bf16 v[84:87], v[88:91], v[238:241], v[84:87]
	v_mfma_f32_16x16x32_bf16 v[132:135], v[144:147], v[182:185], v[132:135]
	v_mfma_f32_16x16x32_bf16 v[128:131], v[152:155], v[182:185], v[128:131]
	v_mfma_f32_16x16x32_bf16 v[116:119], v[144:147], v[198:201], v[116:119]
	v_mfma_f32_16x16x32_bf16 v[112:115], v[152:155], v[198:201], v[112:115]
	v_mfma_f32_16x16x32_bf16 v[100:103], v[144:147], v[206:209], v[100:103]
	v_mfma_f32_16x16x32_bf16 v[96:99], v[152:155], v[206:209], v[96:99]
	v_mfma_f32_16x16x32_bf16 v[76:79], v[144:147], v[234:237], v[76:79]
	v_mfma_f32_16x16x32_bf16 v[72:75], v[152:155], v[234:237], v[72:75]
	v_mfma_f32_16x16x32_bf16 v[132:135], v[148:151], v[186:189], v[132:135]
	v_mfma_f32_16x16x32_bf16 v[128:131], v[156:159], v[186:189], v[128:131]
	v_mfma_f32_16x16x32_bf16 v[116:119], v[148:151], v[202:205], v[116:119]
	v_mfma_f32_16x16x32_bf16 v[112:115], v[156:159], v[202:205], v[112:115]
	v_mfma_f32_16x16x32_bf16 v[100:103], v[148:151], v[210:213], v[100:103]
	v_mfma_f32_16x16x32_bf16 v[96:99], v[156:159], v[210:213], v[96:99]
	v_mfma_f32_16x16x32_bf16 v[76:79], v[148:151], v[238:241], v[76:79]
	v_mfma_f32_16x16x32_bf16 v[72:75], v[156:159], v[238:241], v[72:75]
	s_barrier
	s_add_i32 s55, s55, s44
	v_lshl_add_u64 v[214:215], s[34:35], 0, v[160:161]
	s_mov_b32 m0, s55
	ds_read_b128 v[182:185], v197 offset:16384
	ds_read_b128 v[186:189], v197 offset:17408
	ds_read_b128 v[198:201], v197 offset:18432
	ds_read_b128 v[202:205], v197 offset:19456
	ds_read_b128 v[206:209], v197 offset:20480
	ds_read_b128 v[210:213], v197 offset:21504
	ds_read_b128 v[234:237], v197 offset:22528
	ds_read_b128 v[238:241], v197 offset:23552
	global_load_lds_dwordx4 v[214:215], off
	s_add_i32 m0, s55, 0x2000
	s_add_u32 s56, s34, 0x40000
	v_lshl_add_u64 v[216:217], s[34:35], 0, v[176:177]
	s_addc_u32 s57, s35, 0
	s_add_i32 s55, s58, s44
	global_load_lds_dwordx4 v[216:217], off
	v_lshl_add_u64 v[242:243], s[56:57], 0, v[160:161]
	s_mov_b32 m0, s55
	v_lshl_add_u64 v[244:245], s[36:37], 0, v[174:175]
	global_load_lds_dwordx4 v[242:243], off
	v_lshl_add_u64 v[242:243], s[56:57], 0, v[176:177]
	s_add_i32 m0, s55, 0x2000
	s_nop 0
	global_load_lds_dwordx4 v[242:243], off
	v_lshl_add_u64 v[242:243], s[36:37], 0, v[172:173]
	s_mov_b32 m0, s45
	s_nop 0
	global_load_lds_dwordx4 v[242:243], off
	s_mov_b32 m0, s46
	s_nop 0
	global_load_lds_dwordx4 v[244:245], off
	s_waitcnt vmcnt(8)
	s_waitcnt lgkmcnt(0)
	s_barrier
	s_waitcnt lgkmcnt(0)
	v_mfma_f32_16x16x32_bf16 v[60:63], v[64:67], v[182:185], v[60:63]
	v_mfma_f32_16x16x32_bf16 v[56:59], v[80:83], v[182:185], v[56:59]
	v_mfma_f32_16x16x32_bf16 v[44:47], v[64:67], v[198:201], v[44:47]
	v_mfma_f32_16x16x32_bf16 v[40:43], v[80:83], v[198:201], v[40:43]
	v_mfma_f32_16x16x32_bf16 v[28:31], v[64:67], v[206:209], v[28:31]
	v_mfma_f32_16x16x32_bf16 v[24:27], v[80:83], v[206:209], v[24:27]
	v_mfma_f32_16x16x32_bf16 v[12:15], v[64:67], v[234:237], v[12:15]
	v_mfma_f32_16x16x32_bf16 v[8:11], v[80:83], v[234:237], v[8:11]
	v_mfma_f32_16x16x32_bf16 v[60:63], v[68:71], v[186:189], v[60:63]
	v_mfma_f32_16x16x32_bf16 v[56:59], v[88:91], v[186:189], v[56:59]
	v_mfma_f32_16x16x32_bf16 v[44:47], v[68:71], v[202:205], v[44:47]
	v_mfma_f32_16x16x32_bf16 v[40:43], v[88:91], v[202:205], v[40:43]
	v_mfma_f32_16x16x32_bf16 v[28:31], v[68:71], v[210:213], v[28:31]
	v_mfma_f32_16x16x32_bf16 v[24:27], v[88:91], v[210:213], v[24:27]
	v_mfma_f32_16x16x32_bf16 v[12:15], v[68:71], v[238:241], v[12:15]
	v_mfma_f32_16x16x32_bf16 v[8:11], v[88:91], v[238:241], v[8:11]
	v_mfma_f32_16x16x32_bf16 v[52:55], v[144:147], v[182:185], v[52:55]
	v_mfma_f32_16x16x32_bf16 v[48:51], v[152:155], v[182:185], v[48:51]
	v_mfma_f32_16x16x32_bf16 v[36:39], v[144:147], v[198:201], v[36:39]
	v_mfma_f32_16x16x32_bf16 v[32:35], v[152:155], v[198:201], v[32:35]
	v_mfma_f32_16x16x32_bf16 v[20:23], v[144:147], v[206:209], v[20:23]
	v_mfma_f32_16x16x32_bf16 v[16:19], v[152:155], v[206:209], v[16:19]
	v_mfma_f32_16x16x32_bf16 v[4:7], v[144:147], v[234:237], v[4:7]
	v_mfma_f32_16x16x32_bf16 v[0:3], v[152:155], v[234:237], v[0:3]
	v_mfma_f32_16x16x32_bf16 v[52:55], v[148:151], v[186:189], v[52:55]
	v_mfma_f32_16x16x32_bf16 v[48:51], v[156:159], v[186:189], v[48:51]
	v_mfma_f32_16x16x32_bf16 v[36:39], v[148:151], v[202:205], v[36:39]
	v_mfma_f32_16x16x32_bf16 v[32:35], v[156:159], v[202:205], v[32:35]
	v_mfma_f32_16x16x32_bf16 v[20:23], v[148:151], v[210:213], v[20:23]
	v_mfma_f32_16x16x32_bf16 v[16:19], v[156:159], v[210:213], v[16:19]
	v_mfma_f32_16x16x32_bf16 v[4:7], v[148:151], v[238:241], v[4:7]
	v_mfma_f32_16x16x32_bf16 v[0:3], v[156:159], v[238:241], v[0:3]
	s_barrier
	s_add_i32 s55, 0, 0x18000
	s_add_i32 s56, 0, 0x1c000
	v_add_u32_e32 v88, s55, v192
	v_add_u32_e32 v156, s56, v192
	ds_read_b128 v[64:67], v88
	ds_read_b128 v[68:71], v88 offset:1024
	ds_read_b128 v[80:83], v88 offset:2048
	ds_read_b128 v[88:91], v88 offset:3072
	ds_read_b128 v[144:147], v156
	ds_read_b128 v[148:151], v156 offset:1024
	ds_read_b128 v[152:155], v156 offset:2048
	ds_read_b128 v[156:159], v156 offset:3072
	s_add_u32 s36, s36, 0x40000
	s_addc_u32 s37, s37, 0
	s_mov_b32 m0, s47
	v_lshl_add_u64 v[246:247], s[36:37], 0, v[172:173]
	ds_read_b128 v[182:185], v197 offset:32768
	ds_read_b128 v[186:189], v197 offset:33792
	ds_read_b128 v[198:201], v197 offset:34816
	ds_read_b128 v[202:205], v197 offset:35840
	ds_read_b128 v[206:209], v197 offset:36864
	ds_read_b128 v[210:213], v197 offset:37888
	ds_read_b128 v[234:237], v197 offset:38912
	ds_read_b128 v[238:241], v197 offset:39936
	global_load_lds_dwordx4 v[246:247], off
	v_lshl_add_u64 v[246:247], s[36:37], 0, v[174:175]
	s_mov_b32 m0, s48
	s_nop 0
	global_load_lds_dwordx4 v[246:247], off
	s_waitcnt vmcnt(8)
	s_waitcnt lgkmcnt(0)
	s_barrier
	s_waitcnt lgkmcnt(0)
	v_mfma_f32_16x16x32_bf16 v[140:143], v[64:67], v[182:185], v[140:143]
	v_mfma_f32_16x16x32_bf16 v[136:139], v[80:83], v[182:185], v[136:139]
	v_mfma_f32_16x16x32_bf16 v[124:127], v[64:67], v[198:201], v[124:127]
	v_mfma_f32_16x16x32_bf16 v[120:123], v[80:83], v[198:201], v[120:123]
	v_mfma_f32_16x16x32_bf16 v[108:111], v[64:67], v[206:209], v[108:111]
	v_mfma_f32_16x16x32_bf16 v[104:107], v[80:83], v[206:209], v[104:107]
	v_mfma_f32_16x16x32_bf16 v[92:95], v[64:67], v[234:237], v[92:95]
	v_mfma_f32_16x16x32_bf16 v[84:87], v[80:83], v[234:237], v[84:87]
	v_mfma_f32_16x16x32_bf16 v[140:143], v[68:71], v[186:189], v[140:143]
	v_mfma_f32_16x16x32_bf16 v[136:139], v[88:91], v[186:189], v[136:139]
	v_mfma_f32_16x16x32_bf16 v[124:127], v[68:71], v[202:205], v[124:127]
	v_mfma_f32_16x16x32_bf16 v[120:123], v[88:91], v[202:205], v[120:123]
	v_mfma_f32_16x16x32_bf16 v[108:111], v[68:71], v[210:213], v[108:111]
	v_mfma_f32_16x16x32_bf16 v[104:107], v[88:91], v[210:213], v[104:107]
	v_mfma_f32_16x16x32_bf16 v[92:95], v[68:71], v[238:241], v[92:95]
	v_mfma_f32_16x16x32_bf16 v[84:87], v[88:91], v[238:241], v[84:87]
	v_mfma_f32_16x16x32_bf16 v[132:135], v[144:147], v[182:185], v[132:135]
	v_mfma_f32_16x16x32_bf16 v[128:131], v[152:155], v[182:185], v[128:131]
	v_mfma_f32_16x16x32_bf16 v[116:119], v[144:147], v[198:201], v[116:119]
	v_mfma_f32_16x16x32_bf16 v[112:115], v[152:155], v[198:201], v[112:115]
	v_mfma_f32_16x16x32_bf16 v[100:103], v[144:147], v[206:209], v[100:103]
	v_mfma_f32_16x16x32_bf16 v[96:99], v[152:155], v[206:209], v[96:99]
	v_mfma_f32_16x16x32_bf16 v[76:79], v[144:147], v[234:237], v[76:79]
	v_mfma_f32_16x16x32_bf16 v[72:75], v[152:155], v[234:237], v[72:75]
	v_mfma_f32_16x16x32_bf16 v[132:135], v[148:151], v[186:189], v[132:135]
	v_mfma_f32_16x16x32_bf16 v[128:131], v[156:159], v[186:189], v[128:131]
	v_mfma_f32_16x16x32_bf16 v[116:119], v[148:151], v[202:205], v[116:119]
	v_mfma_f32_16x16x32_bf16 v[112:115], v[156:159], v[202:205], v[112:115]
	v_mfma_f32_16x16x32_bf16 v[100:103], v[148:151], v[210:213], v[100:103]
	v_mfma_f32_16x16x32_bf16 v[96:99], v[156:159], v[210:213], v[96:99]
	v_mfma_f32_16x16x32_bf16 v[76:79], v[148:151], v[238:241], v[76:79]
	v_mfma_f32_16x16x32_bf16 v[72:75], v[156:159], v[238:241], v[72:75]
	s_barrier
	s_add_i32 s36, s55, s44
	v_lshl_add_u64 v[214:215], v[214:215], 0, s[20:21]
	s_mov_b32 m0, s36
	ds_read_b128 v[182:185], v197 offset:49152
	ds_read_b128 v[186:189], v197 offset:50176
	ds_read_b128 v[198:201], v197 offset:51200
	ds_read_b128 v[202:205], v197 offset:52224
	ds_read_b128 v[206:209], v197 offset:53248
	ds_read_b128 v[210:213], v197 offset:54272
	ds_read_b128 v[234:237], v197 offset:55296
	ds_read_b128 v[238:241], v197 offset:56320
	global_load_lds_dwordx4 v[214:215], off
	s_add_i32 m0, s36, 0x2000
	s_add_u32 s34, s34, 0x40080
	v_lshl_add_u64 v[214:215], v[216:217], 0, s[20:21]
	s_addc_u32 s35, s35, 0
	s_add_i32 s36, s56, s44
	global_load_lds_dwordx4 v[214:215], off
	v_lshl_add_u64 v[214:215], s[34:35], 0, v[160:161]
	s_mov_b32 m0, s36
	s_nop 0
	global_load_lds_dwordx4 v[214:215], off
	v_lshl_add_u64 v[214:215], s[34:35], 0, v[176:177]
	s_add_i32 m0, s36, 0x2000
	s_nop 0
	global_load_lds_dwordx4 v[214:215], off
	v_lshl_add_u64 v[214:215], v[242:243], 0, s[20:21]
	s_mov_b32 m0, s51
	s_nop 0
	global_load_lds_dwordx4 v[214:215], off
	v_lshl_add_u64 v[214:215], v[244:245], 0, s[20:21]
	s_mov_b32 m0, s52
	s_nop 0
	global_load_lds_dwordx4 v[214:215], off
	s_waitcnt vmcnt(8)
	s_waitcnt lgkmcnt(0)
	s_barrier
	s_waitcnt lgkmcnt(0)
	v_mfma_f32_16x16x32_bf16 v[60:63], v[64:67], v[182:185], v[60:63]
	v_mfma_f32_16x16x32_bf16 v[56:59], v[80:83], v[182:185], v[56:59]
	v_mfma_f32_16x16x32_bf16 v[44:47], v[64:67], v[198:201], v[44:47]
	v_mfma_f32_16x16x32_bf16 v[40:43], v[80:83], v[198:201], v[40:43]
	v_mfma_f32_16x16x32_bf16 v[28:31], v[64:67], v[206:209], v[28:31]
	v_mfma_f32_16x16x32_bf16 v[24:27], v[80:83], v[206:209], v[24:27]
	v_mfma_f32_16x16x32_bf16 v[12:15], v[64:67], v[234:237], v[12:15]
	v_mfma_f32_16x16x32_bf16 v[8:11], v[80:83], v[234:237], v[8:11]
	v_mfma_f32_16x16x32_bf16 v[60:63], v[68:71], v[186:189], v[60:63]
	v_mfma_f32_16x16x32_bf16 v[56:59], v[88:91], v[186:189], v[56:59]
	v_mfma_f32_16x16x32_bf16 v[44:47], v[68:71], v[202:205], v[44:47]
	v_mfma_f32_16x16x32_bf16 v[40:43], v[88:91], v[202:205], v[40:43]
	v_mfma_f32_16x16x32_bf16 v[28:31], v[68:71], v[210:213], v[28:31]
	v_mfma_f32_16x16x32_bf16 v[24:27], v[88:91], v[210:213], v[24:27]
	v_mfma_f32_16x16x32_bf16 v[12:15], v[68:71], v[238:241], v[12:15]
	v_mfma_f32_16x16x32_bf16 v[8:11], v[88:91], v[238:241], v[8:11]
	v_mfma_f32_16x16x32_bf16 v[52:55], v[144:147], v[182:185], v[52:55]
	v_mfma_f32_16x16x32_bf16 v[48:51], v[152:155], v[182:185], v[48:51]
	v_mfma_f32_16x16x32_bf16 v[36:39], v[144:147], v[198:201], v[36:39]
	v_mfma_f32_16x16x32_bf16 v[32:35], v[152:155], v[198:201], v[32:35]
	v_mfma_f32_16x16x32_bf16 v[20:23], v[144:147], v[206:209], v[20:23]
	v_mfma_f32_16x16x32_bf16 v[16:19], v[152:155], v[206:209], v[16:19]
	v_mfma_f32_16x16x32_bf16 v[4:7], v[144:147], v[234:237], v[4:7]
	v_mfma_f32_16x16x32_bf16 v[0:3], v[152:155], v[234:237], v[0:3]
	v_mfma_f32_16x16x32_bf16 v[52:55], v[148:151], v[186:189], v[52:55]
	v_mfma_f32_16x16x32_bf16 v[48:51], v[156:159], v[186:189], v[48:51]
	v_mfma_f32_16x16x32_bf16 v[36:39], v[148:151], v[202:205], v[36:39]
	v_mfma_f32_16x16x32_bf16 v[32:35], v[156:159], v[202:205], v[32:35]
	v_mfma_f32_16x16x32_bf16 v[20:23], v[148:151], v[210:213], v[20:23]
	v_mfma_f32_16x16x32_bf16 v[16:19], v[156:159], v[210:213], v[16:19]
	v_mfma_f32_16x16x32_bf16 v[4:7], v[148:151], v[238:241], v[4:7]
	v_mfma_f32_16x16x32_bf16 v[0:3], v[156:159], v[238:241], v[0:3]
	s_barrier
	s_add_i32 s31, s31, 2
	s_add_u32 s4, s4, 0x100
	s_addc_u32 s5, s5, 0
	s_add_u32 s17, s17, 0x100
	s_addc_u32 s29, s29, 0
	s_cmp_gt_u32 s31, 13
	s_cbranch_scc0 .LBB0_1176
	s_and_b64 vcc, exec, s[10:11]
	s_cbranch_vccz .LBB0_1179
	s_barrier

.LBB0_1314:
	s_add_u32 s28, s26, 0xfff80080
	s_addc_u32 s29, s27, -1
	s_add_i32 s52, 0, 0x10000
	s_cmp_eq_u32 s51, 28
	s_cselect_b32 s31, s15, s29
	s_cselect_b32 s30, s47, s28
	s_cselect_b32 s29, s13, s50
	s_cselect_b32 s28, s48, s49
	s_add_i32 s54, 0, 0x14000
	v_add_u32_e32 v140, s52, v157
	v_add_u32_e32 v154, s54, v157
	ds_read_b128 v[128:131], v140
	ds_read_b128 v[132:135], v140 offset:1024
	ds_read_b128 v[136:139], v140 offset:2048
	ds_read_b128 v[140:143], v140 offset:3072
	ds_read_b128 v[172:175], v154
	ds_read_b128 v[176:179], v154 offset:1024
	ds_read_b128 v[180:183], v154 offset:2048
	ds_read_b128 v[184:187], v154 offset:3072
	v_lshl_add_u64 v[154:155], s[26:27], 0, v[150:151]
	s_add_i32 m0, s39, 0xc000
	ds_read_b128 v[196:199], v159
	ds_read_b128 v[200:203], v159 offset:1024
	ds_read_b128 v[204:207], v159 offset:2048
	ds_read_b128 v[208:211], v159 offset:3072
	ds_read_b128 v[212:215], v159 offset:4096
	ds_read_b128 v[234:237], v159 offset:5120
	ds_read_b128 v[238:241], v159 offset:6144
	ds_read_b128 v[242:245], v159 offset:7168
	global_load_lds_dwordx4 v[154:155], off
	v_lshl_add_u64 v[154:155], s[26:27], 0, v[152:153]
	s_add_i32 m0, s39, 0xe000
	s_nop 0
	global_load_lds_dwordx4 v[154:155], off
	s_waitcnt vmcnt(8)
	s_waitcnt lgkmcnt(0)
	s_barrier
	s_waitcnt lgkmcnt(0)
	v_mfma_f32_16x16x32_bf16 v[124:127], v[128:131], v[196:199], v[124:127]
	v_mfma_f32_16x16x32_bf16 v[120:123], v[136:139], v[196:199], v[120:123]
	v_mfma_f32_16x16x32_bf16 v[112:115], v[128:131], v[204:207], v[112:115]
	v_mfma_f32_16x16x32_bf16 v[104:107], v[136:139], v[204:207], v[104:107]
	v_mfma_f32_16x16x32_bf16 v[92:95], v[128:131], v[212:215], v[92:95]
	v_mfma_f32_16x16x32_bf16 v[88:91], v[136:139], v[212:215], v[88:91]
	v_mfma_f32_16x16x32_bf16 v[80:83], v[128:131], v[238:241], v[80:83]
	v_mfma_f32_16x16x32_bf16 v[72:75], v[136:139], v[238:241], v[72:75]
	v_mfma_f32_16x16x32_bf16 v[124:127], v[132:135], v[200:203], v[124:127]
	v_mfma_f32_16x16x32_bf16 v[120:123], v[140:143], v[200:203], v[120:123]
	v_mfma_f32_16x16x32_bf16 v[112:115], v[132:135], v[208:211], v[112:115]
	v_mfma_f32_16x16x32_bf16 v[104:107], v[140:143], v[208:211], v[104:107]
	v_mfma_f32_16x16x32_bf16 v[92:95], v[132:135], v[234:237], v[92:95]
	v_mfma_f32_16x16x32_bf16 v[88:91], v[140:143], v[234:237], v[88:91]
	v_mfma_f32_16x16x32_bf16 v[80:83], v[132:135], v[242:245], v[80:83]
	v_mfma_f32_16x16x32_bf16 v[72:75], v[140:143], v[242:245], v[72:75]
	v_mfma_f32_16x16x32_bf16 v[116:119], v[172:175], v[196:199], v[116:119]
	v_mfma_f32_16x16x32_bf16 v[108:111], v[180:183], v[196:199], v[108:111]
	v_mfma_f32_16x16x32_bf16 v[100:103], v[172:175], v[204:207], v[100:103]
	v_mfma_f32_16x16x32_bf16 v[96:99], v[180:183], v[204:207], v[96:99]
	v_mfma_f32_16x16x32_bf16 v[84:87], v[172:175], v[212:215], v[84:87]
	v_mfma_f32_16x16x32_bf16 v[76:79], v[180:183], v[212:215], v[76:79]
	v_mfma_f32_16x16x32_bf16 v[68:71], v[172:175], v[238:241], v[68:71]
	v_mfma_f32_16x16x32_bf16 v[64:67], v[180:183], v[238:241], v[64:67]
	v_mfma_f32_16x16x32_bf16 v[116:119], v[176:179], v[200:203], v[116:119]
	v_mfma_f32_16x16x32_bf16 v[108:111], v[184:187], v[200:203], v[108:111]
	v_mfma_f32_16x16x32_bf16 v[100:103], v[176:179], v[208:211], v[100:103]
	v_mfma_f32_16x16x32_bf16 v[96:99], v[184:187], v[208:211], v[96:99]
	v_mfma_f32_16x16x32_bf16 v[84:87], v[176:179], v[234:237], v[84:87]
	v_mfma_f32_16x16x32_bf16 v[76:79], v[184:187], v[234:237], v[76:79]
	v_mfma_f32_16x16x32_bf16 v[68:71], v[176:179], v[242:245], v[68:71]
	v_mfma_f32_16x16x32_bf16 v[64:67], v[184:187], v[242:245], v[64:67]
	s_barrier
	s_add_i32 s52, s52, s37
	v_lshl_add_u64 v[154:155], s[28:29], 0, v[160:161]
	s_mov_b32 m0, s52
	ds_read_b128 v[196:199], v159 offset:16384
	ds_read_b128 v[200:203], v159 offset:17408
	ds_read_b128 v[204:207], v159 offset:18432
	ds_read_b128 v[208:211], v159 offset:19456
	ds_read_b128 v[212:215], v159 offset:20480
	ds_read_b128 v[234:237], v159 offset:21504
	ds_read_b128 v[238:241], v159 offset:22528
	ds_read_b128 v[242:245], v159 offset:23552
	global_load_lds_dwordx4 v[154:155], off
	s_add_i32 m0, s52, 0x2000
	s_add_u32 s52, s28, 0x80000
	v_lshl_add_u64 v[188:189], s[28:29], 0, v[144:145]
	s_addc_u32 s53, s29, 0
	s_add_i32 s54, s54, s37
	global_load_lds_dwordx4 v[188:189], off
	v_lshl_add_u64 v[216:217], s[52:53], 0, v[160:161]
	s_mov_b32 m0, s54
	v_lshl_add_u64 v[246:247], s[30:31], 0, v[146:147]
	global_load_lds_dwordx4 v[216:217], off
	v_lshl_add_u64 v[216:217], s[52:53], 0, v[144:145]
	s_add_i32 m0, s54, 0x2000
	s_nop 0
	global_load_lds_dwordx4 v[216:217], off
	v_lshl_add_u64 v[216:217], s[30:31], 0, v[148:149]
	s_mov_b32 m0, s39
	s_nop 0
	global_load_lds_dwordx4 v[216:217], off
	s_mov_b32 m0, s41
	s_nop 0
	global_load_lds_dwordx4 v[246:247], off
	s_waitcnt vmcnt(8)
	s_waitcnt lgkmcnt(0)
	s_barrier
	s_waitcnt lgkmcnt(0)
	v_mfma_f32_16x16x32_bf16 v[60:63], v[128:131], v[196:199], v[60:63]
	v_mfma_f32_16x16x32_bf16 v[56:59], v[136:139], v[196:199], v[56:59]
	v_mfma_f32_16x16x32_bf16 v[48:51], v[128:131], v[204:207], v[48:51]
	v_mfma_f32_16x16x32_bf16 v[40:43], v[136:139], v[204:207], v[40:43]
	v_mfma_f32_16x16x32_bf16 v[28:31], v[128:131], v[212:215], v[28:31]
	v_mfma_f32_16x16x32_bf16 v[24:27], v[136:139], v[212:215], v[24:27]
	v_mfma_f32_16x16x32_bf16 v[16:19], v[128:131], v[238:241], v[16:19]
	v_mfma_f32_16x16x32_bf16 v[8:11], v[136:139], v[238:241], v[8:11]
	v_mfma_f32_16x16x32_bf16 v[60:63], v[132:135], v[200:203], v[60:63]
	v_mfma_f32_16x16x32_bf16 v[56:59], v[140:143], v[200:203], v[56:59]
	v_mfma_f32_16x16x32_bf16 v[48:51], v[132:135], v[208:211], v[48:51]
	v_mfma_f32_16x16x32_bf16 v[40:43], v[140:143], v[208:211], v[40:43]
	v_mfma_f32_16x16x32_bf16 v[28:31], v[132:135], v[234:237], v[28:31]
	v_mfma_f32_16x16x32_bf16 v[24:27], v[140:143], v[234:237], v[24:27]
	v_mfma_f32_16x16x32_bf16 v[16:19], v[132:135], v[242:245], v[16:19]
	v_mfma_f32_16x16x32_bf16 v[8:11], v[140:143], v[242:245], v[8:11]
	v_mfma_f32_16x16x32_bf16 v[52:55], v[172:175], v[196:199], v[52:55]
	v_mfma_f32_16x16x32_bf16 v[44:47], v[180:183], v[196:199], v[44:47]
	v_mfma_f32_16x16x32_bf16 v[36:39], v[172:175], v[204:207], v[36:39]
	v_mfma_f32_16x16x32_bf16 v[32:35], v[180:183], v[204:207], v[32:35]
	v_mfma_f32_16x16x32_bf16 v[20:23], v[172:175], v[212:215], v[20:23]
	v_mfma_f32_16x16x32_bf16 v[12:15], v[180:183], v[212:215], v[12:15]
	v_mfma_f32_16x16x32_bf16 v[4:7], v[172:175], v[238:241], v[4:7]
	v_mfma_f32_16x16x32_bf16 v[0:3], v[180:183], v[238:241], v[0:3]
	v_mfma_f32_16x16x32_bf16 v[52:55], v[176:179], v[200:203], v[52:55]
	v_mfma_f32_16x16x32_bf16 v[44:47], v[184:187], v[200:203], v[44:47]
	v_mfma_f32_16x16x32_bf16 v[36:39], v[176:179], v[208:211], v[36:39]
	v_mfma_f32_16x16x32_bf16 v[32:35], v[184:187], v[208:211], v[32:35]
	v_mfma_f32_16x16x32_bf16 v[20:23], v[176:179], v[234:237], v[20:23]
	v_mfma_f32_16x16x32_bf16 v[12:15], v[184:187], v[234:237], v[12:15]
	v_mfma_f32_16x16x32_bf16 v[4:7], v[176:179], v[242:245], v[4:7]
	v_mfma_f32_16x16x32_bf16 v[0:3], v[184:187], v[242:245], v[0:3]
	s_barrier
	s_add_i32 s52, 0, 0x18000
	s_add_i32 s53, 0, 0x1c000
	v_add_u32_e32 v140, s52, v157
	v_add_u32_e32 v162, s53, v157
	ds_read_b128 v[128:131], v140
	ds_read_b128 v[132:135], v140 offset:1024
	ds_read_b128 v[136:139], v140 offset:2048
	ds_read_b128 v[140:143], v140 offset:3072
	ds_read_b128 v[172:175], v162
	ds_read_b128 v[176:179], v162 offset:1024
	ds_read_b128 v[180:183], v162 offset:2048
	ds_read_b128 v[184:187], v162 offset:3072
	s_add_u32 s30, s30, 0x80000
	s_addc_u32 s31, s31, 0
	s_mov_b32 m0, s42
	v_lshl_add_u64 v[248:249], s[30:31], 0, v[148:149]
	ds_read_b128 v[196:199], v159 offset:32768
	ds_read_b128 v[200:203], v159 offset:33792
	ds_read_b128 v[204:207], v159 offset:34816
	ds_read_b128 v[208:211], v159 offset:35840
	ds_read_b128 v[212:215], v159 offset:36864
	ds_read_b128 v[234:237], v159 offset:37888
	ds_read_b128 v[238:241], v159 offset:38912
	ds_read_b128 v[242:245], v159 offset:39936
	global_load_lds_dwordx4 v[248:249], off
	v_lshl_add_u64 v[248:249], s[30:31], 0, v[146:147]
	s_mov_b32 m0, s43
	s_nop 0
	global_load_lds_dwordx4 v[248:249], off
	s_waitcnt vmcnt(8)
	s_waitcnt lgkmcnt(0)
	s_barrier
	s_waitcnt lgkmcnt(0)
	v_mfma_f32_16x16x32_bf16 v[124:127], v[128:131], v[196:199], v[124:127]
	v_mfma_f32_16x16x32_bf16 v[120:123], v[136:139], v[196:199], v[120:123]
	v_mfma_f32_16x16x32_bf16 v[112:115], v[128:131], v[204:207], v[112:115]
	v_mfma_f32_16x16x32_bf16 v[104:107], v[136:139], v[204:207], v[104:107]
	v_mfma_f32_16x16x32_bf16 v[92:95], v[128:131], v[212:215], v[92:95]
	v_mfma_f32_16x16x32_bf16 v[88:91], v[136:139], v[212:215], v[88:91]
	v_mfma_f32_16x16x32_bf16 v[80:83], v[128:131], v[238:241], v[80:83]
	v_mfma_f32_16x16x32_bf16 v[72:75], v[136:139], v[238:241], v[72:75]
	v_mfma_f32_16x16x32_bf16 v[124:127], v[132:135], v[200:203], v[124:127]
	v_mfma_f32_16x16x32_bf16 v[120:123], v[140:143], v[200:203], v[120:123]
	v_mfma_f32_16x16x32_bf16 v[112:115], v[132:135], v[208:211], v[112:115]
	v_mfma_f32_16x16x32_bf16 v[104:107], v[140:143], v[208:211], v[104:107]
	v_mfma_f32_16x16x32_bf16 v[92:95], v[132:135], v[234:237], v[92:95]
	v_mfma_f32_16x16x32_bf16 v[88:91], v[140:143], v[234:237], v[88:91]
	v_mfma_f32_16x16x32_bf16 v[80:83], v[132:135], v[242:245], v[80:83]
	v_mfma_f32_16x16x32_bf16 v[72:75], v[140:143], v[242:245], v[72:75]
	v_mfma_f32_16x16x32_bf16 v[116:119], v[172:175], v[196:199], v[116:119]
	v_mfma_f32_16x16x32_bf16 v[108:111], v[180:183], v[196:199], v[108:111]
	v_mfma_f32_16x16x32_bf16 v[100:103], v[172:175], v[204:207], v[100:103]
	v_mfma_f32_16x16x32_bf16 v[96:99], v[180:183], v[204:207], v[96:99]
	v_mfma_f32_16x16x32_bf16 v[84:87], v[172:175], v[212:215], v[84:87]
	v_mfma_f32_16x16x32_bf16 v[76:79], v[180:183], v[212:215], v[76:79]
	v_mfma_f32_16x16x32_bf16 v[68:71], v[172:175], v[238:241], v[68:71]
	v_mfma_f32_16x16x32_bf16 v[64:67], v[180:183], v[238:241], v[64:67]
	v_mfma_f32_16x16x32_bf16 v[116:119], v[176:179], v[200:203], v[116:119]
	v_mfma_f32_16x16x32_bf16 v[108:111], v[184:187], v[200:203], v[108:111]
	v_mfma_f32_16x16x32_bf16 v[100:103], v[176:179], v[208:211], v[100:103]
	v_mfma_f32_16x16x32_bf16 v[96:99], v[184:187], v[208:211], v[96:99]
	v_mfma_f32_16x16x32_bf16 v[84:87], v[176:179], v[234:237], v[84:87]
	v_mfma_f32_16x16x32_bf16 v[76:79], v[184:187], v[234:237], v[76:79]
	v_mfma_f32_16x16x32_bf16 v[68:71], v[176:179], v[242:245], v[68:71]
	v_mfma_f32_16x16x32_bf16 v[64:67], v[184:187], v[242:245], v[64:67]
	s_barrier
	s_add_i32 s30, s52, s37
	v_lshl_add_u64 v[154:155], v[154:155], 0, s[20:21]
	s_mov_b32 m0, s30
	ds_read_b128 v[196:199], v159 offset:49152
	ds_read_b128 v[200:203], v159 offset:50176
	ds_read_b128 v[204:207], v159 offset:51200
	ds_read_b128 v[208:211], v159 offset:52224
	ds_read_b128 v[212:215], v159 offset:53248
	ds_read_b128 v[234:237], v159 offset:54272
	ds_read_b128 v[238:241], v159 offset:55296
	ds_read_b128 v[242:245], v159 offset:56320
	global_load_lds_dwordx4 v[154:155], off
	s_add_i32 m0, s30, 0x2000
	s_add_u32 s28, s28, 0x80080
	v_lshl_add_u64 v[154:155], v[188:189], 0, s[20:21]
	s_addc_u32 s29, s29, 0
	s_add_i32 s30, s53, s37
	global_load_lds_dwordx4 v[154:155], off
	v_lshl_add_u64 v[154:155], s[28:29], 0, v[160:161]
	s_mov_b32 m0, s30
	s_nop 0
	global_load_lds_dwordx4 v[154:155], off
	v_lshl_add_u64 v[154:155], s[28:29], 0, v[144:145]
	s_add_i32 m0, s30, 0x2000
	s_nop 0
	global_load_lds_dwordx4 v[154:155], off
	v_lshl_add_u64 v[154:155], v[216:217], 0, s[20:21]
	s_mov_b32 m0, s44
	s_nop 0
	global_load_lds_dwordx4 v[154:155], off
	v_lshl_add_u64 v[154:155], v[246:247], 0, s[20:21]
	s_mov_b32 m0, s45
	s_nop 0
	global_load_lds_dwordx4 v[154:155], off
	s_waitcnt vmcnt(8)
	s_waitcnt lgkmcnt(0)
	s_barrier
	s_waitcnt lgkmcnt(0)
	v_mfma_f32_16x16x32_bf16 v[60:63], v[128:131], v[196:199], v[60:63]
	v_mfma_f32_16x16x32_bf16 v[56:59], v[136:139], v[196:199], v[56:59]
	v_mfma_f32_16x16x32_bf16 v[48:51], v[128:131], v[204:207], v[48:51]
	v_mfma_f32_16x16x32_bf16 v[40:43], v[136:139], v[204:207], v[40:43]
	v_mfma_f32_16x16x32_bf16 v[28:31], v[128:131], v[212:215], v[28:31]
	v_mfma_f32_16x16x32_bf16 v[24:27], v[136:139], v[212:215], v[24:27]
	v_mfma_f32_16x16x32_bf16 v[16:19], v[128:131], v[238:241], v[16:19]
	v_mfma_f32_16x16x32_bf16 v[8:11], v[136:139], v[238:241], v[8:11]
	v_mfma_f32_16x16x32_bf16 v[60:63], v[132:135], v[200:203], v[60:63]
	v_mfma_f32_16x16x32_bf16 v[56:59], v[140:143], v[200:203], v[56:59]
	v_mfma_f32_16x16x32_bf16 v[48:51], v[132:135], v[208:211], v[48:51]
	v_mfma_f32_16x16x32_bf16 v[40:43], v[140:143], v[208:211], v[40:43]
	v_mfma_f32_16x16x32_bf16 v[28:31], v[132:135], v[234:237], v[28:31]
	v_mfma_f32_16x16x32_bf16 v[24:27], v[140:143], v[234:237], v[24:27]
	v_mfma_f32_16x16x32_bf16 v[16:19], v[132:135], v[242:245], v[16:19]
	v_mfma_f32_16x16x32_bf16 v[8:11], v[140:143], v[242:245], v[8:11]
	v_mfma_f32_16x16x32_bf16 v[52:55], v[172:175], v[196:199], v[52:55]
	v_mfma_f32_16x16x32_bf16 v[44:47], v[180:183], v[196:199], v[44:47]
	v_mfma_f32_16x16x32_bf16 v[36:39], v[172:175], v[204:207], v[36:39]
	v_mfma_f32_16x16x32_bf16 v[32:35], v[180:183], v[204:207], v[32:35]
	v_mfma_f32_16x16x32_bf16 v[20:23], v[172:175], v[212:215], v[20:23]
	v_mfma_f32_16x16x32_bf16 v[12:15], v[180:183], v[212:215], v[12:15]
	v_mfma_f32_16x16x32_bf16 v[4:7], v[172:175], v[238:241], v[4:7]
	v_mfma_f32_16x16x32_bf16 v[0:3], v[180:183], v[238:241], v[0:3]
	v_mfma_f32_16x16x32_bf16 v[52:55], v[176:179], v[200:203], v[52:55]
	v_mfma_f32_16x16x32_bf16 v[44:47], v[184:187], v[200:203], v[44:47]
	v_mfma_f32_16x16x32_bf16 v[36:39], v[176:179], v[208:211], v[36:39]
	v_mfma_f32_16x16x32_bf16 v[32:35], v[184:187], v[208:211], v[32:35]
	v_mfma_f32_16x16x32_bf16 v[20:23], v[176:179], v[234:237], v[20:23]
	v_mfma_f32_16x16x32_bf16 v[12:15], v[184:187], v[234:237], v[12:15]
	v_mfma_f32_16x16x32_bf16 v[4:7], v[176:179], v[242:245], v[4:7]
	v_mfma_f32_16x16x32_bf16 v[0:3], v[184:187], v[242:245], v[0:3]
	s_barrier
	s_add_i32 s51, s51, 2
	s_add_u32 s26, s26, 0x100
	s_addc_u32 s27, s27, 0
	s_add_u32 s49, s49, 0x100
	s_addc_u32 s50, s50, 0
	s_cmp_gt_u32 s51, 29
	s_cbranch_scc0 .LBB0_1314
	s_and_b64 vcc, exec, s[10:11]
	s_cbranch_vccz .LBB0_1317
	s_barrier

.LBB0_1451:
	s_add_u32 s30, s28, 0xfff80080
	s_addc_u32 s31, s29, -1
	s_add_i32 s55, 0, 0x10000
	s_cmp_eq_u32 s54, 28
	s_cselect_b32 s35, s15, s31
	s_cselect_b32 s34, s50, s30
	s_cselect_b32 s31, s13, s53
	s_cselect_b32 s30, s51, s52
	s_add_i32 s58, 0, 0x14000
	v_add_u32_e32 v154, s55, v139
	v_add_u32_e32 v158, s58, v139
	ds_read_b128 v[142:145], v154
	ds_read_b128 v[146:149], v154 offset:1024
	ds_read_b128 v[150:153], v154 offset:2048
	ds_read_b128 v[154:157], v154 offset:3072
	ds_read_b128 v[172:175], v158
	ds_read_b128 v[176:179], v158 offset:1024
	ds_read_b128 v[180:183], v158 offset:2048
	ds_read_b128 v[184:187], v158 offset:3072
	v_lshl_add_u64 v[158:159], s[28:29], 0, v[134:135]
	s_add_i32 m0, s27, 0xc000
	ds_read_b128 v[196:199], v141
	ds_read_b128 v[200:203], v141 offset:1024
	ds_read_b128 v[204:207], v141 offset:2048
	ds_read_b128 v[208:211], v141 offset:3072
	ds_read_b128 v[212:215], v141 offset:4096
	ds_read_b128 v[234:237], v141 offset:5120
	ds_read_b128 v[238:241], v141 offset:6144
	ds_read_b128 v[242:245], v141 offset:7168
	global_load_lds_dwordx4 v[158:159], off
	v_lshl_add_u64 v[158:159], s[28:29], 0, v[136:137]
	s_add_i32 m0, s27, 0xe000
	s_nop 0
	global_load_lds_dwordx4 v[158:159], off
	s_waitcnt vmcnt(8)
	s_waitcnt lgkmcnt(0)
	s_barrier
	s_waitcnt lgkmcnt(0)
	v_mfma_f32_16x16x32_bf16 v[124:127], v[142:145], v[196:199], v[124:127]
	v_mfma_f32_16x16x32_bf16 v[120:123], v[150:153], v[196:199], v[120:123]
	v_mfma_f32_16x16x32_bf16 v[108:111], v[142:145], v[204:207], v[108:111]
	v_mfma_f32_16x16x32_bf16 v[104:107], v[150:153], v[204:207], v[104:107]
	v_mfma_f32_16x16x32_bf16 v[92:95], v[142:145], v[212:215], v[92:95]
	v_mfma_f32_16x16x32_bf16 v[88:91], v[150:153], v[212:215], v[88:91]
	v_mfma_f32_16x16x32_bf16 v[76:79], v[142:145], v[238:241], v[76:79]
	v_mfma_f32_16x16x32_bf16 v[72:75], v[150:153], v[238:241], v[72:75]
	v_mfma_f32_16x16x32_bf16 v[124:127], v[146:149], v[200:203], v[124:127]
	v_mfma_f32_16x16x32_bf16 v[120:123], v[154:157], v[200:203], v[120:123]
	v_mfma_f32_16x16x32_bf16 v[108:111], v[146:149], v[208:211], v[108:111]
	v_mfma_f32_16x16x32_bf16 v[104:107], v[154:157], v[208:211], v[104:107]
	v_mfma_f32_16x16x32_bf16 v[92:95], v[146:149], v[234:237], v[92:95]
	v_mfma_f32_16x16x32_bf16 v[88:91], v[154:157], v[234:237], v[88:91]
	v_mfma_f32_16x16x32_bf16 v[76:79], v[146:149], v[242:245], v[76:79]
	v_mfma_f32_16x16x32_bf16 v[72:75], v[154:157], v[242:245], v[72:75]
	v_mfma_f32_16x16x32_bf16 v[116:119], v[172:175], v[196:199], v[116:119]
	v_mfma_f32_16x16x32_bf16 v[112:115], v[180:183], v[196:199], v[112:115]
	v_mfma_f32_16x16x32_bf16 v[100:103], v[172:175], v[204:207], v[100:103]
	v_mfma_f32_16x16x32_bf16 v[96:99], v[180:183], v[204:207], v[96:99]
	v_mfma_f32_16x16x32_bf16 v[84:87], v[172:175], v[212:215], v[84:87]
	v_mfma_f32_16x16x32_bf16 v[80:83], v[180:183], v[212:215], v[80:83]
	v_mfma_f32_16x16x32_bf16 v[68:71], v[172:175], v[238:241], v[68:71]
	v_mfma_f32_16x16x32_bf16 v[64:67], v[180:183], v[238:241], v[64:67]
	v_mfma_f32_16x16x32_bf16 v[116:119], v[176:179], v[200:203], v[116:119]
	v_mfma_f32_16x16x32_bf16 v[112:115], v[184:187], v[200:203], v[112:115]
	v_mfma_f32_16x16x32_bf16 v[100:103], v[176:179], v[208:211], v[100:103]
	v_mfma_f32_16x16x32_bf16 v[96:99], v[184:187], v[208:211], v[96:99]
	v_mfma_f32_16x16x32_bf16 v[84:87], v[176:179], v[234:237], v[84:87]
	v_mfma_f32_16x16x32_bf16 v[80:83], v[184:187], v[234:237], v[80:83]
	v_mfma_f32_16x16x32_bf16 v[68:71], v[176:179], v[242:245], v[68:71]
	v_mfma_f32_16x16x32_bf16 v[64:67], v[184:187], v[242:245], v[64:67]
	s_barrier
	s_add_i32 s55, s55, s39
	v_lshl_add_u64 v[158:159], s[30:31], 0, v[160:161]
	s_mov_b32 m0, s55
	ds_read_b128 v[196:199], v141 offset:16384
	ds_read_b128 v[200:203], v141 offset:17408
	ds_read_b128 v[204:207], v141 offset:18432
	ds_read_b128 v[208:211], v141 offset:19456
	ds_read_b128 v[212:215], v141 offset:20480
	ds_read_b128 v[234:237], v141 offset:21504
	ds_read_b128 v[238:241], v141 offset:22528
	ds_read_b128 v[242:245], v141 offset:23552
	global_load_lds_dwordx4 v[158:159], off
	s_add_i32 m0, s55, 0x2000
	s_add_u32 s56, s30, 0x80000
	v_lshl_add_u64 v[188:189], s[30:31], 0, v[128:129]
	s_addc_u32 s57, s31, 0
	s_add_i32 s55, s58, s39
	global_load_lds_dwordx4 v[188:189], off
	v_lshl_add_u64 v[216:217], s[56:57], 0, v[160:161]
	s_mov_b32 m0, s55
	v_lshl_add_u64 v[246:247], s[34:35], 0, v[130:131]
	global_load_lds_dwordx4 v[216:217], off
	v_lshl_add_u64 v[216:217], s[56:57], 0, v[128:129]
	s_add_i32 m0, s55, 0x2000
	s_nop 0
	global_load_lds_dwordx4 v[216:217], off
	v_lshl_add_u64 v[216:217], s[34:35], 0, v[132:133]
	s_mov_b32 m0, s27
	s_nop 0
	global_load_lds_dwordx4 v[216:217], off
	s_mov_b32 m0, s43
	s_nop 0
	global_load_lds_dwordx4 v[246:247], off
	s_waitcnt vmcnt(8)
	s_waitcnt lgkmcnt(0)
	s_barrier
	s_waitcnt lgkmcnt(0)
	v_mfma_f32_16x16x32_bf16 v[60:63], v[142:145], v[196:199], v[60:63]
	v_mfma_f32_16x16x32_bf16 v[56:59], v[150:153], v[196:199], v[56:59]
	v_mfma_f32_16x16x32_bf16 v[44:47], v[142:145], v[204:207], v[44:47]
	v_mfma_f32_16x16x32_bf16 v[40:43], v[150:153], v[204:207], v[40:43]
	v_mfma_f32_16x16x32_bf16 v[28:31], v[142:145], v[212:215], v[28:31]
	v_mfma_f32_16x16x32_bf16 v[24:27], v[150:153], v[212:215], v[24:27]
	v_mfma_f32_16x16x32_bf16 v[12:15], v[142:145], v[238:241], v[12:15]
	v_mfma_f32_16x16x32_bf16 v[8:11], v[150:153], v[238:241], v[8:11]
	v_mfma_f32_16x16x32_bf16 v[60:63], v[146:149], v[200:203], v[60:63]
	v_mfma_f32_16x16x32_bf16 v[56:59], v[154:157], v[200:203], v[56:59]
	v_mfma_f32_16x16x32_bf16 v[44:47], v[146:149], v[208:211], v[44:47]
	v_mfma_f32_16x16x32_bf16 v[40:43], v[154:157], v[208:211], v[40:43]
	v_mfma_f32_16x16x32_bf16 v[28:31], v[146:149], v[234:237], v[28:31]
	v_mfma_f32_16x16x32_bf16 v[24:27], v[154:157], v[234:237], v[24:27]
	v_mfma_f32_16x16x32_bf16 v[12:15], v[146:149], v[242:245], v[12:15]
	v_mfma_f32_16x16x32_bf16 v[8:11], v[154:157], v[242:245], v[8:11]
	v_mfma_f32_16x16x32_bf16 v[52:55], v[172:175], v[196:199], v[52:55]
	v_mfma_f32_16x16x32_bf16 v[48:51], v[180:183], v[196:199], v[48:51]
	v_mfma_f32_16x16x32_bf16 v[36:39], v[172:175], v[204:207], v[36:39]
	v_mfma_f32_16x16x32_bf16 v[32:35], v[180:183], v[204:207], v[32:35]
	v_mfma_f32_16x16x32_bf16 v[20:23], v[172:175], v[212:215], v[20:23]
	v_mfma_f32_16x16x32_bf16 v[16:19], v[180:183], v[212:215], v[16:19]
	v_mfma_f32_16x16x32_bf16 v[4:7], v[172:175], v[238:241], v[4:7]
	v_mfma_f32_16x16x32_bf16 v[0:3], v[180:183], v[238:241], v[0:3]
	v_mfma_f32_16x16x32_bf16 v[52:55], v[176:179], v[200:203], v[52:55]
	v_mfma_f32_16x16x32_bf16 v[48:51], v[184:187], v[200:203], v[48:51]
	v_mfma_f32_16x16x32_bf16 v[36:39], v[176:179], v[208:211], v[36:39]
	v_mfma_f32_16x16x32_bf16 v[32:35], v[184:187], v[208:211], v[32:35]
	v_mfma_f32_16x16x32_bf16 v[20:23], v[176:179], v[234:237], v[20:23]
	v_mfma_f32_16x16x32_bf16 v[16:19], v[184:187], v[234:237], v[16:19]
	v_mfma_f32_16x16x32_bf16 v[4:7], v[176:179], v[242:245], v[4:7]
	v_mfma_f32_16x16x32_bf16 v[0:3], v[184:187], v[242:245], v[0:3]
	s_barrier
	s_add_i32 s55, 0, 0x18000
	s_add_i32 s56, 0, 0x1c000
	v_add_u32_e32 v154, s55, v139
	v_add_u32_e32 v162, s56, v139
	ds_read_b128 v[142:145], v154
	ds_read_b128 v[146:149], v154 offset:1024
	ds_read_b128 v[150:153], v154 offset:2048
	ds_read_b128 v[154:157], v154 offset:3072
	ds_read_b128 v[172:175], v162
	ds_read_b128 v[176:179], v162 offset:1024
	ds_read_b128 v[180:183], v162 offset:2048
	ds_read_b128 v[184:187], v162 offset:3072
	s_add_u32 s34, s34, 0x80000
	s_addc_u32 s35, s35, 0
	s_mov_b32 m0, s44
	v_lshl_add_u64 v[248:249], s[34:35], 0, v[132:133]
	ds_read_b128 v[196:199], v141 offset:32768
	ds_read_b128 v[200:203], v141 offset:33792
	ds_read_b128 v[204:207], v141 offset:34816
	ds_read_b128 v[208:211], v141 offset:35840
	ds_read_b128 v[212:215], v141 offset:36864
	ds_read_b128 v[234:237], v141 offset:37888
	ds_read_b128 v[238:241], v141 offset:38912
	ds_read_b128 v[242:245], v141 offset:39936
	global_load_lds_dwordx4 v[248:249], off
	v_lshl_add_u64 v[248:249], s[34:35], 0, v[130:131]
	s_mov_b32 m0, s45
	s_nop 0
	global_load_lds_dwordx4 v[248:249], off
	s_waitcnt vmcnt(8)
	s_waitcnt lgkmcnt(0)
	s_barrier
	s_waitcnt lgkmcnt(0)
	v_mfma_f32_16x16x32_bf16 v[124:127], v[142:145], v[196:199], v[124:127]
	v_mfma_f32_16x16x32_bf16 v[120:123], v[150:153], v[196:199], v[120:123]
	v_mfma_f32_16x16x32_bf16 v[108:111], v[142:145], v[204:207], v[108:111]
	v_mfma_f32_16x16x32_bf16 v[104:107], v[150:153], v[204:207], v[104:107]
	v_mfma_f32_16x16x32_bf16 v[92:95], v[142:145], v[212:215], v[92:95]
	v_mfma_f32_16x16x32_bf16 v[88:91], v[150:153], v[212:215], v[88:91]
	v_mfma_f32_16x16x32_bf16 v[76:79], v[142:145], v[238:241], v[76:79]
	v_mfma_f32_16x16x32_bf16 v[72:75], v[150:153], v[238:241], v[72:75]
	v_mfma_f32_16x16x32_bf16 v[124:127], v[146:149], v[200:203], v[124:127]
	v_mfma_f32_16x16x32_bf16 v[120:123], v[154:157], v[200:203], v[120:123]
	v_mfma_f32_16x16x32_bf16 v[108:111], v[146:149], v[208:211], v[108:111]
	v_mfma_f32_16x16x32_bf16 v[104:107], v[154:157], v[208:211], v[104:107]
	v_mfma_f32_16x16x32_bf16 v[92:95], v[146:149], v[234:237], v[92:95]
	v_mfma_f32_16x16x32_bf16 v[88:91], v[154:157], v[234:237], v[88:91]
	v_mfma_f32_16x16x32_bf16 v[76:79], v[146:149], v[242:245], v[76:79]
	v_mfma_f32_16x16x32_bf16 v[72:75], v[154:157], v[242:245], v[72:75]
	v_mfma_f32_16x16x32_bf16 v[116:119], v[172:175], v[196:199], v[116:119]
	v_mfma_f32_16x16x32_bf16 v[112:115], v[180:183], v[196:199], v[112:115]
	v_mfma_f32_16x16x32_bf16 v[100:103], v[172:175], v[204:207], v[100:103]
	v_mfma_f32_16x16x32_bf16 v[96:99], v[180:183], v[204:207], v[96:99]
	v_mfma_f32_16x16x32_bf16 v[84:87], v[172:175], v[212:215], v[84:87]
	v_mfma_f32_16x16x32_bf16 v[80:83], v[180:183], v[212:215], v[80:83]
	v_mfma_f32_16x16x32_bf16 v[68:71], v[172:175], v[238:241], v[68:71]
	v_mfma_f32_16x16x32_bf16 v[64:67], v[180:183], v[238:241], v[64:67]
	v_mfma_f32_16x16x32_bf16 v[116:119], v[176:179], v[200:203], v[116:119]
	v_mfma_f32_16x16x32_bf16 v[112:115], v[184:187], v[200:203], v[112:115]
	v_mfma_f32_16x16x32_bf16 v[100:103], v[176:179], v[208:211], v[100:103]
	v_mfma_f32_16x16x32_bf16 v[96:99], v[184:187], v[208:211], v[96:99]
	v_mfma_f32_16x16x32_bf16 v[84:87], v[176:179], v[234:237], v[84:87]
	v_mfma_f32_16x16x32_bf16 v[80:83], v[184:187], v[234:237], v[80:83]
	v_mfma_f32_16x16x32_bf16 v[68:71], v[176:179], v[242:245], v[68:71]
	v_mfma_f32_16x16x32_bf16 v[64:67], v[184:187], v[242:245], v[64:67]
	s_barrier
	s_add_i32 s34, s55, s39
	v_lshl_add_u64 v[158:159], v[158:159], 0, s[20:21]
	s_mov_b32 m0, s34
	ds_read_b128 v[196:199], v141 offset:49152
	ds_read_b128 v[200:203], v141 offset:50176
	ds_read_b128 v[204:207], v141 offset:51200
	ds_read_b128 v[208:211], v141 offset:52224
	ds_read_b128 v[212:215], v141 offset:53248
	ds_read_b128 v[234:237], v141 offset:54272
	ds_read_b128 v[238:241], v141 offset:55296
	ds_read_b128 v[242:245], v141 offset:56320
	global_load_lds_dwordx4 v[158:159], off
	s_add_i32 m0, s34, 0x2000
	s_add_u32 s30, s30, 0x80080
	v_lshl_add_u64 v[158:159], v[188:189], 0, s[20:21]
	s_addc_u32 s31, s31, 0
	s_add_i32 s34, s56, s39
	global_load_lds_dwordx4 v[158:159], off
	v_lshl_add_u64 v[158:159], s[30:31], 0, v[160:161]
	s_mov_b32 m0, s34
	s_nop 0
	global_load_lds_dwordx4 v[158:159], off
	v_lshl_add_u64 v[158:159], s[30:31], 0, v[128:129]
	s_add_i32 m0, s34, 0x2000
	s_nop 0
	global_load_lds_dwordx4 v[158:159], off
	v_lshl_add_u64 v[158:159], v[216:217], 0, s[20:21]
	s_mov_b32 m0, s46
	s_nop 0
	global_load_lds_dwordx4 v[158:159], off
	v_lshl_add_u64 v[158:159], v[246:247], 0, s[20:21]
	s_mov_b32 m0, s47
	s_nop 0
	global_load_lds_dwordx4 v[158:159], off
	s_waitcnt vmcnt(8)
	s_waitcnt lgkmcnt(0)
	s_barrier
	s_waitcnt lgkmcnt(0)
	v_mfma_f32_16x16x32_bf16 v[60:63], v[142:145], v[196:199], v[60:63]
	v_mfma_f32_16x16x32_bf16 v[56:59], v[150:153], v[196:199], v[56:59]
	v_mfma_f32_16x16x32_bf16 v[44:47], v[142:145], v[204:207], v[44:47]
	v_mfma_f32_16x16x32_bf16 v[40:43], v[150:153], v[204:207], v[40:43]
	v_mfma_f32_16x16x32_bf16 v[28:31], v[142:145], v[212:215], v[28:31]
	v_mfma_f32_16x16x32_bf16 v[24:27], v[150:153], v[212:215], v[24:27]
	v_mfma_f32_16x16x32_bf16 v[12:15], v[142:145], v[238:241], v[12:15]
	v_mfma_f32_16x16x32_bf16 v[8:11], v[150:153], v[238:241], v[8:11]
	v_mfma_f32_16x16x32_bf16 v[60:63], v[146:149], v[200:203], v[60:63]
	v_mfma_f32_16x16x32_bf16 v[56:59], v[154:157], v[200:203], v[56:59]
	v_mfma_f32_16x16x32_bf16 v[44:47], v[146:149], v[208:211], v[44:47]
	v_mfma_f32_16x16x32_bf16 v[40:43], v[154:157], v[208:211], v[40:43]
	v_mfma_f32_16x16x32_bf16 v[28:31], v[146:149], v[234:237], v[28:31]
	v_mfma_f32_16x16x32_bf16 v[24:27], v[154:157], v[234:237], v[24:27]
	v_mfma_f32_16x16x32_bf16 v[12:15], v[146:149], v[242:245], v[12:15]
	v_mfma_f32_16x16x32_bf16 v[8:11], v[154:157], v[242:245], v[8:11]
	v_mfma_f32_16x16x32_bf16 v[52:55], v[172:175], v[196:199], v[52:55]
	v_mfma_f32_16x16x32_bf16 v[48:51], v[180:183], v[196:199], v[48:51]
	v_mfma_f32_16x16x32_bf16 v[36:39], v[172:175], v[204:207], v[36:39]
	v_mfma_f32_16x16x32_bf16 v[32:35], v[180:183], v[204:207], v[32:35]
	v_mfma_f32_16x16x32_bf16 v[20:23], v[172:175], v[212:215], v[20:23]
	v_mfma_f32_16x16x32_bf16 v[16:19], v[180:183], v[212:215], v[16:19]
	v_mfma_f32_16x16x32_bf16 v[4:7], v[172:175], v[238:241], v[4:7]
	v_mfma_f32_16x16x32_bf16 v[0:3], v[180:183], v[238:241], v[0:3]
	v_mfma_f32_16x16x32_bf16 v[52:55], v[176:179], v[200:203], v[52:55]
	v_mfma_f32_16x16x32_bf16 v[48:51], v[184:187], v[200:203], v[48:51]
	v_mfma_f32_16x16x32_bf16 v[36:39], v[176:179], v[208:211], v[36:39]
	v_mfma_f32_16x16x32_bf16 v[32:35], v[184:187], v[208:211], v[32:35]
	v_mfma_f32_16x16x32_bf16 v[20:23], v[176:179], v[234:237], v[20:23]
	v_mfma_f32_16x16x32_bf16 v[16:19], v[184:187], v[234:237], v[16:19]
	v_mfma_f32_16x16x32_bf16 v[4:7], v[176:179], v[242:245], v[4:7]
	v_mfma_f32_16x16x32_bf16 v[0:3], v[184:187], v[242:245], v[0:3]
	s_barrier
	s_add_i32 s54, s54, 2
	s_add_u32 s28, s28, 0x100
	s_addc_u32 s29, s29, 0
	s_add_u32 s52, s52, 0x100
	s_addc_u32 s53, s53, 0
	s_cmp_gt_u32 s54, 29
	s_cbranch_scc0 .LBB0_1451
	s_and_b64 vcc, exec, s[10:11]
	s_cbranch_vccz .LBB0_1454
	s_barrier

.LBB0_1522:
	s_add_u32 s28, s26, 0xffe00080
	s_addc_u32 s29, s27, -1
	s_add_i32 s53, 0, 0x10000
	s_cmpk_eq_i32 s52, 0x7c
	s_cselect_b32 s31, s13, s29
	s_cselect_b32 s30, s48, s28
	s_cselect_b32 s29, s11, s51
	s_cselect_b32 s28, s49, s50
	s_add_i32 s56, 0, 0x14000
	v_add_u32_e32 v140, s53, v157
	v_add_u32_e32 v154, s56, v157
	ds_read_b128 v[128:131], v140
	ds_read_b128 v[132:135], v140 offset:1024
	ds_read_b128 v[136:139], v140 offset:2048
	ds_read_b128 v[140:143], v140 offset:3072
	ds_read_b128 v[172:175], v154
	ds_read_b128 v[176:179], v154 offset:1024
	ds_read_b128 v[180:183], v154 offset:2048
	ds_read_b128 v[184:187], v154 offset:3072
	v_lshl_add_u64 v[154:155], s[26:27], 0, v[150:151]
	s_add_i32 m0, s19, 0xc000
	ds_read_b128 v[196:199], v159
	ds_read_b128 v[200:203], v159 offset:1024
	ds_read_b128 v[204:207], v159 offset:2048
	ds_read_b128 v[208:211], v159 offset:3072
	ds_read_b128 v[212:215], v159 offset:4096
	ds_read_b128 v[234:237], v159 offset:5120
	ds_read_b128 v[238:241], v159 offset:6144
	ds_read_b128 v[242:245], v159 offset:7168
	global_load_lds_dwordx4 v[154:155], off
	v_lshl_add_u64 v[154:155], s[26:27], 0, v[152:153]
	s_add_i32 m0, s19, 0xe000
	s_nop 0
	global_load_lds_dwordx4 v[154:155], off
	s_waitcnt vmcnt(8)
	s_waitcnt lgkmcnt(0)
	s_barrier
	s_waitcnt lgkmcnt(0)
	v_mfma_f32_16x16x32_bf16 v[124:127], v[128:131], v[196:199], v[124:127]
	v_mfma_f32_16x16x32_bf16 v[120:123], v[136:139], v[196:199], v[120:123]
	v_mfma_f32_16x16x32_bf16 v[116:119], v[128:131], v[204:207], v[116:119]
	v_mfma_f32_16x16x32_bf16 v[108:111], v[136:139], v[204:207], v[108:111]
	v_mfma_f32_16x16x32_bf16 v[92:95], v[128:131], v[212:215], v[92:95]
	v_mfma_f32_16x16x32_bf16 v[88:91], v[136:139], v[212:215], v[88:91]
	v_mfma_f32_16x16x32_bf16 v[84:87], v[128:131], v[238:241], v[84:87]
	v_mfma_f32_16x16x32_bf16 v[76:79], v[136:139], v[238:241], v[76:79]
	v_mfma_f32_16x16x32_bf16 v[124:127], v[132:135], v[200:203], v[124:127]
	v_mfma_f32_16x16x32_bf16 v[120:123], v[140:143], v[200:203], v[120:123]
	v_mfma_f32_16x16x32_bf16 v[116:119], v[132:135], v[208:211], v[116:119]
	v_mfma_f32_16x16x32_bf16 v[108:111], v[140:143], v[208:211], v[108:111]
	v_mfma_f32_16x16x32_bf16 v[92:95], v[132:135], v[234:237], v[92:95]
	v_mfma_f32_16x16x32_bf16 v[88:91], v[140:143], v[234:237], v[88:91]
	v_mfma_f32_16x16x32_bf16 v[84:87], v[132:135], v[242:245], v[84:87]
	v_mfma_f32_16x16x32_bf16 v[76:79], v[140:143], v[242:245], v[76:79]
	v_mfma_f32_16x16x32_bf16 v[112:115], v[172:175], v[196:199], v[112:115]
	v_mfma_f32_16x16x32_bf16 v[104:107], v[180:183], v[196:199], v[104:107]
	v_mfma_f32_16x16x32_bf16 v[100:103], v[172:175], v[204:207], v[100:103]
	v_mfma_f32_16x16x32_bf16 v[96:99], v[180:183], v[204:207], v[96:99]
	v_mfma_f32_16x16x32_bf16 v[80:83], v[172:175], v[212:215], v[80:83]
	v_mfma_f32_16x16x32_bf16 v[72:75], v[180:183], v[212:215], v[72:75]
	v_mfma_f32_16x16x32_bf16 v[68:71], v[172:175], v[238:241], v[68:71]
	v_mfma_f32_16x16x32_bf16 v[64:67], v[180:183], v[238:241], v[64:67]
	v_mfma_f32_16x16x32_bf16 v[112:115], v[176:179], v[200:203], v[112:115]
	v_mfma_f32_16x16x32_bf16 v[104:107], v[184:187], v[200:203], v[104:107]
	v_mfma_f32_16x16x32_bf16 v[100:103], v[176:179], v[208:211], v[100:103]
	v_mfma_f32_16x16x32_bf16 v[96:99], v[184:187], v[208:211], v[96:99]
	v_mfma_f32_16x16x32_bf16 v[80:83], v[176:179], v[234:237], v[80:83]
	v_mfma_f32_16x16x32_bf16 v[72:75], v[184:187], v[234:237], v[72:75]
	v_mfma_f32_16x16x32_bf16 v[68:71], v[176:179], v[242:245], v[68:71]
	v_mfma_f32_16x16x32_bf16 v[64:67], v[184:187], v[242:245], v[64:67]
	s_barrier
	s_add_i32 s53, s53, s39
	v_lshl_add_u64 v[154:155], s[28:29], 0, v[160:161]
	s_mov_b32 m0, s53
	ds_read_b128 v[196:199], v159 offset:16384
	ds_read_b128 v[200:203], v159 offset:17408
	ds_read_b128 v[204:207], v159 offset:18432
	ds_read_b128 v[208:211], v159 offset:19456
	ds_read_b128 v[212:215], v159 offset:20480
	ds_read_b128 v[234:237], v159 offset:21504
	ds_read_b128 v[238:241], v159 offset:22528
	ds_read_b128 v[242:245], v159 offset:23552
	global_load_lds_dwordx4 v[154:155], off
	s_add_i32 m0, s53, 0x2000
	s_add_u32 s54, s28, 0x200000
	v_lshl_add_u64 v[188:189], s[28:29], 0, v[144:145]
	s_addc_u32 s55, s29, 0
	s_add_i32 s53, s56, s39
	global_load_lds_dwordx4 v[188:189], off
	v_lshl_add_u64 v[216:217], s[54:55], 0, v[160:161]
	s_mov_b32 m0, s53
	v_lshl_add_u64 v[246:247], s[30:31], 0, v[146:147]
	global_load_lds_dwordx4 v[216:217], off
	v_lshl_add_u64 v[216:217], s[54:55], 0, v[144:145]
	s_add_i32 m0, s53, 0x2000
	s_nop 0
	global_load_lds_dwordx4 v[216:217], off
	v_lshl_add_u64 v[216:217], s[30:31], 0, v[148:149]
	s_mov_b32 m0, s19
	s_nop 0
	global_load_lds_dwordx4 v[216:217], off
	s_mov_b32 m0, s41
	s_nop 0
	global_load_lds_dwordx4 v[246:247], off
	s_waitcnt vmcnt(8)
	s_waitcnt lgkmcnt(0)
	s_barrier
	s_waitcnt lgkmcnt(0)
	v_mfma_f32_16x16x32_bf16 v[60:63], v[128:131], v[196:199], v[60:63]
	v_mfma_f32_16x16x32_bf16 v[56:59], v[136:139], v[196:199], v[56:59]
	v_mfma_f32_16x16x32_bf16 v[52:55], v[128:131], v[204:207], v[52:55]
	v_mfma_f32_16x16x32_bf16 v[44:47], v[136:139], v[204:207], v[44:47]
	v_mfma_f32_16x16x32_bf16 v[28:31], v[128:131], v[212:215], v[28:31]
	v_mfma_f32_16x16x32_bf16 v[24:27], v[136:139], v[212:215], v[24:27]
	v_mfma_f32_16x16x32_bf16 v[20:23], v[128:131], v[238:241], v[20:23]
	v_mfma_f32_16x16x32_bf16 v[12:15], v[136:139], v[238:241], v[12:15]
	v_mfma_f32_16x16x32_bf16 v[60:63], v[132:135], v[200:203], v[60:63]
	v_mfma_f32_16x16x32_bf16 v[56:59], v[140:143], v[200:203], v[56:59]
	v_mfma_f32_16x16x32_bf16 v[52:55], v[132:135], v[208:211], v[52:55]
	v_mfma_f32_16x16x32_bf16 v[44:47], v[140:143], v[208:211], v[44:47]
	v_mfma_f32_16x16x32_bf16 v[28:31], v[132:135], v[234:237], v[28:31]
	v_mfma_f32_16x16x32_bf16 v[24:27], v[140:143], v[234:237], v[24:27]
	v_mfma_f32_16x16x32_bf16 v[20:23], v[132:135], v[242:245], v[20:23]
	v_mfma_f32_16x16x32_bf16 v[12:15], v[140:143], v[242:245], v[12:15]
	v_mfma_f32_16x16x32_bf16 v[48:51], v[172:175], v[196:199], v[48:51]
	v_mfma_f32_16x16x32_bf16 v[40:43], v[180:183], v[196:199], v[40:43]
	v_mfma_f32_16x16x32_bf16 v[36:39], v[172:175], v[204:207], v[36:39]
	v_mfma_f32_16x16x32_bf16 v[32:35], v[180:183], v[204:207], v[32:35]
	v_mfma_f32_16x16x32_bf16 v[16:19], v[172:175], v[212:215], v[16:19]
	v_mfma_f32_16x16x32_bf16 v[8:11], v[180:183], v[212:215], v[8:11]
	v_mfma_f32_16x16x32_bf16 v[4:7], v[172:175], v[238:241], v[4:7]
	v_mfma_f32_16x16x32_bf16 v[0:3], v[180:183], v[238:241], v[0:3]
	v_mfma_f32_16x16x32_bf16 v[48:51], v[176:179], v[200:203], v[48:51]
	v_mfma_f32_16x16x32_bf16 v[40:43], v[184:187], v[200:203], v[40:43]
	v_mfma_f32_16x16x32_bf16 v[36:39], v[176:179], v[208:211], v[36:39]
	v_mfma_f32_16x16x32_bf16 v[32:35], v[184:187], v[208:211], v[32:35]
	v_mfma_f32_16x16x32_bf16 v[16:19], v[176:179], v[234:237], v[16:19]
	v_mfma_f32_16x16x32_bf16 v[8:11], v[184:187], v[234:237], v[8:11]
	v_mfma_f32_16x16x32_bf16 v[4:7], v[176:179], v[242:245], v[4:7]
	v_mfma_f32_16x16x32_bf16 v[0:3], v[184:187], v[242:245], v[0:3]
	s_barrier
	s_add_i32 s53, 0, 0x18000
	s_add_i32 s54, 0, 0x1c000
	v_add_u32_e32 v140, s53, v157
	v_add_u32_e32 v162, s54, v157
	ds_read_b128 v[128:131], v140
	ds_read_b128 v[132:135], v140 offset:1024
	ds_read_b128 v[136:139], v140 offset:2048
	ds_read_b128 v[140:143], v140 offset:3072
	ds_read_b128 v[172:175], v162
	ds_read_b128 v[176:179], v162 offset:1024
	ds_read_b128 v[180:183], v162 offset:2048
	ds_read_b128 v[184:187], v162 offset:3072
	s_add_u32 s30, s30, 0x200000
	s_addc_u32 s31, s31, 0
	s_mov_b32 m0, s42
	v_lshl_add_u64 v[248:249], s[30:31], 0, v[148:149]
	ds_read_b128 v[196:199], v159 offset:32768
	ds_read_b128 v[200:203], v159 offset:33792
	ds_read_b128 v[204:207], v159 offset:34816
	ds_read_b128 v[208:211], v159 offset:35840
	ds_read_b128 v[212:215], v159 offset:36864
	ds_read_b128 v[234:237], v159 offset:37888
	ds_read_b128 v[238:241], v159 offset:38912
	ds_read_b128 v[242:245], v159 offset:39936
	global_load_lds_dwordx4 v[248:249], off
	v_lshl_add_u64 v[248:249], s[30:31], 0, v[146:147]
	s_mov_b32 m0, s43
	s_nop 0
	global_load_lds_dwordx4 v[248:249], off
	s_waitcnt vmcnt(8)
	s_waitcnt lgkmcnt(0)
	s_barrier
	s_waitcnt lgkmcnt(0)
	v_mfma_f32_16x16x32_bf16 v[124:127], v[128:131], v[196:199], v[124:127]
	v_mfma_f32_16x16x32_bf16 v[120:123], v[136:139], v[196:199], v[120:123]
	v_mfma_f32_16x16x32_bf16 v[116:119], v[128:131], v[204:207], v[116:119]
	v_mfma_f32_16x16x32_bf16 v[108:111], v[136:139], v[204:207], v[108:111]
	v_mfma_f32_16x16x32_bf16 v[92:95], v[128:131], v[212:215], v[92:95]
	v_mfma_f32_16x16x32_bf16 v[88:91], v[136:139], v[212:215], v[88:91]
	v_mfma_f32_16x16x32_bf16 v[84:87], v[128:131], v[238:241], v[84:87]
	v_mfma_f32_16x16x32_bf16 v[76:79], v[136:139], v[238:241], v[76:79]
	v_mfma_f32_16x16x32_bf16 v[124:127], v[132:135], v[200:203], v[124:127]
	v_mfma_f32_16x16x32_bf16 v[120:123], v[140:143], v[200:203], v[120:123]
	v_mfma_f32_16x16x32_bf16 v[116:119], v[132:135], v[208:211], v[116:119]
	v_mfma_f32_16x16x32_bf16 v[108:111], v[140:143], v[208:211], v[108:111]
	v_mfma_f32_16x16x32_bf16 v[92:95], v[132:135], v[234:237], v[92:95]
	v_mfma_f32_16x16x32_bf16 v[88:91], v[140:143], v[234:237], v[88:91]
	v_mfma_f32_16x16x32_bf16 v[84:87], v[132:135], v[242:245], v[84:87]
	v_mfma_f32_16x16x32_bf16 v[76:79], v[140:143], v[242:245], v[76:79]
	v_mfma_f32_16x16x32_bf16 v[112:115], v[172:175], v[196:199], v[112:115]
	v_mfma_f32_16x16x32_bf16 v[104:107], v[180:183], v[196:199], v[104:107]
	v_mfma_f32_16x16x32_bf16 v[100:103], v[172:175], v[204:207], v[100:103]
	v_mfma_f32_16x16x32_bf16 v[96:99], v[180:183], v[204:207], v[96:99]
	v_mfma_f32_16x16x32_bf16 v[80:83], v[172:175], v[212:215], v[80:83]
	v_mfma_f32_16x16x32_bf16 v[72:75], v[180:183], v[212:215], v[72:75]
	v_mfma_f32_16x16x32_bf16 v[68:71], v[172:175], v[238:241], v[68:71]
	v_mfma_f32_16x16x32_bf16 v[64:67], v[180:183], v[238:241], v[64:67]
	v_mfma_f32_16x16x32_bf16 v[112:115], v[176:179], v[200:203], v[112:115]
	v_mfma_f32_16x16x32_bf16 v[104:107], v[184:187], v[200:203], v[104:107]
	v_mfma_f32_16x16x32_bf16 v[100:103], v[176:179], v[208:211], v[100:103]
	v_mfma_f32_16x16x32_bf16 v[96:99], v[184:187], v[208:211], v[96:99]
	v_mfma_f32_16x16x32_bf16 v[80:83], v[176:179], v[234:237], v[80:83]
	v_mfma_f32_16x16x32_bf16 v[72:75], v[184:187], v[234:237], v[72:75]
	v_mfma_f32_16x16x32_bf16 v[68:71], v[176:179], v[242:245], v[68:71]
	v_mfma_f32_16x16x32_bf16 v[64:67], v[184:187], v[242:245], v[64:67]
	s_barrier
	s_add_i32 s30, s53, s39
	v_lshl_add_u64 v[154:155], v[154:155], 0, s[20:21]
	s_mov_b32 m0, s30
	ds_read_b128 v[196:199], v159 offset:49152
	ds_read_b128 v[200:203], v159 offset:50176
	ds_read_b128 v[204:207], v159 offset:51200
	ds_read_b128 v[208:211], v159 offset:52224
	ds_read_b128 v[212:215], v159 offset:53248
	ds_read_b128 v[234:237], v159 offset:54272
	ds_read_b128 v[238:241], v159 offset:55296
	ds_read_b128 v[242:245], v159 offset:56320
	global_load_lds_dwordx4 v[154:155], off
	s_add_i32 m0, s30, 0x2000
	s_add_u32 s28, s28, 0x200080
	v_lshl_add_u64 v[154:155], v[188:189], 0, s[20:21]
	s_addc_u32 s29, s29, 0
	s_add_i32 s30, s54, s39
	global_load_lds_dwordx4 v[154:155], off
	v_lshl_add_u64 v[154:155], s[28:29], 0, v[160:161]
	s_mov_b32 m0, s30
	s_nop 0
	global_load_lds_dwordx4 v[154:155], off
	v_lshl_add_u64 v[154:155], s[28:29], 0, v[144:145]
	s_add_i32 m0, s30, 0x2000
	s_nop 0
	global_load_lds_dwordx4 v[154:155], off
	v_lshl_add_u64 v[154:155], v[216:217], 0, s[20:21]
	s_mov_b32 m0, s44
	s_nop 0
	global_load_lds_dwordx4 v[154:155], off
	v_lshl_add_u64 v[154:155], v[246:247], 0, s[20:21]
	s_mov_b32 m0, s45
	s_nop 0
	global_load_lds_dwordx4 v[154:155], off
	s_waitcnt vmcnt(8)
	s_waitcnt lgkmcnt(0)
	s_barrier
	s_waitcnt lgkmcnt(0)
	v_mfma_f32_16x16x32_bf16 v[60:63], v[128:131], v[196:199], v[60:63]
	v_mfma_f32_16x16x32_bf16 v[56:59], v[136:139], v[196:199], v[56:59]
	v_mfma_f32_16x16x32_bf16 v[52:55], v[128:131], v[204:207], v[52:55]
	v_mfma_f32_16x16x32_bf16 v[44:47], v[136:139], v[204:207], v[44:47]
	v_mfma_f32_16x16x32_bf16 v[28:31], v[128:131], v[212:215], v[28:31]
	v_mfma_f32_16x16x32_bf16 v[24:27], v[136:139], v[212:215], v[24:27]
	v_mfma_f32_16x16x32_bf16 v[20:23], v[128:131], v[238:241], v[20:23]
	v_mfma_f32_16x16x32_bf16 v[12:15], v[136:139], v[238:241], v[12:15]
	v_mfma_f32_16x16x32_bf16 v[60:63], v[132:135], v[200:203], v[60:63]
	v_mfma_f32_16x16x32_bf16 v[56:59], v[140:143], v[200:203], v[56:59]
	v_mfma_f32_16x16x32_bf16 v[52:55], v[132:135], v[208:211], v[52:55]
	v_mfma_f32_16x16x32_bf16 v[44:47], v[140:143], v[208:211], v[44:47]
	v_mfma_f32_16x16x32_bf16 v[28:31], v[132:135], v[234:237], v[28:31]
	v_mfma_f32_16x16x32_bf16 v[24:27], v[140:143], v[234:237], v[24:27]
	v_mfma_f32_16x16x32_bf16 v[20:23], v[132:135], v[242:245], v[20:23]
	v_mfma_f32_16x16x32_bf16 v[12:15], v[140:143], v[242:245], v[12:15]
	v_mfma_f32_16x16x32_bf16 v[48:51], v[172:175], v[196:199], v[48:51]
	v_mfma_f32_16x16x32_bf16 v[40:43], v[180:183], v[196:199], v[40:43]
	v_mfma_f32_16x16x32_bf16 v[36:39], v[172:175], v[204:207], v[36:39]
	v_mfma_f32_16x16x32_bf16 v[32:35], v[180:183], v[204:207], v[32:35]
	v_mfma_f32_16x16x32_bf16 v[16:19], v[172:175], v[212:215], v[16:19]
	v_mfma_f32_16x16x32_bf16 v[8:11], v[180:183], v[212:215], v[8:11]
	v_mfma_f32_16x16x32_bf16 v[4:7], v[172:175], v[238:241], v[4:7]
	v_mfma_f32_16x16x32_bf16 v[0:3], v[180:183], v[238:241], v[0:3]
	v_mfma_f32_16x16x32_bf16 v[48:51], v[176:179], v[200:203], v[48:51]
	v_mfma_f32_16x16x32_bf16 v[40:43], v[184:187], v[200:203], v[40:43]
	v_mfma_f32_16x16x32_bf16 v[36:39], v[176:179], v[208:211], v[36:39]
	v_mfma_f32_16x16x32_bf16 v[32:35], v[184:187], v[208:211], v[32:35]
	v_mfma_f32_16x16x32_bf16 v[16:19], v[176:179], v[234:237], v[16:19]
	v_mfma_f32_16x16x32_bf16 v[8:11], v[184:187], v[234:237], v[8:11]
	v_mfma_f32_16x16x32_bf16 v[4:7], v[176:179], v[242:245], v[4:7]
	v_mfma_f32_16x16x32_bf16 v[0:3], v[184:187], v[242:245], v[0:3]
	s_barrier
	s_add_i32 s52, s52, 2
	s_add_u32 s26, s26, 0x100
	s_addc_u32 s27, s27, 0
	s_add_u32 s50, s50, 0x100
	s_addc_u32 s51, s51, 0
	s_cmpk_gt_u32 s52, 0x7d
	s_cbranch_scc0 .LBB0_1522
	s_and_b64 vcc, exec, s[8:9]
	s_cbranch_vccz .LBB0_1525
	s_barrier
